# GEMM K-loops: all LDS-DMA loads in scalar-base + lane-offset form (16 vector 64-bit adds per iteration become 4 scalar add pairs) in 8 of 10 loops
# baseline (speedup 1.0000x reference)
; #define PG8_STAGE(bufoff, gbase, voff) do { _Pragma("unroll") for (int _i = 0; _i < 2; ++_i) \
;     __builtin_amdgcn_global_load_lds((const unsigned*)((const char*)(gbase) + (voff)[_i]), (PG8_LAS unsigned*)(lds + (bufoff) + ldsw + _i * 8192), 16, 0, 0); } while (0)
; #define PG8_LDA(dst, b, h) do { _Pragma("unroll") for (int m = 0; m < 4; ++m) _Pragma("unroll") for (int k = 0; k < 2; ++k) dst[m][k] = *(const PG8_LAS bf16x8*)(lds + PG8_SA(b, h) + aoff + m * 2048 + k * 1024); } while (0)
; #define PG8_LDB(dst, b, h) do { _Pragma("unroll") for (int n = 0; n < 2; ++n) _Pragma("unroll") for (int k = 0; k < 2; ++k) dst[n][k] = *(const PG8_LAS bf16x8*)(lds + PG8_SB(b, h) + boff + n * 2048 + k * 1024); } while (0)
; #define PG8_MMA(ai, bj, At, Bt) do { __builtin_amdgcn_s_setprio(1); _Pragma("unroll") for (int m = 0; m < 4; ++m) _Pragma("unroll") for (int n = 0; n < 2; ++n) _Pragma("unroll") for (int k = 0; k < 2; ++k) \
;     acc[ai][bj][m][n] = __builtin_amdgcn_mfma_f32_16x16x32_bf16(Bt[n][k], At[m][k], acc[ai][bj][m][n], 0, 0, 0); __builtin_amdgcn_s_setprio(0); } while (0)
; #define PG8_WAIT_V(n) asm volatile("s_waitcnt vmcnt(" #n ")" ::: "memory")
; #define PG8_WAIT_L(n) asm volatile("s_waitcnt lgkmcnt(" #n ")" ::: "memory")
; #define PG8_BAR __builtin_amdgcn_s_barrier()
; #define PG8_SCHED __builtin_amdgcn_sched_barrier(0)
; template <class Epi, class Sched>
; DI void gemm_phase(PG8_LAS unsigned char* lds, const Gemm g, const Sched& S, const Epi& E) {
;     ...
;     for (int t = 0; t < nt; t += 2) {
;       const bool last = (t == nt - 2);
;       const char* a1 = cA + (size_t)(t + 1) * kstep;
;       const char* a2 = last ? nA : cA + (size_t)(t + 2) * kstep; const char* b2 = last ? nB : cB + (size_t)(t + 2) * kstep;
;       const char* a3 = a2 + kstep; const char* b3 = b2 + kstep;
;       PG8_LDB(B0, 0, 0); PG8_LDB(B1, 0, 1); PG8_SCHED; PG8_LDA(At, 0, 0); PG8_STAGE(PG8_SA(1, 1), a1 + hstepA, voffA);
;       PG8_WAIT_V(8); PG8_WAIT_L(0); PG8_BAR; PG8_MMA(0, 0, At, B0); PG8_MMA(0, 1, At, B1); PG8_BAR; PG8_SCHED;
;       PG8_LDA(At, 0, 1); PG8_STAGE(PG8_SB(0, 0), b2, voffB); PG8_STAGE(PG8_SB(0, 1), b2 + hstepB, voffB); PG8_STAGE(PG8_SA(0, 0), a2, voffA);
;       PG8_WAIT_V(8); PG8_WAIT_L(0); PG8_BAR; PG8_MMA(1, 0, At, B0); PG8_MMA(1, 1, At, B1); PG8_BAR; PG8_SCHED;
.LBB0_563:
	ds_read_b128 v[128:131], v167
	ds_read_b128 v[132:135], v167 offset:1024
	ds_read_b128 v[136:139], v167 offset:2048
	ds_read_b128 v[140:143], v167 offset:3072
	ds_read_b128 v[158:161], v168
	ds_read_b128 v[162:165], v168 offset:1024
	ds_read_b128 v[172:175], v168 offset:2048
	ds_read_b128 v[176:179], v168 offset:3072
	s_add_u32 s16, s28, 0xfffc0080
	s_addc_u32 s17, s29, -1
	s_cmp_eq_u32 s70, 12
	s_cselect_b32 s35, s19, s17
	s_cselect_b32 s34, s27, s16
	s_cselect_b32 s31, s15, s69
	s_cselect_b32 s30, s67, s68
	s_add_i32 m0, s3, 0xc000
	ds_read_b128 v[180:183], v169
	ds_read_b128 v[184:187], v169 offset:1024
	ds_read_b128 v[188:191], v169 offset:2048
	ds_read_b128 v[192:195], v169 offset:3072
	ds_read_b128 v[196:199], v169 offset:4096
	ds_read_b128 v[200:203], v169 offset:5120
	ds_read_b128 v[204:207], v169 offset:6144
	ds_read_b128 v[208:211], v169 offset:7168
	global_load_lds_dwordx4 v154, s[28:29]
	s_add_i32 m0, s3, 0xe000
	s_nop 0
	global_load_lds_dwordx4 v156, s[28:29]
	s_waitcnt vmcnt(8)
	s_waitcnt lgkmcnt(0)
	s_barrier
	s_setprio 1
	s_waitcnt lgkmcnt(0)
	v_mfma_f32_16x16x32_bf16 v[124:127], v[128:131], v[180:183], v[124:127]
	v_mfma_f32_16x16x32_bf16 v[120:123], v[136:139], v[180:183], v[120:123]
	v_mfma_f32_16x16x32_bf16 v[108:111], v[128:131], v[188:191], v[108:111]
	v_mfma_f32_16x16x32_bf16 v[104:107], v[136:139], v[188:191], v[104:107]
	v_mfma_f32_16x16x32_bf16 v[92:95], v[128:131], v[196:199], v[92:95]
	v_mfma_f32_16x16x32_bf16 v[88:91], v[136:139], v[196:199], v[88:91]
	v_mfma_f32_16x16x32_bf16 v[76:79], v[128:131], v[204:207], v[76:79]
	v_mfma_f32_16x16x32_bf16 v[72:75], v[136:139], v[204:207], v[72:75]
	v_mfma_f32_16x16x32_bf16 v[124:127], v[132:135], v[184:187], v[124:127]
	v_mfma_f32_16x16x32_bf16 v[120:123], v[140:143], v[184:187], v[120:123]
	v_mfma_f32_16x16x32_bf16 v[108:111], v[132:135], v[192:195], v[108:111]
	v_mfma_f32_16x16x32_bf16 v[104:107], v[140:143], v[192:195], v[104:107]
	v_mfma_f32_16x16x32_bf16 v[92:95], v[132:135], v[200:203], v[92:95]
	v_mfma_f32_16x16x32_bf16 v[88:91], v[140:143], v[200:203], v[88:91]
	v_mfma_f32_16x16x32_bf16 v[76:79], v[132:135], v[208:211], v[76:79]
	v_mfma_f32_16x16x32_bf16 v[72:75], v[140:143], v[208:211], v[72:75]
	s_setprio 0
	s_setprio 1
	v_mfma_f32_16x16x32_bf16 v[116:119], v[158:161], v[180:183], v[116:119]
	v_mfma_f32_16x16x32_bf16 v[112:115], v[172:175], v[180:183], v[112:115]
	v_mfma_f32_16x16x32_bf16 v[100:103], v[158:161], v[188:191], v[100:103]
	v_mfma_f32_16x16x32_bf16 v[96:99], v[172:175], v[188:191], v[96:99]
	v_mfma_f32_16x16x32_bf16 v[84:87], v[158:161], v[196:199], v[84:87]
	v_mfma_f32_16x16x32_bf16 v[80:83], v[172:175], v[196:199], v[80:83]
	v_mfma_f32_16x16x32_bf16 v[68:71], v[158:161], v[204:207], v[68:71]
	v_mfma_f32_16x16x32_bf16 v[64:67], v[172:175], v[204:207], v[64:67]
	v_mfma_f32_16x16x32_bf16 v[116:119], v[162:165], v[184:187], v[116:119]
	v_mfma_f32_16x16x32_bf16 v[112:115], v[176:179], v[184:187], v[112:115]
	v_mfma_f32_16x16x32_bf16 v[100:103], v[162:165], v[192:195], v[100:103]
	v_mfma_f32_16x16x32_bf16 v[96:99], v[176:179], v[192:195], v[96:99]
	v_mfma_f32_16x16x32_bf16 v[84:87], v[162:165], v[200:203], v[84:87]
	v_mfma_f32_16x16x32_bf16 v[80:83], v[176:179], v[200:203], v[80:83]
	v_mfma_f32_16x16x32_bf16 v[68:71], v[162:165], v[208:211], v[68:71]
	v_mfma_f32_16x16x32_bf16 v[64:67], v[176:179], v[208:211], v[64:67]
	s_setprio 0
	s_barrier
	s_add_i32 s16, s55, s2
	s_mov_b32 m0, s16
	ds_read_b128 v[180:183], v169 offset:16384
	ds_read_b128 v[184:187], v169 offset:17408
	ds_read_b128 v[188:191], v169 offset:18432
	ds_read_b128 v[192:195], v169 offset:19456
	ds_read_b128 v[196:199], v169 offset:20480
	ds_read_b128 v[200:203], v169 offset:21504
	ds_read_b128 v[204:207], v169 offset:22528
	ds_read_b128 v[208:211], v169 offset:23552
	global_load_lds_dwordx4 v146, s[30:31]
	s_add_i32 m0, s16, 0x2000
	s_add_u32 s16, s30, 0x40000
	s_addc_u32 s17, s31, 0
	s_add_i32 s33, s64, s2
	global_load_lds_dwordx4 v150, s[30:31]
	s_mov_b32 m0, s33
	s_nop 0
	global_load_lds_dwordx4 v146, s[16:17]
	s_add_i32 m0, s33, 0x2000
	s_nop 0
	global_load_lds_dwordx4 v150, s[16:17]
	s_mov_b32 m0, s3
	s_nop 0
	global_load_lds_dwordx4 v144, s[34:35]
	s_mov_b32 m0, s36
	s_nop 0
	global_load_lds_dwordx4 v148, s[34:35]
	s_waitcnt vmcnt(8)
	s_waitcnt lgkmcnt(0)
	s_barrier
	s_setprio 1
	s_waitcnt lgkmcnt(0)
	v_mfma_f32_16x16x32_bf16 v[60:63], v[128:131], v[180:183], v[60:63]
	v_mfma_f32_16x16x32_bf16 v[56:59], v[136:139], v[180:183], v[56:59]
	v_mfma_f32_16x16x32_bf16 v[44:47], v[128:131], v[188:191], v[44:47]
	v_mfma_f32_16x16x32_bf16 v[40:43], v[136:139], v[188:191], v[40:43]
	v_mfma_f32_16x16x32_bf16 v[28:31], v[128:131], v[196:199], v[28:31]
	v_mfma_f32_16x16x32_bf16 v[24:27], v[136:139], v[196:199], v[24:27]
	v_mfma_f32_16x16x32_bf16 v[12:15], v[128:131], v[204:207], v[12:15]
	v_mfma_f32_16x16x32_bf16 v[8:11], v[136:139], v[204:207], v[8:11]
	v_mfma_f32_16x16x32_bf16 v[60:63], v[132:135], v[184:187], v[60:63]
	v_mfma_f32_16x16x32_bf16 v[56:59], v[140:143], v[184:187], v[56:59]
	v_mfma_f32_16x16x32_bf16 v[44:47], v[132:135], v[192:195], v[44:47]
	v_mfma_f32_16x16x32_bf16 v[40:43], v[140:143], v[192:195], v[40:43]
	v_mfma_f32_16x16x32_bf16 v[28:31], v[132:135], v[200:203], v[28:31]
	v_mfma_f32_16x16x32_bf16 v[24:27], v[140:143], v[200:203], v[24:27]
	v_mfma_f32_16x16x32_bf16 v[12:15], v[132:135], v[208:211], v[12:15]
	v_mfma_f32_16x16x32_bf16 v[8:11], v[140:143], v[208:211], v[8:11]
	s_setprio 0
	s_setprio 1
	v_mfma_f32_16x16x32_bf16 v[52:55], v[158:161], v[180:183], v[52:55]
	v_mfma_f32_16x16x32_bf16 v[48:51], v[172:175], v[180:183], v[48:51]
	v_mfma_f32_16x16x32_bf16 v[36:39], v[158:161], v[188:191], v[36:39]
	v_mfma_f32_16x16x32_bf16 v[32:35], v[172:175], v[188:191], v[32:35]
	v_mfma_f32_16x16x32_bf16 v[20:23], v[158:161], v[196:199], v[20:23]
	v_mfma_f32_16x16x32_bf16 v[16:19], v[172:175], v[196:199], v[16:19]
	v_mfma_f32_16x16x32_bf16 v[4:7], v[158:161], v[204:207], v[4:7]
	v_mfma_f32_16x16x32_bf16 v[0:3], v[172:175], v[204:207], v[0:3]
	v_mfma_f32_16x16x32_bf16 v[52:55], v[162:165], v[184:187], v[52:55]
	v_mfma_f32_16x16x32_bf16 v[48:51], v[176:179], v[184:187], v[48:51]
	v_mfma_f32_16x16x32_bf16 v[36:39], v[162:165], v[192:195], v[36:39]
	v_mfma_f32_16x16x32_bf16 v[32:35], v[176:179], v[192:195], v[32:35]
	v_mfma_f32_16x16x32_bf16 v[20:23], v[162:165], v[200:203], v[20:23]
	v_mfma_f32_16x16x32_bf16 v[16:19], v[176:179], v[200:203], v[16:19]
	v_mfma_f32_16x16x32_bf16 v[4:7], v[162:165], v[208:211], v[4:7]
	v_mfma_f32_16x16x32_bf16 v[0:3], v[176:179], v[208:211], v[0:3]
	s_setprio 0
	s_barrier
; #define PG8_STAGE(bufoff, gbase, voff) do { _Pragma("unroll") for (int _i = 0; _i < 2; ++_i) \
;     __builtin_amdgcn_global_load_lds((const unsigned*)((const char*)(gbase) + (voff)[_i]), (PG8_LAS unsigned*)(lds + (bufoff) + ldsw + _i * 8192), 16, 0, 0); } while (0)
; #define PG8_LDA(dst, b, h) do { _Pragma("unroll") for (int m = 0; m < 4; ++m) _Pragma("unroll") for (int k = 0; k < 2; ++k) dst[m][k] = *(const PG8_LAS bf16x8*)(lds + PG8_SA(b, h) + aoff + m * 2048 + k * 1024); } while (0)
; #define PG8_LDB(dst, b, h) do { _Pragma("unroll") for (int n = 0; n < 2; ++n) _Pragma("unroll") for (int k = 0; k < 2; ++k) dst[n][k] = *(const PG8_LAS bf16x8*)(lds + PG8_SB(b, h) + boff + n * 2048 + k * 1024); } while (0)
; #define PG8_MMA(ai, bj, At, Bt) do { __builtin_amdgcn_s_setprio(1); _Pragma("unroll") for (int m = 0; m < 4; ++m) _Pragma("unroll") for (int n = 0; n < 2; ++n) _Pragma("unroll") for (int k = 0; k < 2; ++k) \
;     acc[ai][bj][m][n] = __builtin_amdgcn_mfma_f32_16x16x32_bf16(Bt[n][k], At[m][k], acc[ai][bj][m][n], 0, 0, 0); __builtin_amdgcn_s_setprio(0); } while (0)
; #define PG8_WAIT_V(n) asm volatile("s_waitcnt vmcnt(" #n ")" ::: "memory")
; #define PG8_WAIT_L(n) asm volatile("s_waitcnt lgkmcnt(" #n ")" ::: "memory")
; #define PG8_BAR __builtin_amdgcn_s_barrier()
; #define PG8_SCHED __builtin_amdgcn_sched_barrier(0)
; template <class Epi, class Sched>
; DI void gemm_phase(PG8_LAS unsigned char* lds, const Gemm g, const Sched& S, const Epi& E) {
;     ...
;       PG8_WAIT_V(8); PG8_WAIT_L(0); PG8_BAR; PG8_MMA(1, 0, At, B0); PG8_MMA(1, 1, At, B1); PG8_BAR; PG8_SCHED;
;       PG8_LDB(B0, 1, 0); PG8_LDB(B1, 1, 1); PG8_SCHED; PG8_LDA(At, 1, 0); PG8_STAGE(PG8_SA(0, 1), a2 + hstepA, voffA);
;       PG8_WAIT_V(8); PG8_WAIT_L(0); PG8_BAR; PG8_MMA(0, 0, At, B0); PG8_MMA(0, 1, At, B1); PG8_BAR; PG8_SCHED;
;       PG8_LDA(At, 1, 1); PG8_STAGE(PG8_SB(1, 0), b3, voffB); PG8_STAGE(PG8_SB(1, 1), b3 + hstepB, voffB); PG8_STAGE(PG8_SA(1, 0), a3, voffA);
	s_add_i32 s33, s41, 0x110
	v_add_u32_e32 v140, s33, v166
	ds_read_b128 v[128:131], v140
	ds_read_b128 v[132:135], v140 offset:1024
	ds_read_b128 v[136:139], v140 offset:2048
	ds_read_b128 v[140:143], v140 offset:3072
	ds_read_b128 v[158:161], v171
	ds_read_b128 v[162:165], v171 offset:1024
	ds_read_b128 v[172:175], v171 offset:2048
	ds_read_b128 v[176:179], v171 offset:3072
	s_add_u32 s16, s34, 0x40000
	s_addc_u32 s17, s35, 0
	s_mov_b32 m0, s37
	ds_read_b128 v[180:183], v169 offset:32768
	ds_read_b128 v[184:187], v169 offset:33792
	ds_read_b128 v[188:191], v169 offset:34816
	ds_read_b128 v[192:195], v169 offset:35840
	ds_read_b128 v[196:199], v169 offset:36864
	ds_read_b128 v[200:203], v169 offset:37888
	ds_read_b128 v[204:207], v169 offset:38912
	ds_read_b128 v[208:211], v169 offset:39936
	global_load_lds_dwordx4 v144, s[16:17]
	s_mov_b32 m0, s38
	s_nop 0
	global_load_lds_dwordx4 v148, s[16:17]
	s_waitcnt vmcnt(8)
	s_waitcnt lgkmcnt(0)
	s_barrier
	s_setprio 1
	s_waitcnt lgkmcnt(0)
	v_mfma_f32_16x16x32_bf16 v[124:127], v[128:131], v[180:183], v[124:127]
	v_mfma_f32_16x16x32_bf16 v[120:123], v[136:139], v[180:183], v[120:123]
	v_mfma_f32_16x16x32_bf16 v[108:111], v[128:131], v[188:191], v[108:111]
	v_mfma_f32_16x16x32_bf16 v[104:107], v[136:139], v[188:191], v[104:107]
	v_mfma_f32_16x16x32_bf16 v[92:95], v[128:131], v[196:199], v[92:95]
	v_mfma_f32_16x16x32_bf16 v[88:91], v[136:139], v[196:199], v[88:91]
	v_mfma_f32_16x16x32_bf16 v[76:79], v[128:131], v[204:207], v[76:79]
	v_mfma_f32_16x16x32_bf16 v[72:75], v[136:139], v[204:207], v[72:75]
	v_mfma_f32_16x16x32_bf16 v[124:127], v[132:135], v[184:187], v[124:127]
	v_mfma_f32_16x16x32_bf16 v[120:123], v[140:143], v[184:187], v[120:123]
	v_mfma_f32_16x16x32_bf16 v[108:111], v[132:135], v[192:195], v[108:111]
	v_mfma_f32_16x16x32_bf16 v[104:107], v[140:143], v[192:195], v[104:107]
	v_mfma_f32_16x16x32_bf16 v[92:95], v[132:135], v[200:203], v[92:95]
	v_mfma_f32_16x16x32_bf16 v[88:91], v[140:143], v[200:203], v[88:91]
	v_mfma_f32_16x16x32_bf16 v[76:79], v[132:135], v[208:211], v[76:79]
	v_mfma_f32_16x16x32_bf16 v[72:75], v[140:143], v[208:211], v[72:75]
	s_setprio 0
	s_setprio 1
	v_mfma_f32_16x16x32_bf16 v[116:119], v[158:161], v[180:183], v[116:119]
	v_mfma_f32_16x16x32_bf16 v[112:115], v[172:175], v[180:183], v[112:115]
	v_mfma_f32_16x16x32_bf16 v[100:103], v[158:161], v[188:191], v[100:103]
	v_mfma_f32_16x16x32_bf16 v[96:99], v[172:175], v[188:191], v[96:99]
	v_mfma_f32_16x16x32_bf16 v[84:87], v[158:161], v[196:199], v[84:87]
	v_mfma_f32_16x16x32_bf16 v[80:83], v[172:175], v[196:199], v[80:83]
	v_mfma_f32_16x16x32_bf16 v[68:71], v[158:161], v[204:207], v[68:71]
	v_mfma_f32_16x16x32_bf16 v[64:67], v[172:175], v[204:207], v[64:67]
	v_mfma_f32_16x16x32_bf16 v[116:119], v[162:165], v[184:187], v[116:119]
	v_mfma_f32_16x16x32_bf16 v[112:115], v[176:179], v[184:187], v[112:115]
	v_mfma_f32_16x16x32_bf16 v[100:103], v[162:165], v[192:195], v[100:103]
	v_mfma_f32_16x16x32_bf16 v[96:99], v[176:179], v[192:195], v[96:99]
	v_mfma_f32_16x16x32_bf16 v[84:87], v[162:165], v[200:203], v[84:87]
	v_mfma_f32_16x16x32_bf16 v[80:83], v[176:179], v[200:203], v[80:83]
	v_mfma_f32_16x16x32_bf16 v[68:71], v[162:165], v[208:211], v[68:71]
	v_mfma_f32_16x16x32_bf16 v[64:67], v[176:179], v[208:211], v[64:67]
	s_setprio 0
	s_barrier
	s_add_i32 s16, s33, s2
	s_mov_b32 m0, s16
	ds_read_b128 v[180:183], v169 offset:49152
	ds_read_b128 v[184:187], v169 offset:50176
	ds_read_b128 v[188:191], v169 offset:51200
	ds_read_b128 v[192:195], v169 offset:52224
	ds_read_b128 v[196:199], v169 offset:53248
	ds_read_b128 v[200:203], v169 offset:54272
	ds_read_b128 v[204:207], v169 offset:55296
	ds_read_b128 v[208:211], v169 offset:56320
	s_add_u32 s100, s30, 0x80
	s_addc_u32 s101, s31, 0
	global_load_lds_dwordx4 v146, s[100:101]
	s_add_i32 m0, s16, 0x2000
	s_add_u32 s16, s30, 0x40080
	s_addc_u32 s17, s31, 0
	s_add_i32 s30, s65, s2
	global_load_lds_dwordx4 v150, s[100:101]
	s_mov_b32 m0, s30
	s_nop 0
	global_load_lds_dwordx4 v146, s[16:17]
	s_add_i32 m0, s30, 0x2000
	s_nop 0
	global_load_lds_dwordx4 v150, s[16:17]
	s_mov_b32 m0, s4
	s_nop 0
	s_add_u32 s100, s34, 0x80
	s_addc_u32 s101, s35, 0
	global_load_lds_dwordx4 v144, s[100:101]
	s_mov_b32 m0, s5
	s_nop 0
	global_load_lds_dwordx4 v148, s[100:101]
	s_waitcnt vmcnt(8)
	s_waitcnt lgkmcnt(0)
	s_barrier
; #define PG8_MMA(ai, bj, At, Bt) do { __builtin_amdgcn_s_setprio(1); _Pragma("unroll") for (int m = 0; m < 4; ++m) _Pragma("unroll") for (int n = 0; n < 2; ++n) _Pragma("unroll") for (int k = 0; k < 2; ++k) \
;     acc[ai][bj][m][n] = __builtin_amdgcn_mfma_f32_16x16x32_bf16(Bt[n][k], At[m][k], acc[ai][bj][m][n], 0, 0, 0); __builtin_amdgcn_s_setprio(0); } while (0)
; #define PG8_WAIT_V(n) asm volatile("s_waitcnt vmcnt(" #n ")" ::: "memory")
; #define PG8_WAIT_L(n) asm volatile("s_waitcnt lgkmcnt(" #n ")" ::: "memory")
; #define PG8_BAR __builtin_amdgcn_s_barrier()
; #define PG8_SCHED __builtin_amdgcn_sched_barrier(0)
;   DI void operator()(const f32x4 (&acc)[2][2][4][2], const Unit& u, int wr, int wc, int fr, int fq) const {
;     const int row0 = u.pm * BM + wr * 64 + fr;
;     const size_t base = (size_t)row0 * DM + u.pn * BM + wc * 32 + 8 * fq;
;     f32x4 xv[2][4];
;     u32x4 xh[2][2];
;     ...
;     RES_LD(0)
; #pragma unroll
;     for (int i = 0; i < 8; ++i) {
;       const int ai = i >> 2, m = i & 3;
;       if (i + 1 < 8) RES_LD(i + 1)
; template <class Epi, class Sched>
; DI void gemm_phase(PG8_LAS unsigned char* lds, const Gemm g, const Sched& S, const Epi& E) {
;     ...
;       PG8_WAIT_V(8); PG8_WAIT_L(0); PG8_BAR; PG8_MMA(1, 0, At, B0); PG8_MMA(1, 1, At, B1); PG8_BAR; PG8_SCHED;
;     }
;     if (wr == 0) PG8_BAR;
	s_setprio 1
	s_waitcnt lgkmcnt(0)
	v_mfma_f32_16x16x32_bf16 v[60:63], v[128:131], v[180:183], v[60:63]
	v_mfma_f32_16x16x32_bf16 v[56:59], v[136:139], v[180:183], v[56:59]
	v_mfma_f32_16x16x32_bf16 v[44:47], v[128:131], v[188:191], v[44:47]
	v_mfma_f32_16x16x32_bf16 v[40:43], v[136:139], v[188:191], v[40:43]
	v_mfma_f32_16x16x32_bf16 v[28:31], v[128:131], v[196:199], v[28:31]
	v_mfma_f32_16x16x32_bf16 v[24:27], v[136:139], v[196:199], v[24:27]
	v_mfma_f32_16x16x32_bf16 v[12:15], v[128:131], v[204:207], v[12:15]
	v_mfma_f32_16x16x32_bf16 v[8:11], v[136:139], v[204:207], v[8:11]
	v_mfma_f32_16x16x32_bf16 v[60:63], v[132:135], v[184:187], v[60:63]
	v_mfma_f32_16x16x32_bf16 v[56:59], v[140:143], v[184:187], v[56:59]
	v_mfma_f32_16x16x32_bf16 v[44:47], v[132:135], v[192:195], v[44:47]
	v_mfma_f32_16x16x32_bf16 v[40:43], v[140:143], v[192:195], v[40:43]
	v_mfma_f32_16x16x32_bf16 v[28:31], v[132:135], v[200:203], v[28:31]
	v_mfma_f32_16x16x32_bf16 v[24:27], v[140:143], v[200:203], v[24:27]
	v_mfma_f32_16x16x32_bf16 v[12:15], v[132:135], v[208:211], v[12:15]
	v_mfma_f32_16x16x32_bf16 v[8:11], v[140:143], v[208:211], v[8:11]
	s_setprio 0
	s_setprio 1
	v_mfma_f32_16x16x32_bf16 v[52:55], v[158:161], v[180:183], v[52:55]
	v_mfma_f32_16x16x32_bf16 v[48:51], v[172:175], v[180:183], v[48:51]
	v_mfma_f32_16x16x32_bf16 v[36:39], v[158:161], v[188:191], v[36:39]
	v_mfma_f32_16x16x32_bf16 v[32:35], v[172:175], v[188:191], v[32:35]
	v_mfma_f32_16x16x32_bf16 v[20:23], v[158:161], v[196:199], v[20:23]
	v_mfma_f32_16x16x32_bf16 v[16:19], v[172:175], v[196:199], v[16:19]
	v_mfma_f32_16x16x32_bf16 v[4:7], v[158:161], v[204:207], v[4:7]
	v_mfma_f32_16x16x32_bf16 v[0:3], v[172:175], v[204:207], v[0:3]
	v_mfma_f32_16x16x32_bf16 v[52:55], v[162:165], v[184:187], v[52:55]
	v_mfma_f32_16x16x32_bf16 v[48:51], v[176:179], v[184:187], v[48:51]
	v_mfma_f32_16x16x32_bf16 v[36:39], v[162:165], v[192:195], v[36:39]
	v_mfma_f32_16x16x32_bf16 v[32:35], v[176:179], v[192:195], v[32:35]
	v_mfma_f32_16x16x32_bf16 v[20:23], v[162:165], v[200:203], v[20:23]
	v_mfma_f32_16x16x32_bf16 v[16:19], v[176:179], v[200:203], v[16:19]
	v_mfma_f32_16x16x32_bf16 v[4:7], v[162:165], v[208:211], v[4:7]
	v_mfma_f32_16x16x32_bf16 v[0:3], v[176:179], v[208:211], v[0:3]
	s_setprio 0
	s_barrier
	s_add_i32 s70, s70, 2
	s_add_u32 s28, s28, 0x100
	s_addc_u32 s29, s29, 0
	s_add_u32 s68, s68, 0x100
	s_addc_u32 s69, s69, 0
	s_cmp_gt_u32 s70, 13
	s_cbranch_scc0 .LBB0_563
	v_lshl_add_u32 v164, s26, 8, v153
	v_ashrrev_i32_e32 v165, 31, v164
	s_lshl_b32 s16, s12, 8
	v_lshlrev_b64 v[128:129], 10, v[164:165]
	s_ashr_i32 s17, s16, 31
	v_lshl_add_u64 v[186:187], v[128:129], 0, s[16:17]
	v_or_b32_e32 v186, v186, v152
	v_lshl_add_u64 v[162:163], v[186:187], 2, s[44:45]
	s_mov_b64 s[16:17], 0x10000
	v_add_co_u32_e32 v130, vcc, s39, v162
	global_load_dwordx4 v[158:161], v[162:163], off offset:16
	global_load_dwordx4 v[174:177], v[162:163], off
	global_load_dwordx4 v[178:181], v[162:163], off offset:528
	global_load_dwordx4 v[182:185], v[162:163], off offset:512
	v_lshl_add_u64 v[128:129], v[162:163], 0, s[16:17]
	v_addc_co_u32_e32 v131, vcc, 0, v163, vcc
	s_mov_b64 s[16:17], 0x10200
	global_load_dwordx4 v[140:143], v[130:131], off
	global_load_dwordx4 v[136:139], v[128:129], off offset:16
	v_lshl_add_u64 v[128:129], v[162:163], 0, s[16:17]
	global_load_dwordx4 v[132:135], v[130:131], off offset:512
	s_nop 0
	global_load_dwordx4 v[128:131], v[128:129], off offset:16
	s_and_b64 vcc, exec, s[10:11]
	s_cbranch_vccz .LBB0_566
	s_barrier

; #define PG8_STAGE(bufoff, gbase, voff) do { _Pragma("unroll") for (int _i = 0; _i < 2; ++_i) \
;     __builtin_amdgcn_global_load_lds((const unsigned*)((const char*)(gbase) + (voff)[_i]), (PG8_LAS unsigned*)(lds + (bufoff) + ldsw + _i * 8192), 16, 0, 0); } while (0)
; #define PG8_LDA(dst, b, h) do { _Pragma("unroll") for (int m = 0; m < 4; ++m) _Pragma("unroll") for (int k = 0; k < 2; ++k) dst[m][k] = *(const PG8_LAS bf16x8*)(lds + PG8_SA(b, h) + aoff + m * 2048 + k * 1024); } while (0)
; #define PG8_LDB(dst, b, h) do { _Pragma("unroll") for (int n = 0; n < 2; ++n) _Pragma("unroll") for (int k = 0; k < 2; ++k) dst[n][k] = *(const PG8_LAS bf16x8*)(lds + PG8_SB(b, h) + boff + n * 2048 + k * 1024); } while (0)
; #define PG8_MMA(ai, bj, At, Bt) do { __builtin_amdgcn_s_setprio(1); _Pragma("unroll") for (int m = 0; m < 4; ++m) _Pragma("unroll") for (int n = 0; n < 2; ++n) _Pragma("unroll") for (int k = 0; k < 2; ++k) \
;     acc[ai][bj][m][n] = __builtin_amdgcn_mfma_f32_16x16x32_bf16(Bt[n][k], At[m][k], acc[ai][bj][m][n], 0, 0, 0); __builtin_amdgcn_s_setprio(0); } while (0)
; #define PG8_WAIT_V(n) asm volatile("s_waitcnt vmcnt(" #n ")" ::: "memory")
; #define PG8_WAIT_L(n) asm volatile("s_waitcnt lgkmcnt(" #n ")" ::: "memory")
; #define PG8_BAR __builtin_amdgcn_s_barrier()
; #define PG8_SCHED __builtin_amdgcn_sched_barrier(0)
; template <class Epi, class Sched>
; DI void gemm_phase(PG8_LAS unsigned char* lds, const Gemm g, const Sched& S, const Epi& E) {
;     ...
;     for (int t = 0; t < nt; t += 2) {
;       const bool last = (t == nt - 2);
;       const char* a1 = cA + (size_t)(t + 1) * kstep;
;       const char* a2 = last ? nA : cA + (size_t)(t + 2) * kstep; const char* b2 = last ? nB : cB + (size_t)(t + 2) * kstep;
;       const char* a3 = a2 + kstep; const char* b3 = b2 + kstep;
;       PG8_LDB(B0, 0, 0); PG8_LDB(B1, 0, 1); PG8_SCHED; PG8_LDA(At, 0, 0); PG8_STAGE(PG8_SA(1, 1), a1 + hstepA, voffA);
;       PG8_WAIT_V(8); PG8_WAIT_L(0); PG8_BAR; PG8_MMA(0, 0, At, B0); PG8_MMA(0, 1, At, B1); PG8_BAR; PG8_SCHED;
;       PG8_LDA(At, 0, 1); PG8_STAGE(PG8_SB(0, 0), b2, voffB); PG8_STAGE(PG8_SB(0, 1), b2 + hstepB, voffB); PG8_STAGE(PG8_SA(0, 0), a2, voffA);
;       PG8_WAIT_V(8); PG8_WAIT_L(0); PG8_BAR; PG8_MMA(1, 0, At, B0); PG8_MMA(1, 1, At, B1); PG8_BAR; PG8_SCHED;
.LBB0_647:
	ds_read_b128 v[144:147], v157
	ds_read_b128 v[148:151], v157 offset:1024
	ds_read_b128 v[174:177], v157 offset:2048
	ds_read_b128 v[178:181], v157 offset:3072
	ds_read_b128 v[182:185], v161
	ds_read_b128 v[186:189], v161 offset:1024
	ds_read_b128 v[190:193], v161 offset:2048
	ds_read_b128 v[194:197], v161 offset:3072
	s_add_u32 s16, s6, 0xfffc0080
	s_addc_u32 s17, s7, -1
	s_cmp_eq_u32 s68, 12
	s_cselect_b32 s37, s1, s17
	s_cselect_b32 s36, s25, s16
	s_cselect_b32 s35, s23, s67
	s_cselect_b32 s34, s65, s66
	s_add_i32 m0, s21, 0xc000
	ds_read_b128 v[198:201], v165
	ds_read_b128 v[202:205], v165 offset:1024
	ds_read_b128 v[206:209], v165 offset:2048
	ds_read_b128 v[214:217], v165 offset:3072
	ds_read_b128 v[218:221], v165 offset:4096
	ds_read_b128 v[222:225], v165 offset:5120
	ds_read_b128 v[226:229], v165 offset:6144
	ds_read_b128 v[230:233], v165 offset:7168
	global_load_lds_dwordx4 v140, s[6:7]
	s_add_i32 m0, s21, 0xe000
	s_nop 0
	global_load_lds_dwordx4 v142, s[6:7]
	s_waitcnt vmcnt(8)
	s_waitcnt lgkmcnt(0)
	s_barrier
	s_setprio 1
	s_waitcnt lgkmcnt(0)
	v_mfma_f32_16x16x32_bf16 v[124:127], v[144:147], v[198:201], v[124:127]
	v_mfma_f32_16x16x32_bf16 v[120:123], v[174:177], v[198:201], v[120:123]
	v_mfma_f32_16x16x32_bf16 v[108:111], v[144:147], v[206:209], v[108:111]
	v_mfma_f32_16x16x32_bf16 v[104:107], v[174:177], v[206:209], v[104:107]
	v_mfma_f32_16x16x32_bf16 v[92:95], v[144:147], v[218:221], v[92:95]
	v_mfma_f32_16x16x32_bf16 v[88:91], v[174:177], v[218:221], v[88:91]
	v_mfma_f32_16x16x32_bf16 v[76:79], v[144:147], v[226:229], v[76:79]
	v_mfma_f32_16x16x32_bf16 v[72:75], v[174:177], v[226:229], v[72:75]
	v_mfma_f32_16x16x32_bf16 v[124:127], v[148:151], v[202:205], v[124:127]
	v_mfma_f32_16x16x32_bf16 v[120:123], v[178:181], v[202:205], v[120:123]
	v_mfma_f32_16x16x32_bf16 v[108:111], v[148:151], v[214:217], v[108:111]
	v_mfma_f32_16x16x32_bf16 v[104:107], v[178:181], v[214:217], v[104:107]
	v_mfma_f32_16x16x32_bf16 v[92:95], v[148:151], v[222:225], v[92:95]
	v_mfma_f32_16x16x32_bf16 v[88:91], v[178:181], v[222:225], v[88:91]
	v_mfma_f32_16x16x32_bf16 v[76:79], v[148:151], v[230:233], v[76:79]
	v_mfma_f32_16x16x32_bf16 v[72:75], v[178:181], v[230:233], v[72:75]
	s_setprio 0
	s_setprio 1
	v_mfma_f32_16x16x32_bf16 v[116:119], v[182:185], v[198:201], v[116:119]
	v_mfma_f32_16x16x32_bf16 v[112:115], v[190:193], v[198:201], v[112:115]
	v_mfma_f32_16x16x32_bf16 v[100:103], v[182:185], v[206:209], v[100:103]
	v_mfma_f32_16x16x32_bf16 v[96:99], v[190:193], v[206:209], v[96:99]
	v_mfma_f32_16x16x32_bf16 v[84:87], v[182:185], v[218:221], v[84:87]
	v_mfma_f32_16x16x32_bf16 v[80:83], v[190:193], v[218:221], v[80:83]
	v_mfma_f32_16x16x32_bf16 v[68:71], v[182:185], v[226:229], v[68:71]
	v_mfma_f32_16x16x32_bf16 v[64:67], v[190:193], v[226:229], v[64:67]
	v_mfma_f32_16x16x32_bf16 v[116:119], v[186:189], v[202:205], v[116:119]
	v_mfma_f32_16x16x32_bf16 v[112:115], v[194:197], v[202:205], v[112:115]
	v_mfma_f32_16x16x32_bf16 v[100:103], v[186:189], v[214:217], v[100:103]
	v_mfma_f32_16x16x32_bf16 v[96:99], v[194:197], v[214:217], v[96:99]
	v_mfma_f32_16x16x32_bf16 v[84:87], v[186:189], v[222:225], v[84:87]
	v_mfma_f32_16x16x32_bf16 v[80:83], v[194:197], v[222:225], v[80:83]
	v_mfma_f32_16x16x32_bf16 v[68:71], v[186:189], v[230:233], v[68:71]
	v_mfma_f32_16x16x32_bf16 v[64:67], v[194:197], v[230:233], v[64:67]
	s_setprio 0
	s_barrier
	s_add_i32 s16, s39, s2
	s_mov_b32 m0, s16
	ds_read_b128 v[198:201], v165 offset:16384
	ds_read_b128 v[202:205], v165 offset:17408
	ds_read_b128 v[206:209], v165 offset:18432
	ds_read_b128 v[214:217], v165 offset:19456
	ds_read_b128 v[218:221], v165 offset:20480
	ds_read_b128 v[222:225], v165 offset:21504
	ds_read_b128 v[226:229], v165 offset:22528
	ds_read_b128 v[230:233], v165 offset:23552
	global_load_lds_dwordx4 v132, s[34:35]
	s_add_i32 m0, s16, 0x2000
	s_add_u32 s16, s34, 0x40000
	s_addc_u32 s17, s35, 0
	s_add_i32 s33, s40, s2
	global_load_lds_dwordx4 v128, s[34:35]
	s_mov_b32 m0, s33
	s_nop 0
	global_load_lds_dwordx4 v132, s[16:17]
	s_add_i32 m0, s33, 0x2000
	s_nop 0
	global_load_lds_dwordx4 v128, s[16:17]
	s_mov_b32 m0, s21
	s_nop 0
	global_load_lds_dwordx4 v134, s[36:37]
	s_mov_b32 m0, s4
	s_nop 0
	global_load_lds_dwordx4 v130, s[36:37]
	s_waitcnt vmcnt(8)
	s_waitcnt lgkmcnt(0)
	s_barrier
	s_setprio 1
	s_waitcnt lgkmcnt(0)
	v_mfma_f32_16x16x32_bf16 v[60:63], v[144:147], v[198:201], v[60:63]
	v_mfma_f32_16x16x32_bf16 v[56:59], v[174:177], v[198:201], v[56:59]
	v_mfma_f32_16x16x32_bf16 v[44:47], v[144:147], v[206:209], v[44:47]
	v_mfma_f32_16x16x32_bf16 v[40:43], v[174:177], v[206:209], v[40:43]
	v_mfma_f32_16x16x32_bf16 v[28:31], v[144:147], v[218:221], v[28:31]
	v_mfma_f32_16x16x32_bf16 v[24:27], v[174:177], v[218:221], v[24:27]
	v_mfma_f32_16x16x32_bf16 v[12:15], v[144:147], v[226:229], v[12:15]
	v_mfma_f32_16x16x32_bf16 v[8:11], v[174:177], v[226:229], v[8:11]
	v_mfma_f32_16x16x32_bf16 v[60:63], v[148:151], v[202:205], v[60:63]
	v_mfma_f32_16x16x32_bf16 v[56:59], v[178:181], v[202:205], v[56:59]
	v_mfma_f32_16x16x32_bf16 v[44:47], v[148:151], v[214:217], v[44:47]
	v_mfma_f32_16x16x32_bf16 v[40:43], v[178:181], v[214:217], v[40:43]
	v_mfma_f32_16x16x32_bf16 v[28:31], v[148:151], v[222:225], v[28:31]
	v_mfma_f32_16x16x32_bf16 v[24:27], v[178:181], v[222:225], v[24:27]
	v_mfma_f32_16x16x32_bf16 v[12:15], v[148:151], v[230:233], v[12:15]
	v_mfma_f32_16x16x32_bf16 v[8:11], v[178:181], v[230:233], v[8:11]
	s_setprio 0
	s_setprio 1
	v_mfma_f32_16x16x32_bf16 v[52:55], v[182:185], v[198:201], v[52:55]
	v_mfma_f32_16x16x32_bf16 v[48:51], v[190:193], v[198:201], v[48:51]
	v_mfma_f32_16x16x32_bf16 v[36:39], v[182:185], v[206:209], v[36:39]
	v_mfma_f32_16x16x32_bf16 v[32:35], v[190:193], v[206:209], v[32:35]
	v_mfma_f32_16x16x32_bf16 v[20:23], v[182:185], v[218:221], v[20:23]
	v_mfma_f32_16x16x32_bf16 v[16:19], v[190:193], v[218:221], v[16:19]
	v_mfma_f32_16x16x32_bf16 v[4:7], v[182:185], v[226:229], v[4:7]
	v_mfma_f32_16x16x32_bf16 v[0:3], v[190:193], v[226:229], v[0:3]
	v_mfma_f32_16x16x32_bf16 v[52:55], v[186:189], v[202:205], v[52:55]
	v_mfma_f32_16x16x32_bf16 v[48:51], v[194:197], v[202:205], v[48:51]
	v_mfma_f32_16x16x32_bf16 v[36:39], v[186:189], v[214:217], v[36:39]
	v_mfma_f32_16x16x32_bf16 v[32:35], v[194:197], v[214:217], v[32:35]
	v_mfma_f32_16x16x32_bf16 v[20:23], v[186:189], v[222:225], v[20:23]
	v_mfma_f32_16x16x32_bf16 v[16:19], v[194:197], v[222:225], v[16:19]
	v_mfma_f32_16x16x32_bf16 v[4:7], v[186:189], v[230:233], v[4:7]
	v_mfma_f32_16x16x32_bf16 v[0:3], v[194:197], v[230:233], v[0:3]
	s_setprio 0
	s_barrier
; #define PG8_STAGE(bufoff, gbase, voff) do { _Pragma("unroll") for (int _i = 0; _i < 2; ++_i) \
;     __builtin_amdgcn_global_load_lds((const unsigned*)((const char*)(gbase) + (voff)[_i]), (PG8_LAS unsigned*)(lds + (bufoff) + ldsw + _i * 8192), 16, 0, 0); } while (0)
; #define PG8_LDA(dst, b, h) do { _Pragma("unroll") for (int m = 0; m < 4; ++m) _Pragma("unroll") for (int k = 0; k < 2; ++k) dst[m][k] = *(const PG8_LAS bf16x8*)(lds + PG8_SA(b, h) + aoff + m * 2048 + k * 1024); } while (0)
; #define PG8_LDB(dst, b, h) do { _Pragma("unroll") for (int n = 0; n < 2; ++n) _Pragma("unroll") for (int k = 0; k < 2; ++k) dst[n][k] = *(const PG8_LAS bf16x8*)(lds + PG8_SB(b, h) + boff + n * 2048 + k * 1024); } while (0)
; #define PG8_MMA(ai, bj, At, Bt) do { __builtin_amdgcn_s_setprio(1); _Pragma("unroll") for (int m = 0; m < 4; ++m) _Pragma("unroll") for (int n = 0; n < 2; ++n) _Pragma("unroll") for (int k = 0; k < 2; ++k) \
;     acc[ai][bj][m][n] = __builtin_amdgcn_mfma_f32_16x16x32_bf16(Bt[n][k], At[m][k], acc[ai][bj][m][n], 0, 0, 0); __builtin_amdgcn_s_setprio(0); } while (0)
; #define PG8_WAIT_V(n) asm volatile("s_waitcnt vmcnt(" #n ")" ::: "memory")
; #define PG8_WAIT_L(n) asm volatile("s_waitcnt lgkmcnt(" #n ")" ::: "memory")
; #define PG8_BAR __builtin_amdgcn_s_barrier()
; #define PG8_SCHED __builtin_amdgcn_sched_barrier(0)
; template <class Epi, class Sched>
; DI void gemm_phase(PG8_LAS unsigned char* lds, const Gemm g, const Sched& S, const Epi& E) {
;     ...
;       PG8_WAIT_V(8); PG8_WAIT_L(0); PG8_BAR; PG8_MMA(1, 0, At, B0); PG8_MMA(1, 1, At, B1); PG8_BAR; PG8_SCHED;
;       PG8_LDB(B0, 1, 0); PG8_LDB(B1, 1, 1); PG8_SCHED; PG8_LDA(At, 1, 0); PG8_STAGE(PG8_SA(0, 1), a2 + hstepA, voffA);
;       PG8_WAIT_V(8); PG8_WAIT_L(0); PG8_BAR; PG8_MMA(0, 0, At, B0); PG8_MMA(0, 1, At, B1); PG8_BAR; PG8_SCHED;
;       PG8_LDA(At, 1, 1); PG8_STAGE(PG8_SB(1, 0), b3, voffB); PG8_STAGE(PG8_SB(1, 1), b3 + hstepB, voffB); PG8_STAGE(PG8_SA(1, 0), a3, voffA);
	ds_read_b128 v[144:147], v171
	ds_read_b128 v[148:151], v171 offset:1024
	ds_read_b128 v[174:177], v171 offset:2048
	ds_read_b128 v[178:181], v171 offset:3072
	ds_read_b128 v[182:185], v173
	ds_read_b128 v[186:189], v173 offset:1024
	ds_read_b128 v[190:193], v173 offset:2048
	ds_read_b128 v[194:197], v173 offset:3072
	s_add_u32 s16, s36, 0x40000
	s_addc_u32 s17, s37, 0
	s_mov_b32 m0, s5
	ds_read_b128 v[198:201], v165 offset:32768
	ds_read_b128 v[202:205], v165 offset:33792
	ds_read_b128 v[206:209], v165 offset:34816
	ds_read_b128 v[214:217], v165 offset:35840
	ds_read_b128 v[218:221], v165 offset:36864
	ds_read_b128 v[222:225], v165 offset:37888
	ds_read_b128 v[226:229], v165 offset:38912
	ds_read_b128 v[230:233], v165 offset:39936
	global_load_lds_dwordx4 v134, s[16:17]
	s_mov_b32 m0, s18
	s_nop 0
	global_load_lds_dwordx4 v130, s[16:17]
	s_waitcnt vmcnt(8)
	s_waitcnt lgkmcnt(0)
	s_barrier
	s_setprio 1
	s_waitcnt lgkmcnt(0)
	v_mfma_f32_16x16x32_bf16 v[124:127], v[144:147], v[198:201], v[124:127]
	v_mfma_f32_16x16x32_bf16 v[120:123], v[174:177], v[198:201], v[120:123]
	v_mfma_f32_16x16x32_bf16 v[108:111], v[144:147], v[206:209], v[108:111]
	v_mfma_f32_16x16x32_bf16 v[104:107], v[174:177], v[206:209], v[104:107]
	v_mfma_f32_16x16x32_bf16 v[92:95], v[144:147], v[218:221], v[92:95]
	v_mfma_f32_16x16x32_bf16 v[88:91], v[174:177], v[218:221], v[88:91]
	v_mfma_f32_16x16x32_bf16 v[76:79], v[144:147], v[226:229], v[76:79]
	v_mfma_f32_16x16x32_bf16 v[72:75], v[174:177], v[226:229], v[72:75]
	v_mfma_f32_16x16x32_bf16 v[124:127], v[148:151], v[202:205], v[124:127]
	v_mfma_f32_16x16x32_bf16 v[120:123], v[178:181], v[202:205], v[120:123]
	v_mfma_f32_16x16x32_bf16 v[108:111], v[148:151], v[214:217], v[108:111]
	v_mfma_f32_16x16x32_bf16 v[104:107], v[178:181], v[214:217], v[104:107]
	v_mfma_f32_16x16x32_bf16 v[92:95], v[148:151], v[222:225], v[92:95]
	v_mfma_f32_16x16x32_bf16 v[88:91], v[178:181], v[222:225], v[88:91]
	v_mfma_f32_16x16x32_bf16 v[76:79], v[148:151], v[230:233], v[76:79]
	v_mfma_f32_16x16x32_bf16 v[72:75], v[178:181], v[230:233], v[72:75]
	s_setprio 0
	s_setprio 1
	v_mfma_f32_16x16x32_bf16 v[116:119], v[182:185], v[198:201], v[116:119]
	v_mfma_f32_16x16x32_bf16 v[112:115], v[190:193], v[198:201], v[112:115]
	v_mfma_f32_16x16x32_bf16 v[100:103], v[182:185], v[206:209], v[100:103]
	v_mfma_f32_16x16x32_bf16 v[96:99], v[190:193], v[206:209], v[96:99]
	v_mfma_f32_16x16x32_bf16 v[84:87], v[182:185], v[218:221], v[84:87]
	v_mfma_f32_16x16x32_bf16 v[80:83], v[190:193], v[218:221], v[80:83]
	v_mfma_f32_16x16x32_bf16 v[68:71], v[182:185], v[226:229], v[68:71]
	v_mfma_f32_16x16x32_bf16 v[64:67], v[190:193], v[226:229], v[64:67]
	v_mfma_f32_16x16x32_bf16 v[116:119], v[186:189], v[202:205], v[116:119]
	v_mfma_f32_16x16x32_bf16 v[112:115], v[194:197], v[202:205], v[112:115]
	v_mfma_f32_16x16x32_bf16 v[100:103], v[186:189], v[214:217], v[100:103]
	v_mfma_f32_16x16x32_bf16 v[96:99], v[194:197], v[214:217], v[96:99]
	v_mfma_f32_16x16x32_bf16 v[84:87], v[186:189], v[222:225], v[84:87]
	v_mfma_f32_16x16x32_bf16 v[80:83], v[194:197], v[222:225], v[80:83]
	v_mfma_f32_16x16x32_bf16 v[68:71], v[186:189], v[230:233], v[68:71]
	v_mfma_f32_16x16x32_bf16 v[64:67], v[194:197], v[230:233], v[64:67]
	s_setprio 0
	s_barrier
	s_add_i32 s16, s45, s2
	s_mov_b32 m0, s16
	ds_read_b128 v[198:201], v165 offset:49152
	ds_read_b128 v[202:205], v165 offset:50176
	ds_read_b128 v[206:209], v165 offset:51200
	ds_read_b128 v[214:217], v165 offset:52224
	ds_read_b128 v[218:221], v165 offset:53248
	ds_read_b128 v[222:225], v165 offset:54272
	ds_read_b128 v[226:229], v165 offset:55296
	ds_read_b128 v[230:233], v165 offset:56320
	s_add_u32 s100, s34, 0x80
	s_addc_u32 s101, s35, 0
	global_load_lds_dwordx4 v132, s[100:101]
	s_add_i32 m0, s16, 0x2000
	s_add_u32 s16, s34, 0x40080
	s_addc_u32 s17, s35, 0
	s_add_i32 s33, s53, s2
	global_load_lds_dwordx4 v128, s[100:101]
	s_mov_b32 m0, s33
	s_nop 0
	global_load_lds_dwordx4 v132, s[16:17]
	s_add_i32 m0, s33, 0x2000
	s_nop 0
	global_load_lds_dwordx4 v128, s[16:17]
	s_mov_b32 m0, s19
	s_nop 0
	s_add_u32 s100, s36, 0x80
	s_addc_u32 s101, s37, 0
	global_load_lds_dwordx4 v134, s[100:101]
	s_mov_b32 m0, s38
	s_nop 0
	global_load_lds_dwordx4 v130, s[100:101]
	s_waitcnt vmcnt(8)
	s_waitcnt lgkmcnt(0)
	s_barrier
; #define PG8_MMA(ai, bj, At, Bt) do { __builtin_amdgcn_s_setprio(1); _Pragma("unroll") for (int m = 0; m < 4; ++m) _Pragma("unroll") for (int n = 0; n < 2; ++n) _Pragma("unroll") for (int k = 0; k < 2; ++k) \
;     acc[ai][bj][m][n] = __builtin_amdgcn_mfma_f32_16x16x32_bf16(Bt[n][k], At[m][k], acc[ai][bj][m][n], 0, 0, 0); __builtin_amdgcn_s_setprio(0); } while (0)
; #define PG8_WAIT_V(n) asm volatile("s_waitcnt vmcnt(" #n ")" ::: "memory")
; #define PG8_WAIT_L(n) asm volatile("s_waitcnt lgkmcnt(" #n ")" ::: "memory")
; #define PG8_BAR __builtin_amdgcn_s_barrier()
; #define PG8_SCHED __builtin_amdgcn_sched_barrier(0)
; DI void rows_rstd(float (&rs)[2][4], const float* ps, const Unit& u, int wr, int fr, int fq, int p_lo, int p_hi, float inv_dim) {
;   f32x4 pv[2][4];
; #pragma unroll
;   for (int ai = 0; ai < 2; ++ai)
; #pragma unroll
;     for (int m = 0; m < 4; ++m) pv[ai][m] = *(const f32x4*)(ps + (size_t)(u.pm * BM + ai * HALF + wr * 64 + m * 16 + fr) * 16 + 4 * fq);
;   const bool use = (4 * fq >= p_lo) && (4 * fq < p_hi);
; template <class Epi, class Sched>
; DI void gemm_phase(PG8_LAS unsigned char* lds, const Gemm g, const Sched& S, const Epi& E) {
;     ...
;       PG8_WAIT_V(8); PG8_WAIT_L(0); PG8_BAR; PG8_MMA(1, 0, At, B0); PG8_MMA(1, 1, At, B1); PG8_BAR; PG8_SCHED;
;     }
;     if (wr == 0) PG8_BAR;
	s_setprio 1
	s_waitcnt lgkmcnt(0)
	v_mfma_f32_16x16x32_bf16 v[60:63], v[144:147], v[198:201], v[60:63]
	v_mfma_f32_16x16x32_bf16 v[56:59], v[174:177], v[198:201], v[56:59]
	v_mfma_f32_16x16x32_bf16 v[44:47], v[144:147], v[206:209], v[44:47]
	v_mfma_f32_16x16x32_bf16 v[40:43], v[174:177], v[206:209], v[40:43]
	v_mfma_f32_16x16x32_bf16 v[28:31], v[144:147], v[218:221], v[28:31]
	v_mfma_f32_16x16x32_bf16 v[24:27], v[174:177], v[218:221], v[24:27]
	v_mfma_f32_16x16x32_bf16 v[12:15], v[144:147], v[226:229], v[12:15]
	v_mfma_f32_16x16x32_bf16 v[8:11], v[174:177], v[226:229], v[8:11]
	v_mfma_f32_16x16x32_bf16 v[60:63], v[148:151], v[202:205], v[60:63]
	v_mfma_f32_16x16x32_bf16 v[56:59], v[178:181], v[202:205], v[56:59]
	v_mfma_f32_16x16x32_bf16 v[44:47], v[148:151], v[214:217], v[44:47]
	v_mfma_f32_16x16x32_bf16 v[40:43], v[178:181], v[214:217], v[40:43]
	v_mfma_f32_16x16x32_bf16 v[28:31], v[148:151], v[222:225], v[28:31]
	v_mfma_f32_16x16x32_bf16 v[24:27], v[178:181], v[222:225], v[24:27]
	v_mfma_f32_16x16x32_bf16 v[12:15], v[148:151], v[230:233], v[12:15]
	v_mfma_f32_16x16x32_bf16 v[8:11], v[178:181], v[230:233], v[8:11]
	s_setprio 0
	s_setprio 1
	v_mfma_f32_16x16x32_bf16 v[52:55], v[182:185], v[198:201], v[52:55]
	v_mfma_f32_16x16x32_bf16 v[48:51], v[190:193], v[198:201], v[48:51]
	v_mfma_f32_16x16x32_bf16 v[36:39], v[182:185], v[206:209], v[36:39]
	v_mfma_f32_16x16x32_bf16 v[32:35], v[190:193], v[206:209], v[32:35]
	v_mfma_f32_16x16x32_bf16 v[20:23], v[182:185], v[218:221], v[20:23]
	v_mfma_f32_16x16x32_bf16 v[16:19], v[190:193], v[218:221], v[16:19]
	v_mfma_f32_16x16x32_bf16 v[4:7], v[182:185], v[226:229], v[4:7]
	v_mfma_f32_16x16x32_bf16 v[0:3], v[190:193], v[226:229], v[0:3]
	v_mfma_f32_16x16x32_bf16 v[52:55], v[186:189], v[202:205], v[52:55]
	v_mfma_f32_16x16x32_bf16 v[48:51], v[194:197], v[202:205], v[48:51]
	v_mfma_f32_16x16x32_bf16 v[36:39], v[186:189], v[214:217], v[36:39]
	v_mfma_f32_16x16x32_bf16 v[32:35], v[194:197], v[214:217], v[32:35]
	v_mfma_f32_16x16x32_bf16 v[20:23], v[186:189], v[222:225], v[20:23]
	v_mfma_f32_16x16x32_bf16 v[16:19], v[194:197], v[222:225], v[16:19]
	v_mfma_f32_16x16x32_bf16 v[4:7], v[186:189], v[230:233], v[4:7]
	v_mfma_f32_16x16x32_bf16 v[0:3], v[194:197], v[230:233], v[0:3]
	s_setprio 0
	s_barrier
	s_add_i32 s68, s68, 2
	s_add_u32 s6, s6, 0x100
	s_addc_u32 s7, s7, 0
	s_add_u32 s66, s66, 0x100
	s_addc_u32 s67, s67, 0
	s_cmp_gt_u32 s68, 13
	s_cbranch_scc0 .LBB0_647
	v_lshl_add_u32 v166, s0, 8, v153
	v_or_b32_e32 v162, 16, v166
	v_ashrrev_i32_e32 v167, 31, v166
	v_ashrrev_i32_e32 v163, 31, v162
	v_or_b32_e32 v158, 32, v166
	v_lshlrev_b64 v[146:147], 6, v[166:167]
	v_lshlrev_b64 v[144:145], 6, v[162:163]
	v_ashrrev_i32_e32 v159, 31, v158
	v_lshl_add_u64 v[146:147], v[138:139], 0, v[146:147]
	v_or_b32_e32 v154, 48, v166
	v_lshl_add_u64 v[144:145], v[138:139], 0, v[144:145]
	global_load_dwordx4 v[174:177], v[146:147], off
	v_lshlrev_b64 v[146:147], 6, v[158:159]
	v_ashrrev_i32_e32 v155, 31, v154
	v_lshl_add_u64 v[146:147], v[138:139], 0, v[146:147]
	global_load_dwordx4 v[178:181], v[144:145], off
	global_load_dwordx4 v[182:185], v[146:147], off
	v_lshlrev_b64 v[144:145], 6, v[154:155]
	v_lshl_add_u64 v[144:145], v[138:139], 0, v[144:145]
	global_load_dwordx4 v[186:189], v[144:145], off
	v_add_u32_e32 v150, 0x80, v166
	v_ashrrev_i32_e32 v151, 31, v150
	v_lshlrev_b64 v[144:145], 6, v[150:151]
	v_add_u32_e32 v148, 0x90, v166
	v_lshl_add_u64 v[144:145], v[138:139], 0, v[144:145]
	v_ashrrev_i32_e32 v149, 31, v148
	global_load_dwordx4 v[190:193], v[144:145], off
	v_lshlrev_b64 v[144:145], 6, v[148:149]
	v_lshl_add_u64 v[144:145], v[138:139], 0, v[144:145]
	global_load_dwordx4 v[194:197], v[144:145], off
	v_and_b32_e32 v145, 64, v169
	v_add_u32_e32 v144, 0xb0, v166
	v_add_u32_e32 v146, 0xa0, v166
	v_add_u32_e32 v152, 64, v145
	v_ashrrev_i32_e32 v145, 31, v144
	v_ashrrev_i32_e32 v147, 31, v146
	v_lshlrev_b64 v[198:199], 6, v[144:145]
	v_lshlrev_b64 v[200:201], 6, v[146:147]
	v_lshl_add_u64 v[198:199], v[138:139], 0, v[198:199]
	v_lshl_add_u64 v[202:203], v[138:139], 0, v[200:201]
	global_load_dwordx4 v[198:201], v[198:199], off
	s_nop 0
	global_load_dwordx4 v[202:205], v[202:203], off
	s_and_b64 vcc, exec, s[12:13]
	s_cbranch_vccz .LBB0_650
	s_barrier

; #define PG8_STAGE(bufoff, gbase, voff) do { _Pragma("unroll") for (int _i = 0; _i < 2; ++_i) \
;     __builtin_amdgcn_global_load_lds((const unsigned*)((const char*)(gbase) + (voff)[_i]), (PG8_LAS unsigned*)(lds + (bufoff) + ldsw + _i * 8192), 16, 0, 0); } while (0)
; #define PG8_LDA(dst, b, h) do { _Pragma("unroll") for (int m = 0; m < 4; ++m) _Pragma("unroll") for (int k = 0; k < 2; ++k) dst[m][k] = *(const PG8_LAS bf16x8*)(lds + PG8_SA(b, h) + aoff + m * 2048 + k * 1024); } while (0)
; #define PG8_LDB(dst, b, h) do { _Pragma("unroll") for (int n = 0; n < 2; ++n) _Pragma("unroll") for (int k = 0; k < 2; ++k) dst[n][k] = *(const PG8_LAS bf16x8*)(lds + PG8_SB(b, h) + boff + n * 2048 + k * 1024); } while (0)
; #define PG8_MMA(ai, bj, At, Bt) do { __builtin_amdgcn_s_setprio(1); _Pragma("unroll") for (int m = 0; m < 4; ++m) _Pragma("unroll") for (int n = 0; n < 2; ++n) _Pragma("unroll") for (int k = 0; k < 2; ++k) \
;     acc[ai][bj][m][n] = __builtin_amdgcn_mfma_f32_16x16x32_bf16(Bt[n][k], At[m][k], acc[ai][bj][m][n], 0, 0, 0); __builtin_amdgcn_s_setprio(0); } while (0)
; #define PG8_WAIT_V(n) asm volatile("s_waitcnt vmcnt(" #n ")" ::: "memory")
; #define PG8_WAIT_L(n) asm volatile("s_waitcnt lgkmcnt(" #n ")" ::: "memory")
; #define PG8_BAR __builtin_amdgcn_s_barrier()
; #define PG8_SCHED __builtin_amdgcn_sched_barrier(0)
; template <class Epi, class Sched>
; DI void gemm_phase(PG8_LAS unsigned char* lds, const Gemm g, const Sched& S, const Epi& E) {
;     ...
;     for (int t = 0; t < nt; t += 2) {
;       const bool last = (t == nt - 2);
;       const char* a1 = cA + (size_t)(t + 1) * kstep;
;       const char* a2 = last ? nA : cA + (size_t)(t + 2) * kstep; const char* b2 = last ? nB : cB + (size_t)(t + 2) * kstep;
;       const char* a3 = a2 + kstep; const char* b3 = b2 + kstep;
;       PG8_LDB(B0, 0, 0); PG8_LDB(B1, 0, 1); PG8_SCHED; PG8_LDA(At, 0, 0); PG8_STAGE(PG8_SA(1, 1), a1 + hstepA, voffA);
;       PG8_WAIT_V(8); PG8_WAIT_L(0); PG8_BAR; PG8_MMA(0, 0, At, B0); PG8_MMA(0, 1, At, B1); PG8_BAR; PG8_SCHED;
;       PG8_LDA(At, 0, 1); PG8_STAGE(PG8_SB(0, 0), b2, voffB); PG8_STAGE(PG8_SB(0, 1), b2 + hstepB, voffB); PG8_STAGE(PG8_SA(0, 0), a2, voffA);
;       PG8_WAIT_V(8); PG8_WAIT_L(0); PG8_BAR; PG8_MMA(1, 0, At, B0); PG8_MMA(1, 1, At, B1); PG8_BAR; PG8_SCHED;
.LBB0_721:
	ds_read_b128 v[128:131], v156
	ds_read_b128 v[132:135], v156 offset:1024
	ds_read_b128 v[150:153], v156 offset:2048
	ds_read_b128 v[162:165], v156 offset:3072
	ds_read_b128 v[166:169], v157
	ds_read_b128 v[170:173], v157 offset:1024
	ds_read_b128 v[174:177], v157 offset:2048
	ds_read_b128 v[178:181], v157 offset:3072
	s_add_u32 s26, s24, 0x100
	s_addc_u32 s27, s25, 0
	s_cmp_eq_u32 s65, 40
	s_cselect_b32 s31, s21, s27
	s_cselect_b32 s30, s20, s26
	s_cselect_b32 s29, s23, s64
	s_cselect_b32 s28, s22, s55
	s_add_i32 m0, s3, 0xc000
	ds_read_b128 v[182:185], v158
	ds_read_b128 v[186:189], v158 offset:1024
	ds_read_b128 v[190:193], v158 offset:2048
	ds_read_b128 v[194:197], v158 offset:3072
	ds_read_b128 v[198:201], v158 offset:4096
	ds_read_b128 v[202:205], v158 offset:5120
	ds_read_b128 v[206:209], v158 offset:6144
	ds_read_b128 v[214:217], v158 offset:7168
	global_load_lds_dwordx4 v146, s[24:25]
	s_add_i32 m0, s3, 0xe000
	s_nop 0
	global_load_lds_dwordx4 v148, s[24:25]
	s_waitcnt vmcnt(8)
	s_waitcnt lgkmcnt(0)
	s_barrier
	s_setprio 1
	s_waitcnt lgkmcnt(0)
	v_mfma_f32_16x16x32_bf16 v[124:127], v[128:131], v[182:185], v[124:127]
	v_mfma_f32_16x16x32_bf16 v[120:123], v[150:153], v[182:185], v[120:123]
	v_mfma_f32_16x16x32_bf16 v[108:111], v[128:131], v[190:193], v[108:111]
	v_mfma_f32_16x16x32_bf16 v[104:107], v[150:153], v[190:193], v[104:107]
	v_mfma_f32_16x16x32_bf16 v[92:95], v[128:131], v[198:201], v[92:95]
	v_mfma_f32_16x16x32_bf16 v[88:91], v[150:153], v[198:201], v[88:91]
	v_mfma_f32_16x16x32_bf16 v[76:79], v[128:131], v[206:209], v[76:79]
	v_mfma_f32_16x16x32_bf16 v[72:75], v[150:153], v[206:209], v[72:75]
	v_mfma_f32_16x16x32_bf16 v[124:127], v[132:135], v[186:189], v[124:127]
	v_mfma_f32_16x16x32_bf16 v[120:123], v[162:165], v[186:189], v[120:123]
	v_mfma_f32_16x16x32_bf16 v[108:111], v[132:135], v[194:197], v[108:111]
	v_mfma_f32_16x16x32_bf16 v[104:107], v[162:165], v[194:197], v[104:107]
	v_mfma_f32_16x16x32_bf16 v[92:95], v[132:135], v[202:205], v[92:95]
	v_mfma_f32_16x16x32_bf16 v[88:91], v[162:165], v[202:205], v[88:91]
	v_mfma_f32_16x16x32_bf16 v[76:79], v[132:135], v[214:217], v[76:79]
	v_mfma_f32_16x16x32_bf16 v[72:75], v[162:165], v[214:217], v[72:75]
	s_setprio 0
	s_setprio 1
	v_mfma_f32_16x16x32_bf16 v[116:119], v[166:169], v[182:185], v[116:119]
	v_mfma_f32_16x16x32_bf16 v[112:115], v[174:177], v[182:185], v[112:115]
	v_mfma_f32_16x16x32_bf16 v[100:103], v[166:169], v[190:193], v[100:103]
	v_mfma_f32_16x16x32_bf16 v[96:99], v[174:177], v[190:193], v[96:99]
	v_mfma_f32_16x16x32_bf16 v[84:87], v[166:169], v[198:201], v[84:87]
	v_mfma_f32_16x16x32_bf16 v[80:83], v[174:177], v[198:201], v[80:83]
	v_mfma_f32_16x16x32_bf16 v[68:71], v[166:169], v[206:209], v[68:71]
	v_mfma_f32_16x16x32_bf16 v[64:67], v[174:177], v[206:209], v[64:67]
	v_mfma_f32_16x16x32_bf16 v[116:119], v[170:173], v[186:189], v[116:119]
	v_mfma_f32_16x16x32_bf16 v[112:115], v[178:181], v[186:189], v[112:115]
	v_mfma_f32_16x16x32_bf16 v[100:103], v[170:173], v[194:197], v[100:103]
	v_mfma_f32_16x16x32_bf16 v[96:99], v[178:181], v[194:197], v[96:99]
	v_mfma_f32_16x16x32_bf16 v[84:87], v[170:173], v[202:205], v[84:87]
	v_mfma_f32_16x16x32_bf16 v[80:83], v[178:181], v[202:205], v[80:83]
	v_mfma_f32_16x16x32_bf16 v[68:71], v[170:173], v[214:217], v[68:71]
	v_mfma_f32_16x16x32_bf16 v[64:67], v[178:181], v[214:217], v[64:67]
	s_setprio 0
	s_barrier
	s_add_i32 s16, s37, s2
	s_mov_b32 m0, s16
	ds_read_b128 v[182:185], v158 offset:16384
	ds_read_b128 v[186:189], v158 offset:17408
	ds_read_b128 v[190:193], v158 offset:18432
	ds_read_b128 v[194:197], v158 offset:19456
	ds_read_b128 v[198:201], v158 offset:20480
	ds_read_b128 v[202:205], v158 offset:21504
	ds_read_b128 v[206:209], v158 offset:22528
	ds_read_b128 v[214:217], v158 offset:23552
	global_load_lds_dwordx4 v138, s[28:29]
	s_add_i32 m0, s16, 0x2000
	s_add_u32 s16, s28, 0xb0000
	s_addc_u32 s17, s29, 0
	s_add_i32 s24, s38, s2
	global_load_lds_dwordx4 v142, s[28:29]
	s_mov_b32 m0, s24
	s_nop 0
	global_load_lds_dwordx4 v138, s[16:17]
	s_add_i32 m0, s24, 0x2000
	s_nop 0
	global_load_lds_dwordx4 v142, s[16:17]
	s_mov_b32 m0, s3
	s_nop 0
	global_load_lds_dwordx4 v136, s[30:31]
	s_mov_b32 m0, s34
	s_nop 0
	global_load_lds_dwordx4 v140, s[30:31]
	s_waitcnt vmcnt(8)
	s_waitcnt lgkmcnt(0)
	s_barrier
	s_setprio 1
	s_waitcnt lgkmcnt(0)
	v_mfma_f32_16x16x32_bf16 v[60:63], v[128:131], v[182:185], v[60:63]
	v_mfma_f32_16x16x32_bf16 v[56:59], v[150:153], v[182:185], v[56:59]
	v_mfma_f32_16x16x32_bf16 v[44:47], v[128:131], v[190:193], v[44:47]
	v_mfma_f32_16x16x32_bf16 v[40:43], v[150:153], v[190:193], v[40:43]
	v_mfma_f32_16x16x32_bf16 v[28:31], v[128:131], v[198:201], v[28:31]
	v_mfma_f32_16x16x32_bf16 v[24:27], v[150:153], v[198:201], v[24:27]
	v_mfma_f32_16x16x32_bf16 v[12:15], v[128:131], v[206:209], v[12:15]
	v_mfma_f32_16x16x32_bf16 v[8:11], v[150:153], v[206:209], v[8:11]
	v_mfma_f32_16x16x32_bf16 v[60:63], v[132:135], v[186:189], v[60:63]
	v_mfma_f32_16x16x32_bf16 v[56:59], v[162:165], v[186:189], v[56:59]
	v_mfma_f32_16x16x32_bf16 v[44:47], v[132:135], v[194:197], v[44:47]
	v_mfma_f32_16x16x32_bf16 v[40:43], v[162:165], v[194:197], v[40:43]
	v_mfma_f32_16x16x32_bf16 v[28:31], v[132:135], v[202:205], v[28:31]
	v_mfma_f32_16x16x32_bf16 v[24:27], v[162:165], v[202:205], v[24:27]
	v_mfma_f32_16x16x32_bf16 v[12:15], v[132:135], v[214:217], v[12:15]
	v_mfma_f32_16x16x32_bf16 v[8:11], v[162:165], v[214:217], v[8:11]
	s_setprio 0
	s_setprio 1
	v_mfma_f32_16x16x32_bf16 v[52:55], v[166:169], v[182:185], v[52:55]
	v_mfma_f32_16x16x32_bf16 v[48:51], v[174:177], v[182:185], v[48:51]
	v_mfma_f32_16x16x32_bf16 v[36:39], v[166:169], v[190:193], v[36:39]
	v_mfma_f32_16x16x32_bf16 v[32:35], v[174:177], v[190:193], v[32:35]
	v_mfma_f32_16x16x32_bf16 v[20:23], v[166:169], v[198:201], v[20:23]
	v_mfma_f32_16x16x32_bf16 v[16:19], v[174:177], v[198:201], v[16:19]
	v_mfma_f32_16x16x32_bf16 v[4:7], v[166:169], v[206:209], v[4:7]
	v_mfma_f32_16x16x32_bf16 v[0:3], v[174:177], v[206:209], v[0:3]
	v_mfma_f32_16x16x32_bf16 v[52:55], v[170:173], v[186:189], v[52:55]
	v_mfma_f32_16x16x32_bf16 v[48:51], v[178:181], v[186:189], v[48:51]
	v_mfma_f32_16x16x32_bf16 v[36:39], v[170:173], v[194:197], v[36:39]
	v_mfma_f32_16x16x32_bf16 v[32:35], v[178:181], v[194:197], v[32:35]
	v_mfma_f32_16x16x32_bf16 v[20:23], v[170:173], v[202:205], v[20:23]
	v_mfma_f32_16x16x32_bf16 v[16:19], v[178:181], v[202:205], v[16:19]
	v_mfma_f32_16x16x32_bf16 v[4:7], v[170:173], v[214:217], v[4:7]
	v_mfma_f32_16x16x32_bf16 v[0:3], v[178:181], v[214:217], v[0:3]
	s_setprio 0
	s_barrier
; #define PG8_STAGE(bufoff, gbase, voff) do { _Pragma("unroll") for (int _i = 0; _i < 2; ++_i) \
;     __builtin_amdgcn_global_load_lds((const unsigned*)((const char*)(gbase) + (voff)[_i]), (PG8_LAS unsigned*)(lds + (bufoff) + ldsw + _i * 8192), 16, 0, 0); } while (0)
; #define PG8_LDA(dst, b, h) do { _Pragma("unroll") for (int m = 0; m < 4; ++m) _Pragma("unroll") for (int k = 0; k < 2; ++k) dst[m][k] = *(const PG8_LAS bf16x8*)(lds + PG8_SA(b, h) + aoff + m * 2048 + k * 1024); } while (0)
; #define PG8_LDB(dst, b, h) do { _Pragma("unroll") for (int n = 0; n < 2; ++n) _Pragma("unroll") for (int k = 0; k < 2; ++k) dst[n][k] = *(const PG8_LAS bf16x8*)(lds + PG8_SB(b, h) + boff + n * 2048 + k * 1024); } while (0)
; #define PG8_MMA(ai, bj, At, Bt) do { __builtin_amdgcn_s_setprio(1); _Pragma("unroll") for (int m = 0; m < 4; ++m) _Pragma("unroll") for (int n = 0; n < 2; ++n) _Pragma("unroll") for (int k = 0; k < 2; ++k) \
;     acc[ai][bj][m][n] = __builtin_amdgcn_mfma_f32_16x16x32_bf16(Bt[n][k], At[m][k], acc[ai][bj][m][n], 0, 0, 0); __builtin_amdgcn_s_setprio(0); } while (0)
; #define PG8_WAIT_V(n) asm volatile("s_waitcnt vmcnt(" #n ")" ::: "memory")
; #define PG8_WAIT_L(n) asm volatile("s_waitcnt lgkmcnt(" #n ")" ::: "memory")
; #define PG8_BAR __builtin_amdgcn_s_barrier()
; #define PG8_SCHED __builtin_amdgcn_sched_barrier(0)
; template <class Epi, class Sched>
; DI void gemm_phase(PG8_LAS unsigned char* lds, const Gemm g, const Sched& S, const Epi& E) {
;     ...
;       PG8_LDB(B0, 1, 0); PG8_LDB(B1, 1, 1); PG8_SCHED; PG8_LDA(At, 1, 0); PG8_STAGE(PG8_SA(0, 1), a2 + hstepA, voffA);
;       PG8_WAIT_V(8); PG8_WAIT_L(0); PG8_BAR; PG8_MMA(0, 0, At, B0); PG8_MMA(0, 1, At, B1); PG8_BAR; PG8_SCHED;
	s_mov_b32 s16, 0x18000
	s_add_i32 s24, s16, 0x110
	v_add_u32_e32 v161, s24, v155
	ds_read_b128 v[128:131], v161
	ds_read_b128 v[132:135], v161 offset:1024
	ds_read_b128 v[150:153], v161 offset:2048
	ds_read_b128 v[162:165], v161 offset:3072
	ds_read_b128 v[166:169], v160
	ds_read_b128 v[170:173], v160 offset:1024
	ds_read_b128 v[174:177], v160 offset:2048
	ds_read_b128 v[178:181], v160 offset:3072
	s_add_u32 s16, s30, 0xb0000
	s_addc_u32 s17, s31, 0
	s_mov_b32 m0, s18
	ds_read_b128 v[182:185], v158 offset:32768
	ds_read_b128 v[186:189], v158 offset:33792
	ds_read_b128 v[190:193], v158 offset:34816
	ds_read_b128 v[194:197], v158 offset:35840
	ds_read_b128 v[198:201], v158 offset:36864
	ds_read_b128 v[202:205], v158 offset:37888
	ds_read_b128 v[206:209], v158 offset:38912
	ds_read_b128 v[214:217], v158 offset:39936
	global_load_lds_dwordx4 v136, s[16:17]
	s_mov_b32 m0, s19
	s_nop 0
	global_load_lds_dwordx4 v140, s[16:17]
	s_waitcnt vmcnt(8)
	s_waitcnt lgkmcnt(0)
	s_barrier
	s_setprio 1
	s_waitcnt lgkmcnt(0)
	v_mfma_f32_16x16x32_bf16 v[124:127], v[128:131], v[182:185], v[124:127]
	v_mfma_f32_16x16x32_bf16 v[120:123], v[150:153], v[182:185], v[120:123]
	v_mfma_f32_16x16x32_bf16 v[108:111], v[128:131], v[190:193], v[108:111]
	v_mfma_f32_16x16x32_bf16 v[104:107], v[150:153], v[190:193], v[104:107]
	v_mfma_f32_16x16x32_bf16 v[92:95], v[128:131], v[198:201], v[92:95]
	v_mfma_f32_16x16x32_bf16 v[88:91], v[150:153], v[198:201], v[88:91]
	v_mfma_f32_16x16x32_bf16 v[76:79], v[128:131], v[206:209], v[76:79]
	v_mfma_f32_16x16x32_bf16 v[72:75], v[150:153], v[206:209], v[72:75]
	v_mfma_f32_16x16x32_bf16 v[124:127], v[132:135], v[186:189], v[124:127]
	v_mfma_f32_16x16x32_bf16 v[120:123], v[162:165], v[186:189], v[120:123]
	v_mfma_f32_16x16x32_bf16 v[108:111], v[132:135], v[194:197], v[108:111]
	v_mfma_f32_16x16x32_bf16 v[104:107], v[162:165], v[194:197], v[104:107]
	v_mfma_f32_16x16x32_bf16 v[92:95], v[132:135], v[202:205], v[92:95]
	v_mfma_f32_16x16x32_bf16 v[88:91], v[162:165], v[202:205], v[88:91]
	v_mfma_f32_16x16x32_bf16 v[76:79], v[132:135], v[214:217], v[76:79]
	v_mfma_f32_16x16x32_bf16 v[72:75], v[162:165], v[214:217], v[72:75]
	s_setprio 0
	s_setprio 1
	v_mfma_f32_16x16x32_bf16 v[116:119], v[166:169], v[182:185], v[116:119]
	v_mfma_f32_16x16x32_bf16 v[112:115], v[174:177], v[182:185], v[112:115]
	v_mfma_f32_16x16x32_bf16 v[100:103], v[166:169], v[190:193], v[100:103]
	v_mfma_f32_16x16x32_bf16 v[96:99], v[174:177], v[190:193], v[96:99]
	v_mfma_f32_16x16x32_bf16 v[84:87], v[166:169], v[198:201], v[84:87]
	v_mfma_f32_16x16x32_bf16 v[80:83], v[174:177], v[198:201], v[80:83]
	v_mfma_f32_16x16x32_bf16 v[68:71], v[166:169], v[206:209], v[68:71]
	v_mfma_f32_16x16x32_bf16 v[64:67], v[174:177], v[206:209], v[64:67]
	v_mfma_f32_16x16x32_bf16 v[116:119], v[170:173], v[186:189], v[116:119]
	v_mfma_f32_16x16x32_bf16 v[112:115], v[178:181], v[186:189], v[112:115]
	v_mfma_f32_16x16x32_bf16 v[100:103], v[170:173], v[194:197], v[100:103]
	v_mfma_f32_16x16x32_bf16 v[96:99], v[178:181], v[194:197], v[96:99]
	v_mfma_f32_16x16x32_bf16 v[84:87], v[170:173], v[202:205], v[84:87]
	v_mfma_f32_16x16x32_bf16 v[80:83], v[178:181], v[202:205], v[80:83]
	v_mfma_f32_16x16x32_bf16 v[68:71], v[170:173], v[214:217], v[68:71]
	v_mfma_f32_16x16x32_bf16 v[64:67], v[178:181], v[214:217], v[64:67]
	s_setprio 0
	s_barrier
; #define PG8_STAGE(bufoff, gbase, voff) do { _Pragma("unroll") for (int _i = 0; _i < 2; ++_i) \
;     __builtin_amdgcn_global_load_lds((const unsigned*)((const char*)(gbase) + (voff)[_i]), (PG8_LAS unsigned*)(lds + (bufoff) + ldsw + _i * 8192), 16, 0, 0); } while (0)
; #define PG8_LDA(dst, b, h) do { _Pragma("unroll") for (int m = 0; m < 4; ++m) _Pragma("unroll") for (int k = 0; k < 2; ++k) dst[m][k] = *(const PG8_LAS bf16x8*)(lds + PG8_SA(b, h) + aoff + m * 2048 + k * 1024); } while (0)
; #define PG8_MMA(ai, bj, At, Bt) do { __builtin_amdgcn_s_setprio(1); _Pragma("unroll") for (int m = 0; m < 4; ++m) _Pragma("unroll") for (int n = 0; n < 2; ++n) _Pragma("unroll") for (int k = 0; k < 2; ++k) \
;     acc[ai][bj][m][n] = __builtin_amdgcn_mfma_f32_16x16x32_bf16(Bt[n][k], At[m][k], acc[ai][bj][m][n], 0, 0, 0); __builtin_amdgcn_s_setprio(0); } while (0)
; #define PG8_WAIT_V(n) asm volatile("s_waitcnt vmcnt(" #n ")" ::: "memory")
; #define PG8_WAIT_L(n) asm volatile("s_waitcnt lgkmcnt(" #n ")" ::: "memory")
; #define PG8_BAR __builtin_amdgcn_s_barrier()
; #define PG8_SCHED __builtin_amdgcn_sched_barrier(0)
;   DI void operator()(const f32x4 (&acc)[2][2][4][2], const Unit& u, int wr, int wc, int fr, int fq) const {
;     const int row0 = u.pm * BM + wr * 64 + fr;
;     const size_t base = (size_t)row0 * DM + u.pn * BM + wc * 32 + 8 * fq;
;     f32x4 xv[2][4];
;     u32x4 xh[2][2];
;     ...
;     RES_LD(0)
; #pragma unroll
;     for (int i = 0; i < 8; ++i) {
;       const int ai = i >> 2, m = i & 3;
;       if (i + 1 < 8) RES_LD(i + 1)
; template <class Epi, class Sched>
; DI void gemm_phase(PG8_LAS unsigned char* lds, const Gemm g, const Sched& S, const Epi& E) {
;     ...
;       PG8_LDA(At, 1, 1); PG8_STAGE(PG8_SB(1, 0), b3, voffB); PG8_STAGE(PG8_SB(1, 1), b3 + hstepB, voffB); PG8_STAGE(PG8_SA(1, 0), a3, voffA);
;       PG8_WAIT_V(8); PG8_WAIT_L(0); PG8_BAR; PG8_MMA(1, 0, At, B0); PG8_MMA(1, 1, At, B1); PG8_BAR; PG8_SCHED;
;     }
;     if (wr == 0) PG8_BAR;
	s_add_i32 s16, s24, s2
	s_mov_b32 m0, s16
	ds_read_b128 v[182:185], v158 offset:49152
	ds_read_b128 v[186:189], v158 offset:50176
	ds_read_b128 v[190:193], v158 offset:51200
	ds_read_b128 v[194:197], v158 offset:52224
	ds_read_b128 v[198:201], v158 offset:53248
	ds_read_b128 v[202:205], v158 offset:54272
	ds_read_b128 v[206:209], v158 offset:55296
	ds_read_b128 v[214:217], v158 offset:56320
	s_add_u32 s100, s28, 0x80
	s_addc_u32 s101, s29, 0
	global_load_lds_dwordx4 v138, s[100:101]
	s_add_i32 m0, s16, 0x2000
	s_add_u32 s16, s28, 0xb0080
	s_addc_u32 s17, s29, 0
	s_add_i32 s24, s39, s2
	global_load_lds_dwordx4 v142, s[100:101]
	s_mov_b32 m0, s24
	s_nop 0
	global_load_lds_dwordx4 v138, s[16:17]
	s_add_i32 m0, s24, 0x2000
	s_nop 0
	global_load_lds_dwordx4 v142, s[16:17]
	s_mov_b32 m0, s5
	s_nop 0
	s_add_u32 s100, s30, 0x80
	s_addc_u32 s101, s31, 0
	global_load_lds_dwordx4 v136, s[100:101]
	s_mov_b32 m0, s35
	s_nop 0
	global_load_lds_dwordx4 v140, s[100:101]
	s_waitcnt vmcnt(8)
	s_waitcnt lgkmcnt(0)
	s_barrier
	s_setprio 1
	s_waitcnt lgkmcnt(0)
	v_mfma_f32_16x16x32_bf16 v[60:63], v[128:131], v[182:185], v[60:63]
	v_mfma_f32_16x16x32_bf16 v[56:59], v[150:153], v[182:185], v[56:59]
	v_mfma_f32_16x16x32_bf16 v[44:47], v[128:131], v[190:193], v[44:47]
	v_mfma_f32_16x16x32_bf16 v[40:43], v[150:153], v[190:193], v[40:43]
	v_mfma_f32_16x16x32_bf16 v[28:31], v[128:131], v[198:201], v[28:31]
	v_mfma_f32_16x16x32_bf16 v[24:27], v[150:153], v[198:201], v[24:27]
	v_mfma_f32_16x16x32_bf16 v[12:15], v[128:131], v[206:209], v[12:15]
	v_mfma_f32_16x16x32_bf16 v[8:11], v[150:153], v[206:209], v[8:11]
	v_mfma_f32_16x16x32_bf16 v[60:63], v[132:135], v[186:189], v[60:63]
	v_mfma_f32_16x16x32_bf16 v[56:59], v[162:165], v[186:189], v[56:59]
	v_mfma_f32_16x16x32_bf16 v[44:47], v[132:135], v[194:197], v[44:47]
	v_mfma_f32_16x16x32_bf16 v[40:43], v[162:165], v[194:197], v[40:43]
	v_mfma_f32_16x16x32_bf16 v[28:31], v[132:135], v[202:205], v[28:31]
	v_mfma_f32_16x16x32_bf16 v[24:27], v[162:165], v[202:205], v[24:27]
	v_mfma_f32_16x16x32_bf16 v[12:15], v[132:135], v[214:217], v[12:15]
	v_mfma_f32_16x16x32_bf16 v[8:11], v[162:165], v[214:217], v[8:11]
	s_setprio 0
	s_setprio 1
	v_mfma_f32_16x16x32_bf16 v[52:55], v[166:169], v[182:185], v[52:55]
	v_mfma_f32_16x16x32_bf16 v[48:51], v[174:177], v[182:185], v[48:51]
	v_mfma_f32_16x16x32_bf16 v[36:39], v[166:169], v[190:193], v[36:39]
	v_mfma_f32_16x16x32_bf16 v[32:35], v[174:177], v[190:193], v[32:35]
	v_mfma_f32_16x16x32_bf16 v[20:23], v[166:169], v[198:201], v[20:23]
	v_mfma_f32_16x16x32_bf16 v[16:19], v[174:177], v[198:201], v[16:19]
	v_mfma_f32_16x16x32_bf16 v[4:7], v[166:169], v[206:209], v[4:7]
	v_mfma_f32_16x16x32_bf16 v[0:3], v[174:177], v[206:209], v[0:3]
	v_mfma_f32_16x16x32_bf16 v[52:55], v[170:173], v[186:189], v[52:55]
	v_mfma_f32_16x16x32_bf16 v[48:51], v[178:181], v[186:189], v[48:51]
	v_mfma_f32_16x16x32_bf16 v[36:39], v[170:173], v[194:197], v[36:39]
	v_mfma_f32_16x16x32_bf16 v[32:35], v[178:181], v[194:197], v[32:35]
	v_mfma_f32_16x16x32_bf16 v[20:23], v[170:173], v[202:205], v[20:23]
	v_mfma_f32_16x16x32_bf16 v[16:19], v[178:181], v[202:205], v[16:19]
	v_mfma_f32_16x16x32_bf16 v[4:7], v[170:173], v[214:217], v[4:7]
	v_mfma_f32_16x16x32_bf16 v[0:3], v[178:181], v[214:217], v[0:3]
	s_setprio 0
	s_barrier
	s_add_i32 s65, s65, 2
	s_add_u32 s55, s55, 0x100
	s_addc_u32 s64, s64, 0
	s_cmp_gt_u32 s65, 41
	s_mov_b64 s[24:25], s[26:27]
	s_cbranch_scc0 .LBB0_721
	v_lshl_add_u32 v152, s53, 8, v154
	v_ashrrev_i32_e32 v153, 31, v152
	s_lshl_b32 s16, s45, 8
	v_lshlrev_b64 v[128:129], 11, v[152:153]
	s_ashr_i32 s17, s16, 31
	v_lshl_add_u64 v[128:129], s[50:51], 0, v[128:129]
	v_lshl_add_u64 v[128:129], s[16:17], 1, v[128:129]
	v_lshl_add_u64 v[128:129], v[128:129], 0, s[14:15]
	v_lshl_add_u64 v[150:151], v[128:129], 0, v[144:145]
	s_mov_b32 s16, 0x8000
	v_add_co_u32_e32 v128, vcc, s16, v150
	global_load_dwordx4 v[164:167], v[150:151], off
	global_load_dwordx4 v[168:171], v[150:151], off offset:256
	v_addc_co_u32_e32 v129, vcc, 0, v151, vcc
	global_load_dwordx4 v[132:135], v[128:129], off
	s_nop 0
	global_load_dwordx4 v[128:131], v[128:129], off offset:256
	s_and_b64 vcc, exec, s[12:13]
	s_cbranch_vccz .LBB0_724
	s_barrier

; #define PG8_STAGE(bufoff, gbase, voff) do { _Pragma("unroll") for (int _i = 0; _i < 2; ++_i) \
;     __builtin_amdgcn_global_load_lds((const unsigned*)((const char*)(gbase) + (voff)[_i]), (PG8_LAS unsigned*)(lds + (bufoff) + ldsw + _i * 8192), 16, 0, 0); } while (0)
; #define PG8_LDA(dst, b, h) do { _Pragma("unroll") for (int m = 0; m < 4; ++m) _Pragma("unroll") for (int k = 0; k < 2; ++k) dst[m][k] = *(const PG8_LAS bf16x8*)(lds + PG8_SA(b, h) + aoff + m * 2048 + k * 1024); } while (0)
; #define PG8_LDB(dst, b, h) do { _Pragma("unroll") for (int n = 0; n < 2; ++n) _Pragma("unroll") for (int k = 0; k < 2; ++k) dst[n][k] = *(const PG8_LAS bf16x8*)(lds + PG8_SB(b, h) + boff + n * 2048 + k * 1024); } while (0)
; #define PG8_MMA(ai, bj, At, Bt) do { __builtin_amdgcn_s_setprio(1); _Pragma("unroll") for (int m = 0; m < 4; ++m) _Pragma("unroll") for (int n = 0; n < 2; ++n) _Pragma("unroll") for (int k = 0; k < 2; ++k) \
;     acc[ai][bj][m][n] = __builtin_amdgcn_mfma_f32_16x16x32_bf16(Bt[n][k], At[m][k], acc[ai][bj][m][n], 0, 0, 0); __builtin_amdgcn_s_setprio(0); } while (0)
; #define PG8_WAIT_V(n) asm volatile("s_waitcnt vmcnt(" #n ")" ::: "memory")
; #define PG8_WAIT_L(n) asm volatile("s_waitcnt lgkmcnt(" #n ")" ::: "memory")
; #define PG8_BAR __builtin_amdgcn_s_barrier()
; #define PG8_SCHED __builtin_amdgcn_sched_barrier(0)
; template <class Epi, class Sched>
; DI void gemm_phase(PG8_LAS unsigned char* lds, const Gemm g, const Sched& S, const Epi& E) {
;     ...
;     for (int t = 0; t < nt; t += 2) {
;       const bool last = (t == nt - 2);
;       const char* a1 = cA + (size_t)(t + 1) * kstep;
;       const char* a2 = last ? nA : cA + (size_t)(t + 2) * kstep; const char* b2 = last ? nB : cB + (size_t)(t + 2) * kstep;
;       const char* a3 = a2 + kstep; const char* b3 = b2 + kstep;
;       PG8_LDB(B0, 0, 0); PG8_LDB(B1, 0, 1); PG8_SCHED; PG8_LDA(At, 0, 0); PG8_STAGE(PG8_SA(1, 1), a1 + hstepA, voffA);
;       PG8_WAIT_V(8); PG8_WAIT_L(0); PG8_BAR; PG8_MMA(0, 0, At, B0); PG8_MMA(0, 1, At, B1); PG8_BAR; PG8_SCHED;
;       PG8_LDA(At, 0, 1); PG8_STAGE(PG8_SB(0, 0), b2, voffB); PG8_STAGE(PG8_SB(0, 1), b2 + hstepB, voffB); PG8_STAGE(PG8_SA(0, 0), a2, voffA);
;       PG8_WAIT_V(8); PG8_WAIT_L(0); PG8_BAR; PG8_MMA(1, 0, At, B0); PG8_MMA(1, 1, At, B1); PG8_BAR; PG8_SCHED;
.LBB0_807:
	ds_read_b128 v[144:147], v195
	ds_read_b128 v[148:151], v195 offset:1024
	ds_read_b128 v[152:155], v195 offset:2048
	ds_read_b128 v[156:159], v195 offset:3072
	ds_read_b128 v[160:163], v196
	ds_read_b128 v[164:167], v196 offset:1024
	ds_read_b128 v[168:171], v196 offset:2048
	ds_read_b128 v[172:175], v196 offset:3072
	s_add_u32 s16, s10, 0xfffc0080
	s_addc_u32 s17, s11, -1
	s_cmp_eq_u32 s73, 12
	s_cselect_b32 s45, s1, s17
	s_cselect_b32 s44, s9, s16
	s_cselect_b32 s41, s22, s72
	s_cselect_b32 s40, s29, s31
	s_add_i32 m0, s3, 0xc000
	ds_read_b128 v[176:179], v197
	ds_read_b128 v[180:183], v197 offset:1024
	ds_read_b128 v[184:187], v197 offset:2048
	ds_read_b128 v[188:191], v197 offset:3072
	ds_read_b128 v[202:205], v197 offset:4096
	ds_read_b128 v[206:209], v197 offset:5120
	ds_read_b128 v[214:217], v197 offset:6144
	ds_read_b128 v[218:221], v197 offset:7168
	global_load_lds_dwordx4 v138, s[10:11]
	s_add_i32 m0, s3, 0xe000
	s_nop 0
	global_load_lds_dwordx4 v140, s[10:11]
	s_waitcnt vmcnt(8)
	s_waitcnt lgkmcnt(0)
	s_barrier
	s_setprio 1
	s_waitcnt lgkmcnt(0)
	v_mfma_f32_16x16x32_bf16 v[124:127], v[144:147], v[176:179], v[124:127]
	v_mfma_f32_16x16x32_bf16 v[120:123], v[152:155], v[176:179], v[120:123]
	v_mfma_f32_16x16x32_bf16 v[108:111], v[144:147], v[184:187], v[108:111]
	v_mfma_f32_16x16x32_bf16 v[104:107], v[152:155], v[184:187], v[104:107]
	v_mfma_f32_16x16x32_bf16 v[92:95], v[144:147], v[202:205], v[92:95]
	v_mfma_f32_16x16x32_bf16 v[88:91], v[152:155], v[202:205], v[88:91]
	v_mfma_f32_16x16x32_bf16 v[76:79], v[144:147], v[214:217], v[76:79]
	v_mfma_f32_16x16x32_bf16 v[72:75], v[152:155], v[214:217], v[72:75]
	v_mfma_f32_16x16x32_bf16 v[124:127], v[148:151], v[180:183], v[124:127]
	v_mfma_f32_16x16x32_bf16 v[120:123], v[156:159], v[180:183], v[120:123]
	v_mfma_f32_16x16x32_bf16 v[108:111], v[148:151], v[188:191], v[108:111]
	v_mfma_f32_16x16x32_bf16 v[104:107], v[156:159], v[188:191], v[104:107]
	v_mfma_f32_16x16x32_bf16 v[92:95], v[148:151], v[206:209], v[92:95]
	v_mfma_f32_16x16x32_bf16 v[88:91], v[156:159], v[206:209], v[88:91]
	v_mfma_f32_16x16x32_bf16 v[76:79], v[148:151], v[218:221], v[76:79]
	v_mfma_f32_16x16x32_bf16 v[72:75], v[156:159], v[218:221], v[72:75]
	s_setprio 0
	s_setprio 1
	v_mfma_f32_16x16x32_bf16 v[116:119], v[160:163], v[176:179], v[116:119]
	v_mfma_f32_16x16x32_bf16 v[112:115], v[168:171], v[176:179], v[112:115]
	v_mfma_f32_16x16x32_bf16 v[100:103], v[160:163], v[184:187], v[100:103]
	v_mfma_f32_16x16x32_bf16 v[96:99], v[168:171], v[184:187], v[96:99]
	v_mfma_f32_16x16x32_bf16 v[84:87], v[160:163], v[202:205], v[84:87]
	v_mfma_f32_16x16x32_bf16 v[80:83], v[168:171], v[202:205], v[80:83]
	v_mfma_f32_16x16x32_bf16 v[68:71], v[160:163], v[214:217], v[68:71]
	v_mfma_f32_16x16x32_bf16 v[64:67], v[168:171], v[214:217], v[64:67]
	v_mfma_f32_16x16x32_bf16 v[116:119], v[164:167], v[180:183], v[116:119]
	v_mfma_f32_16x16x32_bf16 v[112:115], v[172:175], v[180:183], v[112:115]
	v_mfma_f32_16x16x32_bf16 v[100:103], v[164:167], v[188:191], v[100:103]
	v_mfma_f32_16x16x32_bf16 v[96:99], v[172:175], v[188:191], v[96:99]
	v_mfma_f32_16x16x32_bf16 v[84:87], v[164:167], v[206:209], v[84:87]
	v_mfma_f32_16x16x32_bf16 v[80:83], v[172:175], v[206:209], v[80:83]
	v_mfma_f32_16x16x32_bf16 v[68:71], v[164:167], v[218:221], v[68:71]
	v_mfma_f32_16x16x32_bf16 v[64:67], v[172:175], v[218:221], v[64:67]
	s_setprio 0
	s_barrier
	s_add_i32 s16, s4, s2
	s_mov_b32 m0, s16
	ds_read_b128 v[176:179], v197 offset:16384
	ds_read_b128 v[180:183], v197 offset:17408
	ds_read_b128 v[184:187], v197 offset:18432
	ds_read_b128 v[188:191], v197 offset:19456
	ds_read_b128 v[202:205], v197 offset:20480
	ds_read_b128 v[206:209], v197 offset:21504
	ds_read_b128 v[214:217], v197 offset:22528
	ds_read_b128 v[218:221], v197 offset:23552
	global_load_lds_dwordx4 v130, s[40:41]
	s_add_i32 m0, s16, 0x2000
	s_add_u32 s16, s40, 0x40000
	s_addc_u32 s17, s41, 0
	s_add_i32 s33, s5, s2
	global_load_lds_dwordx4 v134, s[40:41]
	s_mov_b32 m0, s33
	s_nop 0
	global_load_lds_dwordx4 v130, s[16:17]
	s_add_i32 m0, s33, 0x2000
	s_nop 0
	global_load_lds_dwordx4 v134, s[16:17]
	s_mov_b32 m0, s3
	s_nop 0
	global_load_lds_dwordx4 v128, s[44:45]
	s_mov_b32 m0, s27
	s_nop 0
	global_load_lds_dwordx4 v132, s[44:45]
	s_waitcnt vmcnt(8)
	s_waitcnt lgkmcnt(0)
	s_barrier
	s_setprio 1
	s_waitcnt lgkmcnt(0)
	v_mfma_f32_16x16x32_bf16 v[60:63], v[144:147], v[176:179], v[60:63]
	v_mfma_f32_16x16x32_bf16 v[56:59], v[152:155], v[176:179], v[56:59]
	v_mfma_f32_16x16x32_bf16 v[44:47], v[144:147], v[184:187], v[44:47]
	v_mfma_f32_16x16x32_bf16 v[40:43], v[152:155], v[184:187], v[40:43]
	v_mfma_f32_16x16x32_bf16 v[28:31], v[144:147], v[202:205], v[28:31]
	v_mfma_f32_16x16x32_bf16 v[24:27], v[152:155], v[202:205], v[24:27]
	v_mfma_f32_16x16x32_bf16 v[12:15], v[144:147], v[214:217], v[12:15]
	v_mfma_f32_16x16x32_bf16 v[8:11], v[152:155], v[214:217], v[8:11]
	v_mfma_f32_16x16x32_bf16 v[60:63], v[148:151], v[180:183], v[60:63]
	v_mfma_f32_16x16x32_bf16 v[56:59], v[156:159], v[180:183], v[56:59]
	v_mfma_f32_16x16x32_bf16 v[44:47], v[148:151], v[188:191], v[44:47]
	v_mfma_f32_16x16x32_bf16 v[40:43], v[156:159], v[188:191], v[40:43]
	v_mfma_f32_16x16x32_bf16 v[28:31], v[148:151], v[206:209], v[28:31]
	v_mfma_f32_16x16x32_bf16 v[24:27], v[156:159], v[206:209], v[24:27]
	v_mfma_f32_16x16x32_bf16 v[12:15], v[148:151], v[218:221], v[12:15]
	v_mfma_f32_16x16x32_bf16 v[8:11], v[156:159], v[218:221], v[8:11]
	s_setprio 0
	s_setprio 1
	v_mfma_f32_16x16x32_bf16 v[52:55], v[160:163], v[176:179], v[52:55]
	v_mfma_f32_16x16x32_bf16 v[48:51], v[168:171], v[176:179], v[48:51]
	v_mfma_f32_16x16x32_bf16 v[36:39], v[160:163], v[184:187], v[36:39]
	v_mfma_f32_16x16x32_bf16 v[32:35], v[168:171], v[184:187], v[32:35]
	v_mfma_f32_16x16x32_bf16 v[20:23], v[160:163], v[202:205], v[20:23]
	v_mfma_f32_16x16x32_bf16 v[16:19], v[168:171], v[202:205], v[16:19]
	v_mfma_f32_16x16x32_bf16 v[4:7], v[160:163], v[214:217], v[4:7]
	v_mfma_f32_16x16x32_bf16 v[0:3], v[168:171], v[214:217], v[0:3]
	v_mfma_f32_16x16x32_bf16 v[52:55], v[164:167], v[180:183], v[52:55]
	v_mfma_f32_16x16x32_bf16 v[48:51], v[172:175], v[180:183], v[48:51]
	v_mfma_f32_16x16x32_bf16 v[36:39], v[164:167], v[188:191], v[36:39]
	v_mfma_f32_16x16x32_bf16 v[32:35], v[172:175], v[188:191], v[32:35]
	v_mfma_f32_16x16x32_bf16 v[20:23], v[164:167], v[206:209], v[20:23]
	v_mfma_f32_16x16x32_bf16 v[16:19], v[172:175], v[206:209], v[16:19]
	v_mfma_f32_16x16x32_bf16 v[4:7], v[164:167], v[218:221], v[4:7]
	v_mfma_f32_16x16x32_bf16 v[0:3], v[172:175], v[218:221], v[0:3]
	s_setprio 0
	s_barrier
; #define PG8_STAGE(bufoff, gbase, voff) do { _Pragma("unroll") for (int _i = 0; _i < 2; ++_i) \
;     __builtin_amdgcn_global_load_lds((const unsigned*)((const char*)(gbase) + (voff)[_i]), (PG8_LAS unsigned*)(lds + (bufoff) + ldsw + _i * 8192), 16, 0, 0); } while (0)
; #define PG8_LDA(dst, b, h) do { _Pragma("unroll") for (int m = 0; m < 4; ++m) _Pragma("unroll") for (int k = 0; k < 2; ++k) dst[m][k] = *(const PG8_LAS bf16x8*)(lds + PG8_SA(b, h) + aoff + m * 2048 + k * 1024); } while (0)
; #define PG8_LDB(dst, b, h) do { _Pragma("unroll") for (int n = 0; n < 2; ++n) _Pragma("unroll") for (int k = 0; k < 2; ++k) dst[n][k] = *(const PG8_LAS bf16x8*)(lds + PG8_SB(b, h) + boff + n * 2048 + k * 1024); } while (0)
; #define PG8_MMA(ai, bj, At, Bt) do { __builtin_amdgcn_s_setprio(1); _Pragma("unroll") for (int m = 0; m < 4; ++m) _Pragma("unroll") for (int n = 0; n < 2; ++n) _Pragma("unroll") for (int k = 0; k < 2; ++k) \
;     acc[ai][bj][m][n] = __builtin_amdgcn_mfma_f32_16x16x32_bf16(Bt[n][k], At[m][k], acc[ai][bj][m][n], 0, 0, 0); __builtin_amdgcn_s_setprio(0); } while (0)
; #define PG8_WAIT_V(n) asm volatile("s_waitcnt vmcnt(" #n ")" ::: "memory")
; #define PG8_WAIT_L(n) asm volatile("s_waitcnt lgkmcnt(" #n ")" ::: "memory")
; #define PG8_BAR __builtin_amdgcn_s_barrier()
; #define PG8_SCHED __builtin_amdgcn_sched_barrier(0)
; template <class Epi, class Sched>
; DI void gemm_phase(PG8_LAS unsigned char* lds, const Gemm g, const Sched& S, const Epi& E) {
;     ...
;       PG8_WAIT_V(8); PG8_WAIT_L(0); PG8_BAR; PG8_MMA(1, 0, At, B0); PG8_MMA(1, 1, At, B1); PG8_BAR; PG8_SCHED;
;       PG8_LDB(B0, 1, 0); PG8_LDB(B1, 1, 1); PG8_SCHED; PG8_LDA(At, 1, 0); PG8_STAGE(PG8_SA(0, 1), a2 + hstepA, voffA);
;       PG8_WAIT_V(8); PG8_WAIT_L(0); PG8_BAR; PG8_MMA(0, 0, At, B0); PG8_MMA(0, 1, At, B1); PG8_BAR; PG8_SCHED;
;       PG8_LDA(At, 1, 1); PG8_STAGE(PG8_SB(1, 0), b3, voffB); PG8_STAGE(PG8_SB(1, 1), b3 + hstepB, voffB); PG8_STAGE(PG8_SA(1, 0), a3, voffA);
	ds_read_b128 v[144:147], v199
	ds_read_b128 v[148:151], v199 offset:1024
	ds_read_b128 v[152:155], v199 offset:2048
	ds_read_b128 v[156:159], v199 offset:3072
	ds_read_b128 v[160:163], v200
	ds_read_b128 v[164:167], v200 offset:1024
	ds_read_b128 v[168:171], v200 offset:2048
	ds_read_b128 v[172:175], v200 offset:3072
	s_add_u32 s16, s44, 0x40000
	s_addc_u32 s17, s45, 0
	s_mov_b32 m0, s53
	ds_read_b128 v[176:179], v197 offset:32768
	ds_read_b128 v[180:183], v197 offset:33792
	ds_read_b128 v[184:187], v197 offset:34816
	ds_read_b128 v[188:191], v197 offset:35840
	ds_read_b128 v[202:205], v197 offset:36864
	ds_read_b128 v[206:209], v197 offset:37888
	ds_read_b128 v[214:217], v197 offset:38912
	ds_read_b128 v[218:221], v197 offset:39936
	global_load_lds_dwordx4 v128, s[16:17]
	s_mov_b32 m0, s55
	s_nop 0
	global_load_lds_dwordx4 v132, s[16:17]
	s_waitcnt vmcnt(8)
	s_waitcnt lgkmcnt(0)
	s_barrier
	s_setprio 1
	s_waitcnt lgkmcnt(0)
	v_mfma_f32_16x16x32_bf16 v[124:127], v[144:147], v[176:179], v[124:127]
	v_mfma_f32_16x16x32_bf16 v[120:123], v[152:155], v[176:179], v[120:123]
	v_mfma_f32_16x16x32_bf16 v[108:111], v[144:147], v[184:187], v[108:111]
	v_mfma_f32_16x16x32_bf16 v[104:107], v[152:155], v[184:187], v[104:107]
	v_mfma_f32_16x16x32_bf16 v[92:95], v[144:147], v[202:205], v[92:95]
	v_mfma_f32_16x16x32_bf16 v[88:91], v[152:155], v[202:205], v[88:91]
	v_mfma_f32_16x16x32_bf16 v[76:79], v[144:147], v[214:217], v[76:79]
	v_mfma_f32_16x16x32_bf16 v[72:75], v[152:155], v[214:217], v[72:75]
	v_mfma_f32_16x16x32_bf16 v[124:127], v[148:151], v[180:183], v[124:127]
	v_mfma_f32_16x16x32_bf16 v[120:123], v[156:159], v[180:183], v[120:123]
	v_mfma_f32_16x16x32_bf16 v[108:111], v[148:151], v[188:191], v[108:111]
	v_mfma_f32_16x16x32_bf16 v[104:107], v[156:159], v[188:191], v[104:107]
	v_mfma_f32_16x16x32_bf16 v[92:95], v[148:151], v[206:209], v[92:95]
	v_mfma_f32_16x16x32_bf16 v[88:91], v[156:159], v[206:209], v[88:91]
	v_mfma_f32_16x16x32_bf16 v[76:79], v[148:151], v[218:221], v[76:79]
	v_mfma_f32_16x16x32_bf16 v[72:75], v[156:159], v[218:221], v[72:75]
	s_setprio 0
	s_setprio 1
	v_mfma_f32_16x16x32_bf16 v[116:119], v[160:163], v[176:179], v[116:119]
	v_mfma_f32_16x16x32_bf16 v[112:115], v[168:171], v[176:179], v[112:115]
	v_mfma_f32_16x16x32_bf16 v[100:103], v[160:163], v[184:187], v[100:103]
	v_mfma_f32_16x16x32_bf16 v[96:99], v[168:171], v[184:187], v[96:99]
	v_mfma_f32_16x16x32_bf16 v[84:87], v[160:163], v[202:205], v[84:87]
	v_mfma_f32_16x16x32_bf16 v[80:83], v[168:171], v[202:205], v[80:83]
	v_mfma_f32_16x16x32_bf16 v[68:71], v[160:163], v[214:217], v[68:71]
	v_mfma_f32_16x16x32_bf16 v[64:67], v[168:171], v[214:217], v[64:67]
	v_mfma_f32_16x16x32_bf16 v[116:119], v[164:167], v[180:183], v[116:119]
	v_mfma_f32_16x16x32_bf16 v[112:115], v[172:175], v[180:183], v[112:115]
	v_mfma_f32_16x16x32_bf16 v[100:103], v[164:167], v[188:191], v[100:103]
	v_mfma_f32_16x16x32_bf16 v[96:99], v[172:175], v[188:191], v[96:99]
	v_mfma_f32_16x16x32_bf16 v[84:87], v[164:167], v[206:209], v[84:87]
	v_mfma_f32_16x16x32_bf16 v[80:83], v[172:175], v[206:209], v[80:83]
	v_mfma_f32_16x16x32_bf16 v[68:71], v[164:167], v[218:221], v[68:71]
	v_mfma_f32_16x16x32_bf16 v[64:67], v[172:175], v[218:221], v[64:67]
	s_setprio 0
	s_barrier
	s_add_i32 s16, s69, s2
	s_mov_b32 m0, s16
	ds_read_b128 v[176:179], v197 offset:49152
	ds_read_b128 v[180:183], v197 offset:50176
	ds_read_b128 v[184:187], v197 offset:51200
	ds_read_b128 v[188:191], v197 offset:52224
	ds_read_b128 v[202:205], v197 offset:53248
	ds_read_b128 v[206:209], v197 offset:54272
	ds_read_b128 v[214:217], v197 offset:55296
	ds_read_b128 v[218:221], v197 offset:56320
	s_add_u32 s100, s40, 0x80
	s_addc_u32 s101, s41, 0
	global_load_lds_dwordx4 v130, s[100:101]
	s_add_i32 m0, s16, 0x2000
	s_add_u32 s16, s40, 0x40080
	s_addc_u32 s17, s41, 0
	s_add_i32 s33, s70, s2
	global_load_lds_dwordx4 v134, s[100:101]
	s_mov_b32 m0, s33
	s_nop 0
	global_load_lds_dwordx4 v130, s[16:17]
	s_add_i32 m0, s33, 0x2000
	s_nop 0
	global_load_lds_dwordx4 v134, s[16:17]
	s_mov_b32 m0, s65
	s_nop 0
	s_add_u32 s100, s44, 0x80
	s_addc_u32 s101, s45, 0
	global_load_lds_dwordx4 v128, s[100:101]
	s_mov_b32 m0, s66
	s_nop 0
	global_load_lds_dwordx4 v132, s[100:101]
	s_waitcnt vmcnt(8)
	s_waitcnt lgkmcnt(0)
	s_barrier
; #define PG8_MMA(ai, bj, At, Bt) do { __builtin_amdgcn_s_setprio(1); _Pragma("unroll") for (int m = 0; m < 4; ++m) _Pragma("unroll") for (int n = 0; n < 2; ++n) _Pragma("unroll") for (int k = 0; k < 2; ++k) \
;     acc[ai][bj][m][n] = __builtin_amdgcn_mfma_f32_16x16x32_bf16(Bt[n][k], At[m][k], acc[ai][bj][m][n], 0, 0, 0); __builtin_amdgcn_s_setprio(0); } while (0)
; #define PG8_WAIT_V(n) asm volatile("s_waitcnt vmcnt(" #n ")" ::: "memory")
; #define PG8_WAIT_L(n) asm volatile("s_waitcnt lgkmcnt(" #n ")" ::: "memory")
; #define PG8_BAR __builtin_amdgcn_s_barrier()
; #define PG8_SCHED __builtin_amdgcn_sched_barrier(0)
; DI void rows_rstd(float (&rs)[2][4], const float* ps, const Unit& u, int wr, int fr, int fq, int p_lo, int p_hi, float inv_dim) {
;   f32x4 pv[2][4];
; #pragma unroll
;   for (int ai = 0; ai < 2; ++ai)
; #pragma unroll
;     for (int m = 0; m < 4; ++m) pv[ai][m] = *(const f32x4*)(ps + (size_t)(u.pm * BM + ai * HALF + wr * 64 + m * 16 + fr) * 16 + 4 * fq);
; template <class Epi, class Sched>
; DI void gemm_phase(PG8_LAS unsigned char* lds, const Gemm g, const Sched& S, const Epi& E) {
;     ...
;       PG8_WAIT_V(8); PG8_WAIT_L(0); PG8_BAR; PG8_MMA(1, 0, At, B0); PG8_MMA(1, 1, At, B1); PG8_BAR; PG8_SCHED;
;     }
;     if (wr == 0) PG8_BAR;
	s_setprio 1
	s_waitcnt lgkmcnt(0)
	v_mfma_f32_16x16x32_bf16 v[60:63], v[144:147], v[176:179], v[60:63]
	v_mfma_f32_16x16x32_bf16 v[56:59], v[152:155], v[176:179], v[56:59]
	v_mfma_f32_16x16x32_bf16 v[44:47], v[144:147], v[184:187], v[44:47]
	v_mfma_f32_16x16x32_bf16 v[40:43], v[152:155], v[184:187], v[40:43]
	v_mfma_f32_16x16x32_bf16 v[28:31], v[144:147], v[202:205], v[28:31]
	v_mfma_f32_16x16x32_bf16 v[24:27], v[152:155], v[202:205], v[24:27]
	v_mfma_f32_16x16x32_bf16 v[12:15], v[144:147], v[214:217], v[12:15]
	v_mfma_f32_16x16x32_bf16 v[8:11], v[152:155], v[214:217], v[8:11]
	v_mfma_f32_16x16x32_bf16 v[60:63], v[148:151], v[180:183], v[60:63]
	v_mfma_f32_16x16x32_bf16 v[56:59], v[156:159], v[180:183], v[56:59]
	v_mfma_f32_16x16x32_bf16 v[44:47], v[148:151], v[188:191], v[44:47]
	v_mfma_f32_16x16x32_bf16 v[40:43], v[156:159], v[188:191], v[40:43]
	v_mfma_f32_16x16x32_bf16 v[28:31], v[148:151], v[206:209], v[28:31]
	v_mfma_f32_16x16x32_bf16 v[24:27], v[156:159], v[206:209], v[24:27]
	v_mfma_f32_16x16x32_bf16 v[12:15], v[148:151], v[218:221], v[12:15]
	v_mfma_f32_16x16x32_bf16 v[8:11], v[156:159], v[218:221], v[8:11]
	s_setprio 0
	s_setprio 1
	v_mfma_f32_16x16x32_bf16 v[52:55], v[160:163], v[176:179], v[52:55]
	v_mfma_f32_16x16x32_bf16 v[48:51], v[168:171], v[176:179], v[48:51]
	v_mfma_f32_16x16x32_bf16 v[36:39], v[160:163], v[184:187], v[36:39]
	v_mfma_f32_16x16x32_bf16 v[32:35], v[168:171], v[184:187], v[32:35]
	v_mfma_f32_16x16x32_bf16 v[20:23], v[160:163], v[202:205], v[20:23]
	v_mfma_f32_16x16x32_bf16 v[16:19], v[168:171], v[202:205], v[16:19]
	v_mfma_f32_16x16x32_bf16 v[4:7], v[160:163], v[214:217], v[4:7]
	v_mfma_f32_16x16x32_bf16 v[0:3], v[168:171], v[214:217], v[0:3]
	v_mfma_f32_16x16x32_bf16 v[52:55], v[164:167], v[180:183], v[52:55]
	v_mfma_f32_16x16x32_bf16 v[48:51], v[172:175], v[180:183], v[48:51]
	v_mfma_f32_16x16x32_bf16 v[36:39], v[164:167], v[188:191], v[36:39]
	v_mfma_f32_16x16x32_bf16 v[32:35], v[172:175], v[188:191], v[32:35]
	v_mfma_f32_16x16x32_bf16 v[20:23], v[164:167], v[206:209], v[20:23]
	v_mfma_f32_16x16x32_bf16 v[16:19], v[172:175], v[206:209], v[16:19]
	v_mfma_f32_16x16x32_bf16 v[4:7], v[164:167], v[218:221], v[4:7]
	v_mfma_f32_16x16x32_bf16 v[0:3], v[172:175], v[218:221], v[0:3]
	s_setprio 0
	s_barrier
	s_add_i32 s73, s73, 2
	s_add_u32 s10, s10, 0x100
	s_addc_u32 s11, s11, 0
	s_add_u32 s31, s31, 0x100
	s_addc_u32 s72, s72, 0
	s_cmp_gt_u32 s73, 13
	s_cbranch_scc0 .LBB0_807
	v_lshl_add_u32 v184, s8, 8, v143
	v_or_b32_e32 v180, 16, v184
	v_ashrrev_i32_e32 v181, 31, v180
	v_or_b32_e32 v172, 32, v184
	v_lshlrev_b64 v[178:179], 6, v[180:181]
	v_ashrrev_i32_e32 v173, 31, v172
	v_ashrrev_i32_e32 v185, 31, v184
	v_lshl_add_u64 v[144:145], v[136:137], 0, v[178:179]
	v_lshlrev_b64 v[170:171], 6, v[172:173]
	v_lshlrev_b64 v[182:183], 6, v[184:185]
	v_lshl_add_u64 v[146:147], v[136:137], 0, v[170:171]
	global_load_dwordx4 v[162:165], v[144:145], off
	global_load_dwordx4 v[174:177], v[146:147], off
	v_lshl_add_u64 v[144:145], v[136:137], 0, v[182:183]
	global_load_dwordx4 v[186:189], v[144:145], off
	v_or_b32_e32 v168, 48, v184
	v_ashrrev_i32_e32 v169, 31, v168
	v_add_u32_e32 v160, 0x80, v184
	v_add_u32_e32 v156, 0x90, v184
	v_lshlrev_b64 v[166:167], 6, v[168:169]
	v_ashrrev_i32_e32 v161, 31, v160
	v_ashrrev_i32_e32 v157, 31, v156
	v_lshl_add_u64 v[144:145], v[136:137], 0, v[166:167]
	v_lshlrev_b64 v[158:159], 6, v[160:161]
	v_lshlrev_b64 v[154:155], 6, v[156:157]
	v_lshl_add_u64 v[146:147], v[136:137], 0, v[158:159]
	global_load_dwordx4 v[190:193], v[144:145], off
	global_load_dwordx4 v[202:205], v[146:147], off
	v_lshl_add_u64 v[144:145], v[136:137], 0, v[154:155]
	global_load_dwordx4 v[206:209], v[144:145], off
	v_add_u32_e32 v150, 0xa0, v184
	v_ashrrev_i32_e32 v151, 31, v150
	v_lshlrev_b64 v[148:149], 6, v[150:151]
	v_add_u32_e32 v146, 0xb0, v184
	v_lshl_add_u64 v[144:145], v[136:137], 0, v[148:149]
	v_ashrrev_i32_e32 v147, 31, v146
	global_load_dwordx4 v[214:217], v[144:145], off
	v_lshlrev_b64 v[144:145], 6, v[146:147]
	v_lshl_add_u64 v[152:153], v[136:137], 0, v[144:145]
	global_load_dwordx4 v[218:221], v[152:153], off
	s_and_b64 vcc, exec, s[20:21]
	s_cbranch_vccz .LBB0_810
	s_barrier

; #define PG8_STAGE(bufoff, gbase, voff) do { _Pragma("unroll") for (int _i = 0; _i < 2; ++_i) \
;     __builtin_amdgcn_global_load_lds((const unsigned*)((const char*)(gbase) + (voff)[_i]), (PG8_LAS unsigned*)(lds + (bufoff) + ldsw + _i * 8192), 16, 0, 0); } while (0)
; #define PG8_LDA(dst, b, h) do { _Pragma("unroll") for (int m = 0; m < 4; ++m) _Pragma("unroll") for (int k = 0; k < 2; ++k) dst[m][k] = *(const PG8_LAS bf16x8*)(lds + PG8_SA(b, h) + aoff + m * 2048 + k * 1024); } while (0)
; #define PG8_LDB(dst, b, h) do { _Pragma("unroll") for (int n = 0; n < 2; ++n) _Pragma("unroll") for (int k = 0; k < 2; ++k) dst[n][k] = *(const PG8_LAS bf16x8*)(lds + PG8_SB(b, h) + boff + n * 2048 + k * 1024); } while (0)
; #define PG8_MMA(ai, bj, At, Bt) do { __builtin_amdgcn_s_setprio(1); _Pragma("unroll") for (int m = 0; m < 4; ++m) _Pragma("unroll") for (int n = 0; n < 2; ++n) _Pragma("unroll") for (int k = 0; k < 2; ++k) \
;     acc[ai][bj][m][n] = __builtin_amdgcn_mfma_f32_16x16x32_bf16(Bt[n][k], At[m][k], acc[ai][bj][m][n], 0, 0, 0); __builtin_amdgcn_s_setprio(0); } while (0)
; #define PG8_WAIT_V(n) asm volatile("s_waitcnt vmcnt(" #n ")" ::: "memory")
; #define PG8_WAIT_L(n) asm volatile("s_waitcnt lgkmcnt(" #n ")" ::: "memory")
; #define PG8_BAR __builtin_amdgcn_s_barrier()
; #define PG8_SCHED __builtin_amdgcn_sched_barrier(0)
; template <class Epi, class Sched>
; DI void gemm_phase(PG8_LAS unsigned char* lds, const Gemm g, const Sched& S, const Epi& E) {
;     ...
;       PG8_LDB(B0, 0, 0); PG8_LDB(B1, 0, 1); PG8_SCHED; PG8_LDA(At, 0, 0); PG8_STAGE(PG8_SA(1, 1), a1 + hstepA, voffA);
;       PG8_WAIT_V(8); PG8_WAIT_L(0); PG8_BAR; PG8_MMA(0, 0, At, B0); PG8_MMA(0, 1, At, B1); PG8_BAR; PG8_SCHED;
;       PG8_LDA(At, 0, 1); PG8_STAGE(PG8_SB(0, 0), b2, voffB); PG8_STAGE(PG8_SB(0, 1), b2 + hstepB, voffB); PG8_STAGE(PG8_SA(0, 0), a2, voffA);
;       PG8_WAIT_V(8); PG8_WAIT_L(0); PG8_BAR; PG8_MMA(1, 0, At, B0); PG8_MMA(1, 1, At, B1); PG8_BAR; PG8_SCHED;
.LBB0_930:
	ds_read_b128 v[128:131], v191
	ds_read_b128 v[132:135], v191 offset:1024
	ds_read_b128 v[136:139], v191 offset:2048
	ds_read_b128 v[140:143], v191 offset:3072
	ds_read_b128 v[144:147], v192
	ds_read_b128 v[148:151], v192 offset:1024
	ds_read_b128 v[152:155], v192 offset:2048
	ds_read_b128 v[172:175], v192 offset:3072
	s_add_u32 s12, s0, 0x100
	s_addc_u32 s13, s1, 0
	s_cmp_eq_u32 s74, 8
	s_cselect_b32 s39, s35, s13
	s_cselect_b32 s38, s34, s12
	s_cselect_b32 s15, s37, s73
	s_cselect_b32 s14, s36, s72
	s_mov_b32 m0, s65
	ds_read_b128 v[176:179], v193
	ds_read_b128 v[180:183], v193 offset:1024
	ds_read_b128 v[184:187], v193 offset:2048
	ds_read_b128 v[198:201], v193 offset:3072
	ds_read_b128 v[202:205], v193 offset:4096
	ds_read_b128 v[206:209], v193 offset:5120
	ds_read_b128 v[214:217], v193 offset:6144
	ds_read_b128 v[218:221], v193 offset:7168
	global_load_lds_dwordx4 v166, s[0:1]
	s_add_i32 m0, s3, 0xe000
	s_nop 0
	global_load_lds_dwordx4 v168, s[0:1]
	s_waitcnt vmcnt(8)
	s_waitcnt lgkmcnt(0)
	s_barrier
	s_setprio 1
	s_waitcnt lgkmcnt(0)
	v_mfma_f32_16x16x32_bf16 v[120:123], v[128:131], v[176:179], v[120:123]
	v_mfma_f32_16x16x32_bf16 v[124:127], v[136:139], v[176:179], v[124:127]
	v_mfma_f32_16x16x32_bf16 v[104:107], v[128:131], v[184:187], v[104:107]
	v_mfma_f32_16x16x32_bf16 v[108:111], v[136:139], v[184:187], v[108:111]
	v_mfma_f32_16x16x32_bf16 v[88:91], v[128:131], v[202:205], v[88:91]
	v_mfma_f32_16x16x32_bf16 v[92:95], v[136:139], v[202:205], v[92:95]
	v_mfma_f32_16x16x32_bf16 v[72:75], v[128:131], v[214:217], v[72:75]
	v_mfma_f32_16x16x32_bf16 v[76:79], v[136:139], v[214:217], v[76:79]
	v_mfma_f32_16x16x32_bf16 v[120:123], v[132:135], v[180:183], v[120:123]
	v_mfma_f32_16x16x32_bf16 v[124:127], v[140:143], v[180:183], v[124:127]
	v_mfma_f32_16x16x32_bf16 v[104:107], v[132:135], v[198:201], v[104:107]
	v_mfma_f32_16x16x32_bf16 v[108:111], v[140:143], v[198:201], v[108:111]
	v_mfma_f32_16x16x32_bf16 v[88:91], v[132:135], v[206:209], v[88:91]
	v_mfma_f32_16x16x32_bf16 v[92:95], v[140:143], v[206:209], v[92:95]
	v_mfma_f32_16x16x32_bf16 v[72:75], v[132:135], v[218:221], v[72:75]
	v_mfma_f32_16x16x32_bf16 v[76:79], v[140:143], v[218:221], v[76:79]
	s_setprio 0
	s_setprio 1
	v_mfma_f32_16x16x32_bf16 v[112:115], v[144:147], v[176:179], v[112:115]
	v_mfma_f32_16x16x32_bf16 v[116:119], v[152:155], v[176:179], v[116:119]
	v_mfma_f32_16x16x32_bf16 v[96:99], v[144:147], v[184:187], v[96:99]
	v_mfma_f32_16x16x32_bf16 v[100:103], v[152:155], v[184:187], v[100:103]
	v_mfma_f32_16x16x32_bf16 v[80:83], v[144:147], v[202:205], v[80:83]
	v_mfma_f32_16x16x32_bf16 v[84:87], v[152:155], v[202:205], v[84:87]
	v_mfma_f32_16x16x32_bf16 v[64:67], v[144:147], v[214:217], v[64:67]
	v_mfma_f32_16x16x32_bf16 v[68:71], v[152:155], v[214:217], v[68:71]
	v_mfma_f32_16x16x32_bf16 v[112:115], v[148:151], v[180:183], v[112:115]
	v_mfma_f32_16x16x32_bf16 v[116:119], v[172:175], v[180:183], v[116:119]
	v_mfma_f32_16x16x32_bf16 v[96:99], v[148:151], v[198:201], v[96:99]
	v_mfma_f32_16x16x32_bf16 v[100:103], v[172:175], v[198:201], v[100:103]
	v_mfma_f32_16x16x32_bf16 v[80:83], v[148:151], v[206:209], v[80:83]
	v_mfma_f32_16x16x32_bf16 v[84:87], v[172:175], v[206:209], v[84:87]
	v_mfma_f32_16x16x32_bf16 v[64:67], v[148:151], v[218:221], v[64:67]
	v_mfma_f32_16x16x32_bf16 v[68:71], v[172:175], v[218:221], v[68:71]
	s_setprio 0
	s_barrier
	s_add_i32 s0, s44, s2
	s_mov_b32 m0, s0
	ds_read_b128 v[176:179], v193 offset:16384
	ds_read_b128 v[180:183], v193 offset:17408
	ds_read_b128 v[184:187], v193 offset:18432
	ds_read_b128 v[198:201], v193 offset:19456
	ds_read_b128 v[202:205], v193 offset:20480
	ds_read_b128 v[206:209], v193 offset:21504
	ds_read_b128 v[214:217], v193 offset:22528
	ds_read_b128 v[218:221], v193 offset:23552
	global_load_lds_dwordx4 v158, s[14:15]
	s_add_i32 m0, s0, 0x2000
	s_add_u32 s0, s14, 0x30000
	s_addc_u32 s1, s15, 0
	s_add_i32 s16, s45, s2
	global_load_lds_dwordx4 v162, s[14:15]
	s_mov_b32 m0, s16
	s_nop 0
	global_load_lds_dwordx4 v158, s[0:1]
	s_add_i32 m0, s16, 0x2000
	s_nop 0
	global_load_lds_dwordx4 v162, s[0:1]
	s_mov_b32 m0, s3
	s_nop 0
	global_load_lds_dwordx4 v156, s[38:39]
	s_mov_b32 m0, s4
	s_nop 0
	global_load_lds_dwordx4 v160, s[38:39]
	s_waitcnt vmcnt(8)
	s_waitcnt lgkmcnt(0)
	s_barrier
	s_setprio 1
	s_waitcnt lgkmcnt(0)
	v_mfma_f32_16x16x32_bf16 v[56:59], v[128:131], v[176:179], v[56:59]
	v_mfma_f32_16x16x32_bf16 v[60:63], v[136:139], v[176:179], v[60:63]
	v_mfma_f32_16x16x32_bf16 v[40:43], v[128:131], v[184:187], v[40:43]
	v_mfma_f32_16x16x32_bf16 v[44:47], v[136:139], v[184:187], v[44:47]
	v_mfma_f32_16x16x32_bf16 v[24:27], v[128:131], v[202:205], v[24:27]
	v_mfma_f32_16x16x32_bf16 v[28:31], v[136:139], v[202:205], v[28:31]
	v_mfma_f32_16x16x32_bf16 v[8:11], v[128:131], v[214:217], v[8:11]
	v_mfma_f32_16x16x32_bf16 v[12:15], v[136:139], v[214:217], v[12:15]
	v_mfma_f32_16x16x32_bf16 v[56:59], v[132:135], v[180:183], v[56:59]
	v_mfma_f32_16x16x32_bf16 v[60:63], v[140:143], v[180:183], v[60:63]
	v_mfma_f32_16x16x32_bf16 v[40:43], v[132:135], v[198:201], v[40:43]
	v_mfma_f32_16x16x32_bf16 v[44:47], v[140:143], v[198:201], v[44:47]
	v_mfma_f32_16x16x32_bf16 v[24:27], v[132:135], v[206:209], v[24:27]
	v_mfma_f32_16x16x32_bf16 v[28:31], v[140:143], v[206:209], v[28:31]
	v_mfma_f32_16x16x32_bf16 v[8:11], v[132:135], v[218:221], v[8:11]
	v_mfma_f32_16x16x32_bf16 v[12:15], v[140:143], v[218:221], v[12:15]
	s_setprio 0
	s_setprio 1
	v_mfma_f32_16x16x32_bf16 v[48:51], v[144:147], v[176:179], v[48:51]
	v_mfma_f32_16x16x32_bf16 v[52:55], v[152:155], v[176:179], v[52:55]
	v_mfma_f32_16x16x32_bf16 v[32:35], v[144:147], v[184:187], v[32:35]
	v_mfma_f32_16x16x32_bf16 v[36:39], v[152:155], v[184:187], v[36:39]
	v_mfma_f32_16x16x32_bf16 v[16:19], v[144:147], v[202:205], v[16:19]
	v_mfma_f32_16x16x32_bf16 v[20:23], v[152:155], v[202:205], v[20:23]
	v_mfma_f32_16x16x32_bf16 v[4:7], v[144:147], v[214:217], v[4:7]
	v_mfma_f32_16x16x32_bf16 v[0:3], v[152:155], v[214:217], v[0:3]
	v_mfma_f32_16x16x32_bf16 v[48:51], v[148:151], v[180:183], v[48:51]
	v_mfma_f32_16x16x32_bf16 v[52:55], v[172:175], v[180:183], v[52:55]
	v_mfma_f32_16x16x32_bf16 v[32:35], v[148:151], v[198:201], v[32:35]
	v_mfma_f32_16x16x32_bf16 v[36:39], v[172:175], v[198:201], v[36:39]
	v_mfma_f32_16x16x32_bf16 v[16:19], v[148:151], v[206:209], v[16:19]
	v_mfma_f32_16x16x32_bf16 v[20:23], v[172:175], v[206:209], v[20:23]
	v_mfma_f32_16x16x32_bf16 v[4:7], v[148:151], v[218:221], v[4:7]
	v_mfma_f32_16x16x32_bf16 v[0:3], v[172:175], v[218:221], v[0:3]
	s_setprio 0
	s_barrier
; #define PG8_STAGE(bufoff, gbase, voff) do { _Pragma("unroll") for (int _i = 0; _i < 2; ++_i) \
;     __builtin_amdgcn_global_load_lds((const unsigned*)((const char*)(gbase) + (voff)[_i]), (PG8_LAS unsigned*)(lds + (bufoff) + ldsw + _i * 8192), 16, 0, 0); } while (0)
; #define PG8_LDA(dst, b, h) do { _Pragma("unroll") for (int m = 0; m < 4; ++m) _Pragma("unroll") for (int k = 0; k < 2; ++k) dst[m][k] = *(const PG8_LAS bf16x8*)(lds + PG8_SA(b, h) + aoff + m * 2048 + k * 1024); } while (0)
; #define PG8_LDB(dst, b, h) do { _Pragma("unroll") for (int n = 0; n < 2; ++n) _Pragma("unroll") for (int k = 0; k < 2; ++k) dst[n][k] = *(const PG8_LAS bf16x8*)(lds + PG8_SB(b, h) + boff + n * 2048 + k * 1024); } while (0)
; #define PG8_MMA(ai, bj, At, Bt) do { __builtin_amdgcn_s_setprio(1); _Pragma("unroll") for (int m = 0; m < 4; ++m) _Pragma("unroll") for (int n = 0; n < 2; ++n) _Pragma("unroll") for (int k = 0; k < 2; ++k) \
;     acc[ai][bj][m][n] = __builtin_amdgcn_mfma_f32_16x16x32_bf16(Bt[n][k], At[m][k], acc[ai][bj][m][n], 0, 0, 0); __builtin_amdgcn_s_setprio(0); } while (0)
; #define PG8_WAIT_V(n) asm volatile("s_waitcnt vmcnt(" #n ")" ::: "memory")
; #define PG8_WAIT_L(n) asm volatile("s_waitcnt lgkmcnt(" #n ")" ::: "memory")
; #define PG8_BAR __builtin_amdgcn_s_barrier()
; #define PG8_SCHED __builtin_amdgcn_sched_barrier(0)
; template <class Epi, class Sched>
; DI void gemm_phase(PG8_LAS unsigned char* lds, const Gemm g, const Sched& S, const Epi& E) {
;     ...
;       PG8_LDB(B0, 1, 0); PG8_LDB(B1, 1, 1); PG8_SCHED; PG8_LDA(At, 1, 0); PG8_STAGE(PG8_SA(0, 1), a2 + hstepA, voffA);
;       PG8_WAIT_V(8); PG8_WAIT_L(0); PG8_BAR; PG8_MMA(0, 0, At, B0); PG8_MMA(0, 1, At, B1); PG8_BAR; PG8_SCHED;
;       PG8_LDA(At, 1, 1); PG8_STAGE(PG8_SB(1, 0), b3, voffB); PG8_STAGE(PG8_SB(1, 1), b3 + hstepB, voffB); PG8_STAGE(PG8_SA(1, 0), a3, voffA);
;       PG8_WAIT_V(8); PG8_WAIT_L(0); PG8_BAR; PG8_MMA(1, 0, At, B0); PG8_MMA(1, 1, At, B1); PG8_BAR; PG8_SCHED;
;     }
;     if (wr == 0) PG8_BAR;
	ds_read_b128 v[128:131], v195
	ds_read_b128 v[132:135], v195 offset:1024
	ds_read_b128 v[136:139], v195 offset:2048
	ds_read_b128 v[140:143], v195 offset:3072
	ds_read_b128 v[144:147], v196
	ds_read_b128 v[148:151], v196 offset:1024
	ds_read_b128 v[152:155], v196 offset:2048
	ds_read_b128 v[172:175], v196 offset:3072
	s_add_u32 s0, s38, 0x58000
	s_addc_u32 s1, s39, 0
	s_mov_b32 m0, s5
	ds_read_b128 v[176:179], v193 offset:32768
	ds_read_b128 v[180:183], v193 offset:33792
	ds_read_b128 v[184:187], v193 offset:34816
	ds_read_b128 v[198:201], v193 offset:35840
	ds_read_b128 v[202:205], v193 offset:36864
	ds_read_b128 v[206:209], v193 offset:37888
	ds_read_b128 v[214:217], v193 offset:38912
	ds_read_b128 v[218:221], v193 offset:39936
	global_load_lds_dwordx4 v156, s[0:1]
	s_mov_b32 m0, s18
	s_nop 0
	global_load_lds_dwordx4 v160, s[0:1]
	s_waitcnt vmcnt(8)
	s_waitcnt lgkmcnt(0)
	s_barrier
	s_setprio 1
	s_waitcnt lgkmcnt(0)
	v_mfma_f32_16x16x32_bf16 v[120:123], v[128:131], v[176:179], v[120:123]
	v_mfma_f32_16x16x32_bf16 v[124:127], v[136:139], v[176:179], v[124:127]
	v_mfma_f32_16x16x32_bf16 v[104:107], v[128:131], v[184:187], v[104:107]
	v_mfma_f32_16x16x32_bf16 v[108:111], v[136:139], v[184:187], v[108:111]
	v_mfma_f32_16x16x32_bf16 v[88:91], v[128:131], v[202:205], v[88:91]
	v_mfma_f32_16x16x32_bf16 v[92:95], v[136:139], v[202:205], v[92:95]
	v_mfma_f32_16x16x32_bf16 v[72:75], v[128:131], v[214:217], v[72:75]
	v_mfma_f32_16x16x32_bf16 v[76:79], v[136:139], v[214:217], v[76:79]
	v_mfma_f32_16x16x32_bf16 v[120:123], v[132:135], v[180:183], v[120:123]
	v_mfma_f32_16x16x32_bf16 v[124:127], v[140:143], v[180:183], v[124:127]
	v_mfma_f32_16x16x32_bf16 v[104:107], v[132:135], v[198:201], v[104:107]
	v_mfma_f32_16x16x32_bf16 v[108:111], v[140:143], v[198:201], v[108:111]
	v_mfma_f32_16x16x32_bf16 v[88:91], v[132:135], v[206:209], v[88:91]
	v_mfma_f32_16x16x32_bf16 v[92:95], v[140:143], v[206:209], v[92:95]
	v_mfma_f32_16x16x32_bf16 v[72:75], v[132:135], v[218:221], v[72:75]
	v_mfma_f32_16x16x32_bf16 v[76:79], v[140:143], v[218:221], v[76:79]
	s_setprio 0
	s_setprio 1
	v_mfma_f32_16x16x32_bf16 v[112:115], v[144:147], v[176:179], v[112:115]
	v_mfma_f32_16x16x32_bf16 v[116:119], v[152:155], v[176:179], v[116:119]
	v_mfma_f32_16x16x32_bf16 v[96:99], v[144:147], v[184:187], v[96:99]
	v_mfma_f32_16x16x32_bf16 v[100:103], v[152:155], v[184:187], v[100:103]
	v_mfma_f32_16x16x32_bf16 v[80:83], v[144:147], v[202:205], v[80:83]
	v_mfma_f32_16x16x32_bf16 v[84:87], v[152:155], v[202:205], v[84:87]
	v_mfma_f32_16x16x32_bf16 v[64:67], v[144:147], v[214:217], v[64:67]
	v_mfma_f32_16x16x32_bf16 v[68:71], v[152:155], v[214:217], v[68:71]
	v_mfma_f32_16x16x32_bf16 v[112:115], v[148:151], v[180:183], v[112:115]
	v_mfma_f32_16x16x32_bf16 v[116:119], v[172:175], v[180:183], v[116:119]
	v_mfma_f32_16x16x32_bf16 v[96:99], v[148:151], v[198:201], v[96:99]
	v_mfma_f32_16x16x32_bf16 v[100:103], v[172:175], v[198:201], v[100:103]
	v_mfma_f32_16x16x32_bf16 v[80:83], v[148:151], v[206:209], v[80:83]
	v_mfma_f32_16x16x32_bf16 v[84:87], v[172:175], v[206:209], v[84:87]
	v_mfma_f32_16x16x32_bf16 v[64:67], v[148:151], v[218:221], v[64:67]
	v_mfma_f32_16x16x32_bf16 v[68:71], v[172:175], v[218:221], v[68:71]
	s_setprio 0
	s_barrier
	s_add_i32 s0, s66, s2
	s_mov_b32 m0, s0
	ds_read_b128 v[176:179], v193 offset:49152
	ds_read_b128 v[180:183], v193 offset:50176
	ds_read_b128 v[184:187], v193 offset:51200
	ds_read_b128 v[198:201], v193 offset:52224
	ds_read_b128 v[202:205], v193 offset:53248
	ds_read_b128 v[206:209], v193 offset:54272
	ds_read_b128 v[214:217], v193 offset:55296
	ds_read_b128 v[218:221], v193 offset:56320
	s_add_u32 s100, s14, 0x80
	s_addc_u32 s101, s15, 0
	global_load_lds_dwordx4 v158, s[100:101]
	s_add_i32 m0, s0, 0x2000
	s_add_u32 s0, s14, 0x30080
	s_addc_u32 s1, s15, 0
	s_add_i32 s14, s67, s2
	global_load_lds_dwordx4 v162, s[100:101]
	s_mov_b32 m0, s14
	s_nop 0
	global_load_lds_dwordx4 v158, s[0:1]
	s_add_i32 m0, s14, 0x2000
	s_nop 0
	global_load_lds_dwordx4 v162, s[0:1]
	s_mov_b32 m0, s19
	s_nop 0
	s_add_u32 s100, s38, 0x80
	s_addc_u32 s101, s39, 0
	global_load_lds_dwordx4 v156, s[100:101]
	s_mov_b32 m0, s31
	s_nop 0
	global_load_lds_dwordx4 v160, s[100:101]
	s_waitcnt vmcnt(8)
	s_waitcnt lgkmcnt(0)
	s_barrier
	s_setprio 1
	s_waitcnt lgkmcnt(0)
	v_mfma_f32_16x16x32_bf16 v[56:59], v[128:131], v[176:179], v[56:59]
	v_mfma_f32_16x16x32_bf16 v[60:63], v[136:139], v[176:179], v[60:63]
	v_mfma_f32_16x16x32_bf16 v[40:43], v[128:131], v[184:187], v[40:43]
	v_mfma_f32_16x16x32_bf16 v[44:47], v[136:139], v[184:187], v[44:47]
	v_mfma_f32_16x16x32_bf16 v[24:27], v[128:131], v[202:205], v[24:27]
	v_mfma_f32_16x16x32_bf16 v[28:31], v[136:139], v[202:205], v[28:31]
	v_mfma_f32_16x16x32_bf16 v[8:11], v[128:131], v[214:217], v[8:11]
	v_mfma_f32_16x16x32_bf16 v[12:15], v[136:139], v[214:217], v[12:15]
	v_mfma_f32_16x16x32_bf16 v[56:59], v[132:135], v[180:183], v[56:59]
	v_mfma_f32_16x16x32_bf16 v[60:63], v[140:143], v[180:183], v[60:63]
	v_mfma_f32_16x16x32_bf16 v[40:43], v[132:135], v[198:201], v[40:43]
	v_mfma_f32_16x16x32_bf16 v[44:47], v[140:143], v[198:201], v[44:47]
	v_mfma_f32_16x16x32_bf16 v[24:27], v[132:135], v[206:209], v[24:27]
	v_mfma_f32_16x16x32_bf16 v[28:31], v[140:143], v[206:209], v[28:31]
	v_mfma_f32_16x16x32_bf16 v[8:11], v[132:135], v[218:221], v[8:11]
	v_mfma_f32_16x16x32_bf16 v[12:15], v[140:143], v[218:221], v[12:15]
	s_setprio 0
	s_setprio 1
	v_mfma_f32_16x16x32_bf16 v[48:51], v[144:147], v[176:179], v[48:51]
	v_mfma_f32_16x16x32_bf16 v[52:55], v[152:155], v[176:179], v[52:55]
	v_mfma_f32_16x16x32_bf16 v[32:35], v[144:147], v[184:187], v[32:35]
	v_mfma_f32_16x16x32_bf16 v[36:39], v[152:155], v[184:187], v[36:39]
	v_mfma_f32_16x16x32_bf16 v[16:19], v[144:147], v[202:205], v[16:19]
	v_mfma_f32_16x16x32_bf16 v[20:23], v[152:155], v[202:205], v[20:23]
	v_mfma_f32_16x16x32_bf16 v[4:7], v[144:147], v[214:217], v[4:7]
	v_mfma_f32_16x16x32_bf16 v[0:3], v[152:155], v[214:217], v[0:3]
	v_mfma_f32_16x16x32_bf16 v[48:51], v[148:151], v[180:183], v[48:51]
	v_mfma_f32_16x16x32_bf16 v[52:55], v[172:175], v[180:183], v[52:55]
	v_mfma_f32_16x16x32_bf16 v[32:35], v[148:151], v[198:201], v[32:35]
	v_mfma_f32_16x16x32_bf16 v[36:39], v[172:175], v[198:201], v[36:39]
	v_mfma_f32_16x16x32_bf16 v[16:19], v[148:151], v[206:209], v[16:19]
	v_mfma_f32_16x16x32_bf16 v[20:23], v[172:175], v[206:209], v[20:23]
	v_mfma_f32_16x16x32_bf16 v[4:7], v[148:151], v[218:221], v[4:7]
	v_mfma_f32_16x16x32_bf16 v[0:3], v[172:175], v[218:221], v[0:3]
	s_setprio 0
	s_barrier
	s_add_i32 s74, s74, 2
	s_add_u32 s72, s72, 0x100
	s_addc_u32 s73, s73, 0
	s_cmp_gt_u32 s74, 9
	s_mov_b64 s[0:1], s[12:13]
	s_cbranch_scc0 .LBB0_930
	s_and_b64 vcc, exec, s[28:29]
	s_cbranch_vccz .LBB0_933
	s_barrier

; #define PG8_STAGE(bufoff, gbase, voff) do { _Pragma("unroll") for (int _i = 0; _i < 2; ++_i) \
;     __builtin_amdgcn_global_load_lds((const unsigned*)((const char*)(gbase) + (voff)[_i]), (PG8_LAS unsigned*)(lds + (bufoff) + ldsw + _i * 8192), 16, 0, 0); } while (0)
; #define PG8_LDA(dst, b, h) do { _Pragma("unroll") for (int m = 0; m < 4; ++m) _Pragma("unroll") for (int k = 0; k < 2; ++k) dst[m][k] = *(const PG8_LAS bf16x8*)(lds + PG8_SA(b, h) + aoff + m * 2048 + k * 1024); } while (0)
; #define PG8_LDB(dst, b, h) do { _Pragma("unroll") for (int n = 0; n < 2; ++n) _Pragma("unroll") for (int k = 0; k < 2; ++k) dst[n][k] = *(const PG8_LAS bf16x8*)(lds + PG8_SB(b, h) + boff + n * 2048 + k * 1024); } while (0)
; #define PG8_MMA(ai, bj, At, Bt) do { __builtin_amdgcn_s_setprio(1); _Pragma("unroll") for (int m = 0; m < 4; ++m) _Pragma("unroll") for (int n = 0; n < 2; ++n) _Pragma("unroll") for (int k = 0; k < 2; ++k) \
;     acc[ai][bj][m][n] = __builtin_amdgcn_mfma_f32_16x16x32_bf16(Bt[n][k], At[m][k], acc[ai][bj][m][n], 0, 0, 0); __builtin_amdgcn_s_setprio(0); } while (0)
; #define PG8_WAIT_V(n) asm volatile("s_waitcnt vmcnt(" #n ")" ::: "memory")
; #define PG8_WAIT_L(n) asm volatile("s_waitcnt lgkmcnt(" #n ")" ::: "memory")
; #define PG8_BAR __builtin_amdgcn_s_barrier()
; #define PG8_SCHED __builtin_amdgcn_sched_barrier(0)
; template <class Epi, class Sched>
; DI void gemm_phase(PG8_LAS unsigned char* lds, const Gemm g, const Sched& S, const Epi& E) {
;     ...
;       PG8_LDB(B0, 0, 0); PG8_LDB(B1, 0, 1); PG8_SCHED; PG8_LDA(At, 0, 0); PG8_STAGE(PG8_SA(1, 1), a1 + hstepA, voffA);
;       PG8_WAIT_V(8); PG8_WAIT_L(0); PG8_BAR; PG8_MMA(0, 0, At, B0); PG8_MMA(0, 1, At, B1); PG8_BAR; PG8_SCHED;
;       PG8_LDA(At, 0, 1); PG8_STAGE(PG8_SB(0, 0), b2, voffB); PG8_STAGE(PG8_SB(0, 1), b2 + hstepB, voffB); PG8_STAGE(PG8_SA(0, 0), a2, voffA);
;       PG8_WAIT_V(8); PG8_WAIT_L(0); PG8_BAR; PG8_MMA(1, 0, At, B0); PG8_MMA(1, 1, At, B1); PG8_BAR; PG8_SCHED;
.LBB0_1300:
	ds_read_b128 v[128:131], v156
	ds_read_b128 v[132:135], v156 offset:1024
	ds_read_b128 v[150:153], v156 offset:2048
	ds_read_b128 v[162:165], v156 offset:3072
	ds_read_b128 v[166:169], v157
	ds_read_b128 v[170:173], v157 offset:1024
	ds_read_b128 v[174:177], v157 offset:2048
	ds_read_b128 v[178:181], v157 offset:3072
	s_add_u32 s17, s62, 0xfffc0080
	s_addc_u32 s33, s63, -1
	s_cmp_eq_u32 s75, 12
	s_cselect_b32 s67, s39, s33
	s_cselect_b32 s66, s59, s17
	s_cselect_b32 s65, s37, s74
	s_cselect_b32 s64, s61, s73
	s_add_i32 m0, s53, 0xc000
	ds_read_b128 v[182:185], v158
	ds_read_b128 v[186:189], v158 offset:1024
	ds_read_b128 v[190:193], v158 offset:2048
	ds_read_b128 v[194:197], v158 offset:3072
	ds_read_b128 v[198:201], v158 offset:4096
	ds_read_b128 v[202:205], v158 offset:5120
	ds_read_b128 v[206:209], v158 offset:6144
	ds_read_b128 v[214:217], v158 offset:7168
	global_load_lds_dwordx4 v146, s[62:63]
	s_add_i32 m0, s53, 0xe000
	s_nop 0
	global_load_lds_dwordx4 v148, s[62:63]
	s_waitcnt vmcnt(8)
	s_waitcnt lgkmcnt(0)
	s_barrier
	s_setprio 1
	s_waitcnt lgkmcnt(0)
	v_mfma_f32_16x16x32_bf16 v[124:127], v[128:131], v[182:185], v[124:127]
	v_mfma_f32_16x16x32_bf16 v[120:123], v[150:153], v[182:185], v[120:123]
	v_mfma_f32_16x16x32_bf16 v[108:111], v[128:131], v[190:193], v[108:111]
	v_mfma_f32_16x16x32_bf16 v[104:107], v[150:153], v[190:193], v[104:107]
	v_mfma_f32_16x16x32_bf16 v[92:95], v[128:131], v[198:201], v[92:95]
	v_mfma_f32_16x16x32_bf16 v[88:91], v[150:153], v[198:201], v[88:91]
	v_mfma_f32_16x16x32_bf16 v[76:79], v[128:131], v[206:209], v[76:79]
	v_mfma_f32_16x16x32_bf16 v[72:75], v[150:153], v[206:209], v[72:75]
	v_mfma_f32_16x16x32_bf16 v[124:127], v[132:135], v[186:189], v[124:127]
	v_mfma_f32_16x16x32_bf16 v[120:123], v[162:165], v[186:189], v[120:123]
	v_mfma_f32_16x16x32_bf16 v[108:111], v[132:135], v[194:197], v[108:111]
	v_mfma_f32_16x16x32_bf16 v[104:107], v[162:165], v[194:197], v[104:107]
	v_mfma_f32_16x16x32_bf16 v[92:95], v[132:135], v[202:205], v[92:95]
	v_mfma_f32_16x16x32_bf16 v[88:91], v[162:165], v[202:205], v[88:91]
	v_mfma_f32_16x16x32_bf16 v[76:79], v[132:135], v[214:217], v[76:79]
	v_mfma_f32_16x16x32_bf16 v[72:75], v[162:165], v[214:217], v[72:75]
	s_setprio 0
	s_setprio 1
	v_mfma_f32_16x16x32_bf16 v[116:119], v[166:169], v[182:185], v[116:119]
	v_mfma_f32_16x16x32_bf16 v[112:115], v[174:177], v[182:185], v[112:115]
	v_mfma_f32_16x16x32_bf16 v[100:103], v[166:169], v[190:193], v[100:103]
	v_mfma_f32_16x16x32_bf16 v[96:99], v[174:177], v[190:193], v[96:99]
	v_mfma_f32_16x16x32_bf16 v[84:87], v[166:169], v[198:201], v[84:87]
	v_mfma_f32_16x16x32_bf16 v[80:83], v[174:177], v[198:201], v[80:83]
	v_mfma_f32_16x16x32_bf16 v[68:71], v[166:169], v[206:209], v[68:71]
	v_mfma_f32_16x16x32_bf16 v[64:67], v[174:177], v[206:209], v[64:67]
	v_mfma_f32_16x16x32_bf16 v[116:119], v[170:173], v[186:189], v[116:119]
	v_mfma_f32_16x16x32_bf16 v[112:115], v[178:181], v[186:189], v[112:115]
	v_mfma_f32_16x16x32_bf16 v[100:103], v[170:173], v[194:197], v[100:103]
	v_mfma_f32_16x16x32_bf16 v[96:99], v[178:181], v[194:197], v[96:99]
	v_mfma_f32_16x16x32_bf16 v[84:87], v[170:173], v[202:205], v[84:87]
	v_mfma_f32_16x16x32_bf16 v[80:83], v[178:181], v[202:205], v[80:83]
	v_mfma_f32_16x16x32_bf16 v[68:71], v[170:173], v[214:217], v[68:71]
	v_mfma_f32_16x16x32_bf16 v[64:67], v[178:181], v[214:217], v[64:67]
	s_setprio 0
	s_barrier
	s_add_i32 s17, s69, s16
	s_mov_b32 m0, s17
	ds_read_b128 v[182:185], v158 offset:16384
	ds_read_b128 v[186:189], v158 offset:17408
	ds_read_b128 v[190:193], v158 offset:18432
	ds_read_b128 v[194:197], v158 offset:19456
	ds_read_b128 v[198:201], v158 offset:20480
	ds_read_b128 v[202:205], v158 offset:21504
	ds_read_b128 v[206:209], v158 offset:22528
	ds_read_b128 v[214:217], v158 offset:23552
	global_load_lds_dwordx4 v138, s[64:65]
	s_add_i32 m0, s17, 0x2000
	s_add_u32 s56, s64, 0x40000
	s_addc_u32 s57, s65, 0
	s_add_i32 s17, s70, s16
	global_load_lds_dwordx4 v142, s[64:65]
	s_mov_b32 m0, s17
	s_nop 0
	global_load_lds_dwordx4 v138, s[56:57]
	s_add_i32 m0, s17, 0x2000
	s_nop 0
	global_load_lds_dwordx4 v142, s[56:57]
	s_mov_b32 m0, s53
	s_nop 0
	global_load_lds_dwordx4 v136, s[66:67]
	s_mov_b32 m0, s18
	s_nop 0
	global_load_lds_dwordx4 v140, s[66:67]
	s_waitcnt vmcnt(8)
	s_waitcnt lgkmcnt(0)
	s_barrier
	s_setprio 1
	s_waitcnt lgkmcnt(0)
	v_mfma_f32_16x16x32_bf16 v[60:63], v[128:131], v[182:185], v[60:63]
	v_mfma_f32_16x16x32_bf16 v[56:59], v[150:153], v[182:185], v[56:59]
	v_mfma_f32_16x16x32_bf16 v[44:47], v[128:131], v[190:193], v[44:47]
	v_mfma_f32_16x16x32_bf16 v[40:43], v[150:153], v[190:193], v[40:43]
	v_mfma_f32_16x16x32_bf16 v[28:31], v[128:131], v[198:201], v[28:31]
	v_mfma_f32_16x16x32_bf16 v[24:27], v[150:153], v[198:201], v[24:27]
	v_mfma_f32_16x16x32_bf16 v[12:15], v[128:131], v[206:209], v[12:15]
	v_mfma_f32_16x16x32_bf16 v[8:11], v[150:153], v[206:209], v[8:11]
	v_mfma_f32_16x16x32_bf16 v[60:63], v[132:135], v[186:189], v[60:63]
	v_mfma_f32_16x16x32_bf16 v[56:59], v[162:165], v[186:189], v[56:59]
	v_mfma_f32_16x16x32_bf16 v[44:47], v[132:135], v[194:197], v[44:47]
	v_mfma_f32_16x16x32_bf16 v[40:43], v[162:165], v[194:197], v[40:43]
	v_mfma_f32_16x16x32_bf16 v[28:31], v[132:135], v[202:205], v[28:31]
	v_mfma_f32_16x16x32_bf16 v[24:27], v[162:165], v[202:205], v[24:27]
	v_mfma_f32_16x16x32_bf16 v[12:15], v[132:135], v[214:217], v[12:15]
	v_mfma_f32_16x16x32_bf16 v[8:11], v[162:165], v[214:217], v[8:11]
	s_setprio 0
	s_setprio 1
	v_mfma_f32_16x16x32_bf16 v[52:55], v[166:169], v[182:185], v[52:55]
	v_mfma_f32_16x16x32_bf16 v[48:51], v[174:177], v[182:185], v[48:51]
	v_mfma_f32_16x16x32_bf16 v[36:39], v[166:169], v[190:193], v[36:39]
	v_mfma_f32_16x16x32_bf16 v[32:35], v[174:177], v[190:193], v[32:35]
	v_mfma_f32_16x16x32_bf16 v[20:23], v[166:169], v[198:201], v[20:23]
	v_mfma_f32_16x16x32_bf16 v[16:19], v[174:177], v[198:201], v[16:19]
	v_mfma_f32_16x16x32_bf16 v[4:7], v[166:169], v[206:209], v[4:7]
	v_mfma_f32_16x16x32_bf16 v[0:3], v[174:177], v[206:209], v[0:3]
	v_mfma_f32_16x16x32_bf16 v[52:55], v[170:173], v[186:189], v[52:55]
	v_mfma_f32_16x16x32_bf16 v[48:51], v[178:181], v[186:189], v[48:51]
	v_mfma_f32_16x16x32_bf16 v[36:39], v[170:173], v[194:197], v[36:39]
	v_mfma_f32_16x16x32_bf16 v[32:35], v[178:181], v[194:197], v[32:35]
	v_mfma_f32_16x16x32_bf16 v[20:23], v[170:173], v[202:205], v[20:23]
	v_mfma_f32_16x16x32_bf16 v[16:19], v[178:181], v[202:205], v[16:19]
	v_mfma_f32_16x16x32_bf16 v[4:7], v[170:173], v[214:217], v[4:7]
	v_mfma_f32_16x16x32_bf16 v[0:3], v[178:181], v[214:217], v[0:3]
	s_setprio 0
	s_barrier
; #define PG8_STAGE(bufoff, gbase, voff) do { _Pragma("unroll") for (int _i = 0; _i < 2; ++_i) \
;     __builtin_amdgcn_global_load_lds((const unsigned*)((const char*)(gbase) + (voff)[_i]), (PG8_LAS unsigned*)(lds + (bufoff) + ldsw + _i * 8192), 16, 0, 0); } while (0)
; #define PG8_LDA(dst, b, h) do { _Pragma("unroll") for (int m = 0; m < 4; ++m) _Pragma("unroll") for (int k = 0; k < 2; ++k) dst[m][k] = *(const PG8_LAS bf16x8*)(lds + PG8_SA(b, h) + aoff + m * 2048 + k * 1024); } while (0)
; #define PG8_LDB(dst, b, h) do { _Pragma("unroll") for (int n = 0; n < 2; ++n) _Pragma("unroll") for (int k = 0; k < 2; ++k) dst[n][k] = *(const PG8_LAS bf16x8*)(lds + PG8_SB(b, h) + boff + n * 2048 + k * 1024); } while (0)
; #define PG8_MMA(ai, bj, At, Bt) do { __builtin_amdgcn_s_setprio(1); _Pragma("unroll") for (int m = 0; m < 4; ++m) _Pragma("unroll") for (int n = 0; n < 2; ++n) _Pragma("unroll") for (int k = 0; k < 2; ++k) \
;     acc[ai][bj][m][n] = __builtin_amdgcn_mfma_f32_16x16x32_bf16(Bt[n][k], At[m][k], acc[ai][bj][m][n], 0, 0, 0); __builtin_amdgcn_s_setprio(0); } while (0)
; #define PG8_WAIT_V(n) asm volatile("s_waitcnt vmcnt(" #n ")" ::: "memory")
; #define PG8_WAIT_L(n) asm volatile("s_waitcnt lgkmcnt(" #n ")" ::: "memory")
; #define PG8_BAR __builtin_amdgcn_s_barrier()
; #define PG8_SCHED __builtin_amdgcn_sched_barrier(0)
; template <class Epi, class Sched>
; DI void gemm_phase(PG8_LAS unsigned char* lds, const Gemm g, const Sched& S, const Epi& E) {
;     ...
;       PG8_LDB(B0, 1, 0); PG8_LDB(B1, 1, 1); PG8_SCHED; PG8_LDA(At, 1, 0); PG8_STAGE(PG8_SA(0, 1), a2 + hstepA, voffA);
;       PG8_WAIT_V(8); PG8_WAIT_L(0); PG8_BAR; PG8_MMA(0, 0, At, B0); PG8_MMA(0, 1, At, B1); PG8_BAR; PG8_SCHED;
	s_mov_b32 s17, 0x18000
	s_addk_i32 s17, 0x110
	v_add_u32_e32 v161, s17, v155
	ds_read_b128 v[128:131], v161
	ds_read_b128 v[132:135], v161 offset:1024
	ds_read_b128 v[150:153], v161 offset:2048
	ds_read_b128 v[162:165], v161 offset:3072
	ds_read_b128 v[166:169], v160
	ds_read_b128 v[170:173], v160 offset:1024
	ds_read_b128 v[174:177], v160 offset:2048
	ds_read_b128 v[178:181], v160 offset:3072
	s_add_u32 s56, s66, 0x40000
	s_addc_u32 s57, s67, 0
	s_mov_b32 m0, s19
	ds_read_b128 v[182:185], v158 offset:32768
	ds_read_b128 v[186:189], v158 offset:33792
	ds_read_b128 v[190:193], v158 offset:34816
	ds_read_b128 v[194:197], v158 offset:35840
	ds_read_b128 v[198:201], v158 offset:36864
	ds_read_b128 v[202:205], v158 offset:37888
	ds_read_b128 v[206:209], v158 offset:38912
	ds_read_b128 v[214:217], v158 offset:39936
	global_load_lds_dwordx4 v136, s[56:57]
	s_mov_b32 m0, s54
	s_nop 0
	global_load_lds_dwordx4 v140, s[56:57]
	s_waitcnt vmcnt(8)
	s_waitcnt lgkmcnt(0)
	s_barrier
	s_setprio 1
	s_waitcnt lgkmcnt(0)
	v_mfma_f32_16x16x32_bf16 v[124:127], v[128:131], v[182:185], v[124:127]
	v_mfma_f32_16x16x32_bf16 v[120:123], v[150:153], v[182:185], v[120:123]
	v_mfma_f32_16x16x32_bf16 v[108:111], v[128:131], v[190:193], v[108:111]
	v_mfma_f32_16x16x32_bf16 v[104:107], v[150:153], v[190:193], v[104:107]
	v_mfma_f32_16x16x32_bf16 v[92:95], v[128:131], v[198:201], v[92:95]
	v_mfma_f32_16x16x32_bf16 v[88:91], v[150:153], v[198:201], v[88:91]
	v_mfma_f32_16x16x32_bf16 v[76:79], v[128:131], v[206:209], v[76:79]
	v_mfma_f32_16x16x32_bf16 v[72:75], v[150:153], v[206:209], v[72:75]
	v_mfma_f32_16x16x32_bf16 v[124:127], v[132:135], v[186:189], v[124:127]
	v_mfma_f32_16x16x32_bf16 v[120:123], v[162:165], v[186:189], v[120:123]
	v_mfma_f32_16x16x32_bf16 v[108:111], v[132:135], v[194:197], v[108:111]
	v_mfma_f32_16x16x32_bf16 v[104:107], v[162:165], v[194:197], v[104:107]
	v_mfma_f32_16x16x32_bf16 v[92:95], v[132:135], v[202:205], v[92:95]
	v_mfma_f32_16x16x32_bf16 v[88:91], v[162:165], v[202:205], v[88:91]
	v_mfma_f32_16x16x32_bf16 v[76:79], v[132:135], v[214:217], v[76:79]
	v_mfma_f32_16x16x32_bf16 v[72:75], v[162:165], v[214:217], v[72:75]
	s_setprio 0
	s_setprio 1
	v_mfma_f32_16x16x32_bf16 v[116:119], v[166:169], v[182:185], v[116:119]
	v_mfma_f32_16x16x32_bf16 v[112:115], v[174:177], v[182:185], v[112:115]
	v_mfma_f32_16x16x32_bf16 v[100:103], v[166:169], v[190:193], v[100:103]
	v_mfma_f32_16x16x32_bf16 v[96:99], v[174:177], v[190:193], v[96:99]
	v_mfma_f32_16x16x32_bf16 v[84:87], v[166:169], v[198:201], v[84:87]
	v_mfma_f32_16x16x32_bf16 v[80:83], v[174:177], v[198:201], v[80:83]
	v_mfma_f32_16x16x32_bf16 v[68:71], v[166:169], v[206:209], v[68:71]
	v_mfma_f32_16x16x32_bf16 v[64:67], v[174:177], v[206:209], v[64:67]
	v_mfma_f32_16x16x32_bf16 v[116:119], v[170:173], v[186:189], v[116:119]
	v_mfma_f32_16x16x32_bf16 v[112:115], v[178:181], v[186:189], v[112:115]
	v_mfma_f32_16x16x32_bf16 v[100:103], v[170:173], v[194:197], v[100:103]
	v_mfma_f32_16x16x32_bf16 v[96:99], v[178:181], v[194:197], v[96:99]
	v_mfma_f32_16x16x32_bf16 v[84:87], v[170:173], v[202:205], v[84:87]
	v_mfma_f32_16x16x32_bf16 v[80:83], v[178:181], v[202:205], v[80:83]
	v_mfma_f32_16x16x32_bf16 v[68:71], v[170:173], v[214:217], v[68:71]
	v_mfma_f32_16x16x32_bf16 v[64:67], v[178:181], v[214:217], v[64:67]
	s_setprio 0
	s_barrier
; #define PG8_STAGE(bufoff, gbase, voff) do { _Pragma("unroll") for (int _i = 0; _i < 2; ++_i) \
;     __builtin_amdgcn_global_load_lds((const unsigned*)((const char*)(gbase) + (voff)[_i]), (PG8_LAS unsigned*)(lds + (bufoff) + ldsw + _i * 8192), 16, 0, 0); } while (0)
; #define PG8_LDA(dst, b, h) do { _Pragma("unroll") for (int m = 0; m < 4; ++m) _Pragma("unroll") for (int k = 0; k < 2; ++k) dst[m][k] = *(const PG8_LAS bf16x8*)(lds + PG8_SA(b, h) + aoff + m * 2048 + k * 1024); } while (0)
; #define PG8_MMA(ai, bj, At, Bt) do { __builtin_amdgcn_s_setprio(1); _Pragma("unroll") for (int m = 0; m < 4; ++m) _Pragma("unroll") for (int n = 0; n < 2; ++n) _Pragma("unroll") for (int k = 0; k < 2; ++k) \
;     acc[ai][bj][m][n] = __builtin_amdgcn_mfma_f32_16x16x32_bf16(Bt[n][k], At[m][k], acc[ai][bj][m][n], 0, 0, 0); __builtin_amdgcn_s_setprio(0); } while (0)
; #define PG8_WAIT_V(n) asm volatile("s_waitcnt vmcnt(" #n ")" ::: "memory")
; #define PG8_WAIT_L(n) asm volatile("s_waitcnt lgkmcnt(" #n ")" ::: "memory")
; #define PG8_BAR __builtin_amdgcn_s_barrier()
; #define PG8_SCHED __builtin_amdgcn_sched_barrier(0)
;   DI void operator()(const f32x4 (&acc)[2][2][4][2], const Unit& u, int wr, int wc, int fr, int fq) const {
;     ...
;     RES_LD(0)
; template <class Epi, class Sched>
; DI void gemm_phase(PG8_LAS unsigned char* lds, const Gemm g, const Sched& S, const Epi& E) {
;     ...
;       PG8_LDA(At, 1, 1); PG8_STAGE(PG8_SB(1, 0), b3, voffB); PG8_STAGE(PG8_SB(1, 1), b3 + hstepB, voffB); PG8_STAGE(PG8_SA(1, 0), a3, voffA);
;       PG8_WAIT_V(8); PG8_WAIT_L(0); PG8_BAR; PG8_MMA(1, 0, At, B0); PG8_MMA(1, 1, At, B1); PG8_BAR; PG8_SCHED;
;     }
;     if (wr == 0) PG8_BAR;
;     E(acc, cur, wr, wc, fr, fq);
	s_add_i32 s17, s17, s16
	s_mov_b32 m0, s17
	ds_read_b128 v[182:185], v158 offset:49152
	ds_read_b128 v[186:189], v158 offset:50176
	ds_read_b128 v[190:193], v158 offset:51200
	ds_read_b128 v[194:197], v158 offset:52224
	ds_read_b128 v[198:201], v158 offset:53248
	ds_read_b128 v[202:205], v158 offset:54272
	ds_read_b128 v[206:209], v158 offset:55296
	ds_read_b128 v[214:217], v158 offset:56320
	s_add_u32 s100, s64, 0x80
	s_addc_u32 s101, s65, 0
	global_load_lds_dwordx4 v138, s[100:101]
	s_add_i32 m0, s17, 0x2000
	s_add_u32 s56, s64, 0x40080
	s_addc_u32 s57, s65, 0
	s_add_i32 s17, s71, s16
	global_load_lds_dwordx4 v142, s[100:101]
	s_mov_b32 m0, s17
	s_nop 0
	global_load_lds_dwordx4 v138, s[56:57]
	s_add_i32 m0, s17, 0x2000
	s_nop 0
	global_load_lds_dwordx4 v142, s[56:57]
	s_mov_b32 m0, s5
	s_nop 0
	s_add_u32 s100, s66, 0x80
	s_addc_u32 s101, s67, 0
	global_load_lds_dwordx4 v136, s[100:101]
	s_mov_b32 m0, s55
	s_nop 0
	global_load_lds_dwordx4 v140, s[100:101]
	s_waitcnt vmcnt(8)
	s_waitcnt lgkmcnt(0)
	s_barrier
	s_setprio 1
	s_waitcnt lgkmcnt(0)
	v_mfma_f32_16x16x32_bf16 v[60:63], v[128:131], v[182:185], v[60:63]
	v_mfma_f32_16x16x32_bf16 v[56:59], v[150:153], v[182:185], v[56:59]
	v_mfma_f32_16x16x32_bf16 v[44:47], v[128:131], v[190:193], v[44:47]
	v_mfma_f32_16x16x32_bf16 v[40:43], v[150:153], v[190:193], v[40:43]
	v_mfma_f32_16x16x32_bf16 v[28:31], v[128:131], v[198:201], v[28:31]
	v_mfma_f32_16x16x32_bf16 v[24:27], v[150:153], v[198:201], v[24:27]
	v_mfma_f32_16x16x32_bf16 v[12:15], v[128:131], v[206:209], v[12:15]
	v_mfma_f32_16x16x32_bf16 v[8:11], v[150:153], v[206:209], v[8:11]
	v_mfma_f32_16x16x32_bf16 v[60:63], v[132:135], v[186:189], v[60:63]
	v_mfma_f32_16x16x32_bf16 v[56:59], v[162:165], v[186:189], v[56:59]
	v_mfma_f32_16x16x32_bf16 v[44:47], v[132:135], v[194:197], v[44:47]
	v_mfma_f32_16x16x32_bf16 v[40:43], v[162:165], v[194:197], v[40:43]
	v_mfma_f32_16x16x32_bf16 v[28:31], v[132:135], v[202:205], v[28:31]
	v_mfma_f32_16x16x32_bf16 v[24:27], v[162:165], v[202:205], v[24:27]
	v_mfma_f32_16x16x32_bf16 v[12:15], v[132:135], v[214:217], v[12:15]
	v_mfma_f32_16x16x32_bf16 v[8:11], v[162:165], v[214:217], v[8:11]
	s_setprio 0
	s_setprio 1
	v_mfma_f32_16x16x32_bf16 v[52:55], v[166:169], v[182:185], v[52:55]
	v_mfma_f32_16x16x32_bf16 v[48:51], v[174:177], v[182:185], v[48:51]
	v_mfma_f32_16x16x32_bf16 v[36:39], v[166:169], v[190:193], v[36:39]
	v_mfma_f32_16x16x32_bf16 v[32:35], v[174:177], v[190:193], v[32:35]
	v_mfma_f32_16x16x32_bf16 v[20:23], v[166:169], v[198:201], v[20:23]
	v_mfma_f32_16x16x32_bf16 v[16:19], v[174:177], v[198:201], v[16:19]
	v_mfma_f32_16x16x32_bf16 v[4:7], v[166:169], v[206:209], v[4:7]
	v_mfma_f32_16x16x32_bf16 v[0:3], v[174:177], v[206:209], v[0:3]
	v_mfma_f32_16x16x32_bf16 v[52:55], v[170:173], v[186:189], v[52:55]
	v_mfma_f32_16x16x32_bf16 v[48:51], v[178:181], v[186:189], v[48:51]
	v_mfma_f32_16x16x32_bf16 v[36:39], v[170:173], v[194:197], v[36:39]
	v_mfma_f32_16x16x32_bf16 v[32:35], v[178:181], v[194:197], v[32:35]
	v_mfma_f32_16x16x32_bf16 v[20:23], v[170:173], v[202:205], v[20:23]
	v_mfma_f32_16x16x32_bf16 v[16:19], v[178:181], v[202:205], v[16:19]
	v_mfma_f32_16x16x32_bf16 v[4:7], v[170:173], v[214:217], v[4:7]
	v_mfma_f32_16x16x32_bf16 v[0:3], v[178:181], v[214:217], v[0:3]
	s_setprio 0
	s_barrier
	s_add_i32 s75, s75, 2
	s_add_u32 s62, s62, 0x100
	s_addc_u32 s63, s63, 0
	s_add_u32 s73, s73, 0x100
	s_addc_u32 s74, s74, 0
	s_cmp_gt_u32 s75, 13
	s_cbranch_scc0 .LBB0_1300
	v_lshl_add_u32 v152, s60, 8, v154
	v_ashrrev_i32_e32 v153, 31, v152
	s_lshl_b32 s56, s58, 8
	v_lshlrev_b64 v[128:129], 11, v[152:153]
	s_ashr_i32 s57, s56, 31
	v_lshl_add_u64 v[128:129], s[50:51], 0, v[128:129]
	v_lshl_add_u64 v[128:129], s[56:57], 1, v[128:129]
	v_lshl_add_u64 v[128:129], v[128:129], 0, s[10:11]
	v_lshl_add_u64 v[150:151], v[128:129], 0, v[144:145]
	s_mov_b32 s17, 0x8000
	v_add_co_u32_e32 v128, vcc, s17, v150
	global_load_dwordx4 v[164:167], v[150:151], off
	global_load_dwordx4 v[168:171], v[150:151], off offset:256
	v_addc_co_u32_e32 v129, vcc, 0, v151, vcc
	global_load_dwordx4 v[132:135], v[128:129], off
	s_nop 0
	global_load_dwordx4 v[128:131], v[128:129], off offset:256
	s_and_b64 vcc, exec, s[8:9]
	s_cbranch_vccz .LBB0_1303
	s_barrier

; #define PG8_STAGE(bufoff, gbase, voff) do { _Pragma("unroll") for (int _i = 0; _i < 2; ++_i) \
;     __builtin_amdgcn_global_load_lds((const unsigned*)((const char*)(gbase) + (voff)[_i]), (PG8_LAS unsigned*)(lds + (bufoff) + ldsw + _i * 8192), 16, 0, 0); } while (0)
; #define PG8_LDA(dst, b, h) do { _Pragma("unroll") for (int m = 0; m < 4; ++m) _Pragma("unroll") for (int k = 0; k < 2; ++k) dst[m][k] = *(const PG8_LAS bf16x8*)(lds + PG8_SA(b, h) + aoff + m * 2048 + k * 1024); } while (0)
; #define PG8_LDB(dst, b, h) do { _Pragma("unroll") for (int n = 0; n < 2; ++n) _Pragma("unroll") for (int k = 0; k < 2; ++k) dst[n][k] = *(const PG8_LAS bf16x8*)(lds + PG8_SB(b, h) + boff + n * 2048 + k * 1024); } while (0)
; #define PG8_MMA(ai, bj, At, Bt) do { __builtin_amdgcn_s_setprio(1); _Pragma("unroll") for (int m = 0; m < 4; ++m) _Pragma("unroll") for (int n = 0; n < 2; ++n) _Pragma("unroll") for (int k = 0; k < 2; ++k) \
;     acc[ai][bj][m][n] = __builtin_amdgcn_mfma_f32_16x16x32_bf16(Bt[n][k], At[m][k], acc[ai][bj][m][n], 0, 0, 0); __builtin_amdgcn_s_setprio(0); } while (0)
; #define PG8_WAIT_V(n) asm volatile("s_waitcnt vmcnt(" #n ")" ::: "memory")
; #define PG8_WAIT_L(n) asm volatile("s_waitcnt lgkmcnt(" #n ")" ::: "memory")
; #define PG8_BAR __builtin_amdgcn_s_barrier()
; #define PG8_SCHED __builtin_amdgcn_sched_barrier(0)
; template <class Epi, class Sched>
; DI void gemm_phase(PG8_LAS unsigned char* lds, const Gemm g, const Sched& S, const Epi& E) {
;     ...
;       PG8_LDB(B0, 0, 0); PG8_LDB(B1, 0, 1); PG8_SCHED; PG8_LDA(At, 0, 0); PG8_STAGE(PG8_SA(1, 1), a1 + hstepA, voffA);
;       PG8_WAIT_V(8); PG8_WAIT_L(0); PG8_BAR; PG8_MMA(0, 0, At, B0); PG8_MMA(0, 1, At, B1); PG8_BAR; PG8_SCHED;
;       PG8_LDA(At, 0, 1); PG8_STAGE(PG8_SB(0, 0), b2, voffB); PG8_STAGE(PG8_SB(0, 1), b2 + hstepB, voffB); PG8_STAGE(PG8_SA(0, 0), a2, voffA);
;       PG8_WAIT_V(8); PG8_WAIT_L(0); PG8_BAR; PG8_MMA(1, 0, At, B0); PG8_MMA(1, 1, At, B1); PG8_BAR; PG8_SCHED;
.LBB0_1384:
	ds_read_b128 v[144:147], v155
	ds_read_b128 v[156:159], v155 offset:1024
	ds_read_b128 v[174:177], v155 offset:2048
	ds_read_b128 v[178:181], v155 offset:3072
	ds_read_b128 v[182:185], v161
	ds_read_b128 v[186:189], v161 offset:1024
	ds_read_b128 v[190:193], v161 offset:2048
	ds_read_b128 v[194:197], v161 offset:3072
	s_add_u32 s30, s2, 0xfffc0080
	s_addc_u32 s31, s3, -1
	s_cmp_eq_u32 s55, 12
	s_cselect_b32 s35, s1, s31
	s_cselect_b32 s34, s23, s30
	s_cselect_b32 s31, s21, s54
	s_cselect_b32 s30, s49, s53
	s_add_i32 m0, s17, 0xc000
	ds_read_b128 v[198:201], v165
	ds_read_b128 v[202:205], v165 offset:1024
	ds_read_b128 v[206:209], v165 offset:2048
	ds_read_b128 v[214:217], v165 offset:3072
	ds_read_b128 v[218:221], v165 offset:4096
	ds_read_b128 v[222:225], v165 offset:5120
	ds_read_b128 v[226:229], v165 offset:6144
	ds_read_b128 v[230:233], v165 offset:7168
	global_load_lds_dwordx4 v140, s[2:3]
	s_add_i32 m0, s17, 0xe000
	s_nop 0
	global_load_lds_dwordx4 v142, s[2:3]
	s_waitcnt vmcnt(8)
	s_waitcnt lgkmcnt(0)
	s_barrier
	s_setprio 1
	s_waitcnt lgkmcnt(0)
	v_mfma_f32_16x16x32_bf16 v[124:127], v[144:147], v[198:201], v[124:127]
	v_mfma_f32_16x16x32_bf16 v[120:123], v[174:177], v[198:201], v[120:123]
	v_mfma_f32_16x16x32_bf16 v[108:111], v[144:147], v[206:209], v[108:111]
	v_mfma_f32_16x16x32_bf16 v[104:107], v[174:177], v[206:209], v[104:107]
	v_mfma_f32_16x16x32_bf16 v[92:95], v[144:147], v[218:221], v[92:95]
	v_mfma_f32_16x16x32_bf16 v[88:91], v[174:177], v[218:221], v[88:91]
	v_mfma_f32_16x16x32_bf16 v[76:79], v[144:147], v[226:229], v[76:79]
	v_mfma_f32_16x16x32_bf16 v[72:75], v[174:177], v[226:229], v[72:75]
	v_mfma_f32_16x16x32_bf16 v[124:127], v[156:159], v[202:205], v[124:127]
	v_mfma_f32_16x16x32_bf16 v[120:123], v[178:181], v[202:205], v[120:123]
	v_mfma_f32_16x16x32_bf16 v[108:111], v[156:159], v[214:217], v[108:111]
	v_mfma_f32_16x16x32_bf16 v[104:107], v[178:181], v[214:217], v[104:107]
	v_mfma_f32_16x16x32_bf16 v[92:95], v[156:159], v[222:225], v[92:95]
	v_mfma_f32_16x16x32_bf16 v[88:91], v[178:181], v[222:225], v[88:91]
	v_mfma_f32_16x16x32_bf16 v[76:79], v[156:159], v[230:233], v[76:79]
	v_mfma_f32_16x16x32_bf16 v[72:75], v[178:181], v[230:233], v[72:75]
	s_setprio 0
	s_setprio 1
	v_mfma_f32_16x16x32_bf16 v[116:119], v[182:185], v[198:201], v[116:119]
	v_mfma_f32_16x16x32_bf16 v[112:115], v[190:193], v[198:201], v[112:115]
	v_mfma_f32_16x16x32_bf16 v[100:103], v[182:185], v[206:209], v[100:103]
	v_mfma_f32_16x16x32_bf16 v[96:99], v[190:193], v[206:209], v[96:99]
	v_mfma_f32_16x16x32_bf16 v[84:87], v[182:185], v[218:221], v[84:87]
	v_mfma_f32_16x16x32_bf16 v[80:83], v[190:193], v[218:221], v[80:83]
	v_mfma_f32_16x16x32_bf16 v[68:71], v[182:185], v[226:229], v[68:71]
	v_mfma_f32_16x16x32_bf16 v[64:67], v[190:193], v[226:229], v[64:67]
	v_mfma_f32_16x16x32_bf16 v[116:119], v[186:189], v[202:205], v[116:119]
	v_mfma_f32_16x16x32_bf16 v[112:115], v[194:197], v[202:205], v[112:115]
	v_mfma_f32_16x16x32_bf16 v[100:103], v[186:189], v[214:217], v[100:103]
	v_mfma_f32_16x16x32_bf16 v[96:99], v[194:197], v[214:217], v[96:99]
	v_mfma_f32_16x16x32_bf16 v[84:87], v[186:189], v[222:225], v[84:87]
	v_mfma_f32_16x16x32_bf16 v[80:83], v[194:197], v[222:225], v[80:83]
	v_mfma_f32_16x16x32_bf16 v[68:71], v[186:189], v[230:233], v[68:71]
	v_mfma_f32_16x16x32_bf16 v[64:67], v[194:197], v[230:233], v[64:67]
	s_setprio 0
	s_barrier
	s_add_i32 s56, s37, s15
	s_mov_b32 m0, s56
	ds_read_b128 v[198:201], v165 offset:16384
	ds_read_b128 v[202:205], v165 offset:17408
	ds_read_b128 v[206:209], v165 offset:18432
	ds_read_b128 v[214:217], v165 offset:19456
	ds_read_b128 v[218:221], v165 offset:20480
	ds_read_b128 v[222:225], v165 offset:21504
	ds_read_b128 v[226:229], v165 offset:22528
	ds_read_b128 v[230:233], v165 offset:23552
	global_load_lds_dwordx4 v132, s[30:31]
	s_add_i32 m0, s56, 0x2000
	s_add_u32 s56, s30, 0x40000
	s_addc_u32 s57, s31, 0
	s_add_i32 s58, s38, s15
	global_load_lds_dwordx4 v128, s[30:31]
	s_mov_b32 m0, s58
	s_add_u32 s98, s34, 0x80
	s_addc_u32 s99, s35, 0
	global_load_lds_dwordx4 v132, s[56:57]
	s_add_i32 m0, s58, 0x2000
	s_nop 0
	global_load_lds_dwordx4 v128, s[56:57]
	s_mov_b32 m0, s17
	s_nop 0
	global_load_lds_dwordx4 v134, s[34:35]
	s_mov_b32 m0, s4
	s_nop 0
	global_load_lds_dwordx4 v130, s[34:35]
	s_waitcnt vmcnt(8)
	s_waitcnt lgkmcnt(0)
	s_barrier
	s_setprio 1
	s_waitcnt lgkmcnt(0)
	v_mfma_f32_16x16x32_bf16 v[60:63], v[144:147], v[198:201], v[60:63]
	v_mfma_f32_16x16x32_bf16 v[56:59], v[174:177], v[198:201], v[56:59]
	v_mfma_f32_16x16x32_bf16 v[44:47], v[144:147], v[206:209], v[44:47]
	v_mfma_f32_16x16x32_bf16 v[40:43], v[174:177], v[206:209], v[40:43]
	v_mfma_f32_16x16x32_bf16 v[28:31], v[144:147], v[218:221], v[28:31]
	v_mfma_f32_16x16x32_bf16 v[24:27], v[174:177], v[218:221], v[24:27]
	v_mfma_f32_16x16x32_bf16 v[12:15], v[144:147], v[226:229], v[12:15]
	v_mfma_f32_16x16x32_bf16 v[8:11], v[174:177], v[226:229], v[8:11]
	v_mfma_f32_16x16x32_bf16 v[60:63], v[156:159], v[202:205], v[60:63]
	v_mfma_f32_16x16x32_bf16 v[56:59], v[178:181], v[202:205], v[56:59]
	v_mfma_f32_16x16x32_bf16 v[44:47], v[156:159], v[214:217], v[44:47]
	v_mfma_f32_16x16x32_bf16 v[40:43], v[178:181], v[214:217], v[40:43]
	v_mfma_f32_16x16x32_bf16 v[28:31], v[156:159], v[222:225], v[28:31]
	v_mfma_f32_16x16x32_bf16 v[24:27], v[178:181], v[222:225], v[24:27]
	v_mfma_f32_16x16x32_bf16 v[12:15], v[156:159], v[230:233], v[12:15]
	v_mfma_f32_16x16x32_bf16 v[8:11], v[178:181], v[230:233], v[8:11]
	s_setprio 0
	s_setprio 1
	v_mfma_f32_16x16x32_bf16 v[52:55], v[182:185], v[198:201], v[52:55]
	v_mfma_f32_16x16x32_bf16 v[48:51], v[190:193], v[198:201], v[48:51]
	v_mfma_f32_16x16x32_bf16 v[36:39], v[182:185], v[206:209], v[36:39]
	v_mfma_f32_16x16x32_bf16 v[32:35], v[190:193], v[206:209], v[32:35]
	v_mfma_f32_16x16x32_bf16 v[20:23], v[182:185], v[218:221], v[20:23]
	v_mfma_f32_16x16x32_bf16 v[16:19], v[190:193], v[218:221], v[16:19]
	v_mfma_f32_16x16x32_bf16 v[4:7], v[182:185], v[226:229], v[4:7]
	v_mfma_f32_16x16x32_bf16 v[0:3], v[190:193], v[226:229], v[0:3]
	v_mfma_f32_16x16x32_bf16 v[52:55], v[186:189], v[202:205], v[52:55]
	v_mfma_f32_16x16x32_bf16 v[48:51], v[194:197], v[202:205], v[48:51]
	v_mfma_f32_16x16x32_bf16 v[36:39], v[186:189], v[214:217], v[36:39]
	v_mfma_f32_16x16x32_bf16 v[32:35], v[194:197], v[214:217], v[32:35]
	v_mfma_f32_16x16x32_bf16 v[20:23], v[186:189], v[222:225], v[20:23]
	v_mfma_f32_16x16x32_bf16 v[16:19], v[194:197], v[222:225], v[16:19]
	v_mfma_f32_16x16x32_bf16 v[4:7], v[186:189], v[230:233], v[4:7]
	v_mfma_f32_16x16x32_bf16 v[0:3], v[194:197], v[230:233], v[0:3]
	s_setprio 0
	s_barrier
; #define PG8_STAGE(bufoff, gbase, voff) do { _Pragma("unroll") for (int _i = 0; _i < 2; ++_i) \
;     __builtin_amdgcn_global_load_lds((const unsigned*)((const char*)(gbase) + (voff)[_i]), (PG8_LAS unsigned*)(lds + (bufoff) + ldsw + _i * 8192), 16, 0, 0); } while (0)
; #define PG8_LDA(dst, b, h) do { _Pragma("unroll") for (int m = 0; m < 4; ++m) _Pragma("unroll") for (int k = 0; k < 2; ++k) dst[m][k] = *(const PG8_LAS bf16x8*)(lds + PG8_SA(b, h) + aoff + m * 2048 + k * 1024); } while (0)
; #define PG8_LDB(dst, b, h) do { _Pragma("unroll") for (int n = 0; n < 2; ++n) _Pragma("unroll") for (int k = 0; k < 2; ++k) dst[n][k] = *(const PG8_LAS bf16x8*)(lds + PG8_SB(b, h) + boff + n * 2048 + k * 1024); } while (0)
; #define PG8_MMA(ai, bj, At, Bt) do { __builtin_amdgcn_s_setprio(1); _Pragma("unroll") for (int m = 0; m < 4; ++m) _Pragma("unroll") for (int n = 0; n < 2; ++n) _Pragma("unroll") for (int k = 0; k < 2; ++k) \
;     acc[ai][bj][m][n] = __builtin_amdgcn_mfma_f32_16x16x32_bf16(Bt[n][k], At[m][k], acc[ai][bj][m][n], 0, 0, 0); __builtin_amdgcn_s_setprio(0); } while (0)
; #define PG8_WAIT_V(n) asm volatile("s_waitcnt vmcnt(" #n ")" ::: "memory")
; #define PG8_WAIT_L(n) asm volatile("s_waitcnt lgkmcnt(" #n ")" ::: "memory")
; #define PG8_BAR __builtin_amdgcn_s_barrier()
; #define PG8_SCHED __builtin_amdgcn_sched_barrier(0)
; template <class Epi, class Sched>
; DI void gemm_phase(PG8_LAS unsigned char* lds, const Gemm g, const Sched& S, const Epi& E) {
;     ...
;       PG8_LDB(B0, 1, 0); PG8_LDB(B1, 1, 1); PG8_SCHED; PG8_LDA(At, 1, 0); PG8_STAGE(PG8_SA(0, 1), a2 + hstepA, voffA);
;       PG8_WAIT_V(8); PG8_WAIT_L(0); PG8_BAR; PG8_MMA(0, 0, At, B0); PG8_MMA(0, 1, At, B1); PG8_BAR; PG8_SCHED;
;       PG8_LDA(At, 1, 1); PG8_STAGE(PG8_SB(1, 0), b3, voffB); PG8_STAGE(PG8_SB(1, 1), b3 + hstepB, voffB); PG8_STAGE(PG8_SA(1, 0), a3, voffA);
;       PG8_WAIT_V(8); PG8_WAIT_L(0); PG8_BAR; PG8_MMA(1, 0, At, B0); PG8_MMA(1, 1, At, B1); PG8_BAR; PG8_SCHED;
	ds_read_b128 v[144:147], v171
	ds_read_b128 v[156:159], v171 offset:1024
	ds_read_b128 v[174:177], v171 offset:2048
	ds_read_b128 v[178:181], v171 offset:3072
	ds_read_b128 v[182:185], v173
	ds_read_b128 v[186:189], v173 offset:1024
	ds_read_b128 v[190:193], v173 offset:2048
	ds_read_b128 v[194:197], v173 offset:3072
	s_add_u32 s34, s34, 0x40000
	s_addc_u32 s35, s35, 0
	s_mov_b32 m0, s5
	ds_read_b128 v[198:201], v165 offset:32768
	ds_read_b128 v[202:205], v165 offset:33792
	ds_read_b128 v[206:209], v165 offset:34816
	ds_read_b128 v[214:217], v165 offset:35840
	ds_read_b128 v[218:221], v165 offset:36864
	ds_read_b128 v[222:225], v165 offset:37888
	ds_read_b128 v[226:229], v165 offset:38912
	ds_read_b128 v[230:233], v165 offset:39936
	global_load_lds_dwordx4 v134, s[34:35]
	s_mov_b32 m0, s19
	s_nop 0
	global_load_lds_dwordx4 v130, s[34:35]
	s_waitcnt vmcnt(8)
	s_waitcnt lgkmcnt(0)
	s_barrier
	s_setprio 1
	s_waitcnt lgkmcnt(0)
	v_mfma_f32_16x16x32_bf16 v[124:127], v[144:147], v[198:201], v[124:127]
	v_mfma_f32_16x16x32_bf16 v[120:123], v[174:177], v[198:201], v[120:123]
	v_mfma_f32_16x16x32_bf16 v[108:111], v[144:147], v[206:209], v[108:111]
	v_mfma_f32_16x16x32_bf16 v[104:107], v[174:177], v[206:209], v[104:107]
	v_mfma_f32_16x16x32_bf16 v[92:95], v[144:147], v[218:221], v[92:95]
	v_mfma_f32_16x16x32_bf16 v[88:91], v[174:177], v[218:221], v[88:91]
	v_mfma_f32_16x16x32_bf16 v[76:79], v[144:147], v[226:229], v[76:79]
	v_mfma_f32_16x16x32_bf16 v[72:75], v[174:177], v[226:229], v[72:75]
	v_mfma_f32_16x16x32_bf16 v[124:127], v[156:159], v[202:205], v[124:127]
	v_mfma_f32_16x16x32_bf16 v[120:123], v[178:181], v[202:205], v[120:123]
	v_mfma_f32_16x16x32_bf16 v[108:111], v[156:159], v[214:217], v[108:111]
	v_mfma_f32_16x16x32_bf16 v[104:107], v[178:181], v[214:217], v[104:107]
	v_mfma_f32_16x16x32_bf16 v[92:95], v[156:159], v[222:225], v[92:95]
	v_mfma_f32_16x16x32_bf16 v[88:91], v[178:181], v[222:225], v[88:91]
	v_mfma_f32_16x16x32_bf16 v[76:79], v[156:159], v[230:233], v[76:79]
	v_mfma_f32_16x16x32_bf16 v[72:75], v[178:181], v[230:233], v[72:75]
	s_setprio 0
	s_setprio 1
	v_mfma_f32_16x16x32_bf16 v[116:119], v[182:185], v[198:201], v[116:119]
	v_mfma_f32_16x16x32_bf16 v[112:115], v[190:193], v[198:201], v[112:115]
	v_mfma_f32_16x16x32_bf16 v[100:103], v[182:185], v[206:209], v[100:103]
	v_mfma_f32_16x16x32_bf16 v[96:99], v[190:193], v[206:209], v[96:99]
	v_mfma_f32_16x16x32_bf16 v[84:87], v[182:185], v[218:221], v[84:87]
	v_mfma_f32_16x16x32_bf16 v[80:83], v[190:193], v[218:221], v[80:83]
	v_mfma_f32_16x16x32_bf16 v[68:71], v[182:185], v[226:229], v[68:71]
	v_mfma_f32_16x16x32_bf16 v[64:67], v[190:193], v[226:229], v[64:67]
	v_mfma_f32_16x16x32_bf16 v[116:119], v[186:189], v[202:205], v[116:119]
	v_mfma_f32_16x16x32_bf16 v[112:115], v[194:197], v[202:205], v[112:115]
	v_mfma_f32_16x16x32_bf16 v[100:103], v[186:189], v[214:217], v[100:103]
	v_mfma_f32_16x16x32_bf16 v[96:99], v[194:197], v[214:217], v[96:99]
	v_mfma_f32_16x16x32_bf16 v[84:87], v[186:189], v[222:225], v[84:87]
	v_mfma_f32_16x16x32_bf16 v[80:83], v[194:197], v[222:225], v[80:83]
	v_mfma_f32_16x16x32_bf16 v[68:71], v[186:189], v[230:233], v[68:71]
	v_mfma_f32_16x16x32_bf16 v[64:67], v[194:197], v[230:233], v[64:67]
	s_setprio 0
	s_barrier
	s_add_i32 s34, s41, s15
	s_mov_b32 m0, s34
	ds_read_b128 v[198:201], v165 offset:49152
	ds_read_b128 v[202:205], v165 offset:50176
	ds_read_b128 v[206:209], v165 offset:51200
	ds_read_b128 v[214:217], v165 offset:52224
	ds_read_b128 v[218:221], v165 offset:53248
	ds_read_b128 v[222:225], v165 offset:54272
	ds_read_b128 v[226:229], v165 offset:55296
	ds_read_b128 v[230:233], v165 offset:56320
	s_add_u32 s100, s30, 0x80
	s_addc_u32 s101, s31, 0
	global_load_lds_dwordx4 v132, s[100:101]
	s_add_i32 m0, s34, 0x2000
	s_add_u32 s30, s30, 0x40080
	s_addc_u32 s31, s31, 0
	s_add_i32 s34, s44, s15
	global_load_lds_dwordx4 v128, s[100:101]
	s_mov_b32 m0, s34
	s_nop 0
	global_load_lds_dwordx4 v132, s[30:31]
	s_add_i32 m0, s34, 0x2000
	s_nop 0
	global_load_lds_dwordx4 v128, s[30:31]
	s_mov_b32 m0, s33
	s_nop 0
	global_load_lds_dwordx4 v134, s[98:99]
	s_mov_b32 m0, s36
	s_nop 0
	global_load_lds_dwordx4 v130, s[98:99]
	s_waitcnt vmcnt(8)
	s_waitcnt lgkmcnt(0)
	s_barrier
; #define PG8_MMA(ai, bj, At, Bt) do { __builtin_amdgcn_s_setprio(1); _Pragma("unroll") for (int m = 0; m < 4; ++m) _Pragma("unroll") for (int n = 0; n < 2; ++n) _Pragma("unroll") for (int k = 0; k < 2; ++k) \
;     acc[ai][bj][m][n] = __builtin_amdgcn_mfma_f32_16x16x32_bf16(Bt[n][k], At[m][k], acc[ai][bj][m][n], 0, 0, 0); __builtin_amdgcn_s_setprio(0); } while (0)
; #define PG8_WAIT_V(n) asm volatile("s_waitcnt vmcnt(" #n ")" ::: "memory")
; #define PG8_WAIT_L(n) asm volatile("s_waitcnt lgkmcnt(" #n ")" ::: "memory")
; #define PG8_BAR __builtin_amdgcn_s_barrier()
; #define PG8_SCHED __builtin_amdgcn_sched_barrier(0)
; DI void rows_rstd(float (&rs)[2][4], const float* ps, const Unit& u, int wr, int fr, int fq, int p_lo, int p_hi, float inv_dim) {
;   f32x4 pv[2][4];
; #pragma unroll
;   for (int ai = 0; ai < 2; ++ai)
; #pragma unroll
;     for (int m = 0; m < 4; ++m) pv[ai][m] = *(const f32x4*)(ps + (size_t)(u.pm * BM + ai * HALF + wr * 64 + m * 16 + fr) * 16 + 4 * fq);
; template <class Epi, class Sched>
; DI void gemm_phase(PG8_LAS unsigned char* lds, const Gemm g, const Sched& S, const Epi& E) {
;     ...
;       PG8_WAIT_V(8); PG8_WAIT_L(0); PG8_BAR; PG8_MMA(1, 0, At, B0); PG8_MMA(1, 1, At, B1); PG8_BAR; PG8_SCHED;
;     }
;     if (wr == 0) PG8_BAR;
	s_setprio 1
	s_waitcnt lgkmcnt(0)
	v_mfma_f32_16x16x32_bf16 v[60:63], v[144:147], v[198:201], v[60:63]
	v_mfma_f32_16x16x32_bf16 v[56:59], v[174:177], v[198:201], v[56:59]
	v_mfma_f32_16x16x32_bf16 v[44:47], v[144:147], v[206:209], v[44:47]
	v_mfma_f32_16x16x32_bf16 v[40:43], v[174:177], v[206:209], v[40:43]
	v_mfma_f32_16x16x32_bf16 v[28:31], v[144:147], v[218:221], v[28:31]
	v_mfma_f32_16x16x32_bf16 v[24:27], v[174:177], v[218:221], v[24:27]
	v_mfma_f32_16x16x32_bf16 v[12:15], v[144:147], v[226:229], v[12:15]
	v_mfma_f32_16x16x32_bf16 v[8:11], v[174:177], v[226:229], v[8:11]
	v_mfma_f32_16x16x32_bf16 v[60:63], v[156:159], v[202:205], v[60:63]
	v_mfma_f32_16x16x32_bf16 v[56:59], v[178:181], v[202:205], v[56:59]
	v_mfma_f32_16x16x32_bf16 v[44:47], v[156:159], v[214:217], v[44:47]
	v_mfma_f32_16x16x32_bf16 v[40:43], v[178:181], v[214:217], v[40:43]
	v_mfma_f32_16x16x32_bf16 v[28:31], v[156:159], v[222:225], v[28:31]
	v_mfma_f32_16x16x32_bf16 v[24:27], v[178:181], v[222:225], v[24:27]
	v_mfma_f32_16x16x32_bf16 v[12:15], v[156:159], v[230:233], v[12:15]
	v_mfma_f32_16x16x32_bf16 v[8:11], v[178:181], v[230:233], v[8:11]
	s_setprio 0
	s_setprio 1
	v_mfma_f32_16x16x32_bf16 v[52:55], v[182:185], v[198:201], v[52:55]
	v_mfma_f32_16x16x32_bf16 v[48:51], v[190:193], v[198:201], v[48:51]
	v_mfma_f32_16x16x32_bf16 v[36:39], v[182:185], v[206:209], v[36:39]
	v_mfma_f32_16x16x32_bf16 v[32:35], v[190:193], v[206:209], v[32:35]
	v_mfma_f32_16x16x32_bf16 v[20:23], v[182:185], v[218:221], v[20:23]
	v_mfma_f32_16x16x32_bf16 v[16:19], v[190:193], v[218:221], v[16:19]
	v_mfma_f32_16x16x32_bf16 v[4:7], v[182:185], v[226:229], v[4:7]
	v_mfma_f32_16x16x32_bf16 v[0:3], v[190:193], v[226:229], v[0:3]
	v_mfma_f32_16x16x32_bf16 v[52:55], v[186:189], v[202:205], v[52:55]
	v_mfma_f32_16x16x32_bf16 v[48:51], v[194:197], v[202:205], v[48:51]
	v_mfma_f32_16x16x32_bf16 v[36:39], v[186:189], v[214:217], v[36:39]
	v_mfma_f32_16x16x32_bf16 v[32:35], v[194:197], v[214:217], v[32:35]
	v_mfma_f32_16x16x32_bf16 v[20:23], v[186:189], v[222:225], v[20:23]
	v_mfma_f32_16x16x32_bf16 v[16:19], v[194:197], v[222:225], v[16:19]
	v_mfma_f32_16x16x32_bf16 v[4:7], v[186:189], v[230:233], v[4:7]
	v_mfma_f32_16x16x32_bf16 v[0:3], v[194:197], v[230:233], v[0:3]
	s_setprio 0
	s_barrier
	s_add_i32 s55, s55, 2
	s_add_u32 s2, s2, 0x100
	s_addc_u32 s3, s3, 0
	s_add_u32 s53, s53, 0x100
	s_addc_u32 s54, s54, 0
	s_cmp_gt_u32 s55, 13
	s_cbranch_scc0 .LBB0_1384
	v_lshl_add_u32 v166, s0, 8, v151
	v_or_b32_e32 v162, 16, v166
	v_ashrrev_i32_e32 v167, 31, v166
	v_ashrrev_i32_e32 v163, 31, v162
	v_or_b32_e32 v158, 32, v166
	v_lshlrev_b64 v[146:147], 6, v[166:167]
	v_lshlrev_b64 v[144:145], 6, v[162:163]
	v_ashrrev_i32_e32 v159, 31, v158
	v_lshl_add_u64 v[146:147], v[138:139], 0, v[146:147]
	v_or_b32_e32 v156, 48, v166
	v_lshl_add_u64 v[144:145], v[138:139], 0, v[144:145]
	global_load_dwordx4 v[174:177], v[146:147], off
	v_lshlrev_b64 v[146:147], 6, v[158:159]
	v_ashrrev_i32_e32 v157, 31, v156
	v_lshl_add_u64 v[146:147], v[138:139], 0, v[146:147]
	global_load_dwordx4 v[178:181], v[144:145], off
	global_load_dwordx4 v[182:185], v[146:147], off
	v_lshlrev_b64 v[144:145], 6, v[156:157]
	v_lshl_add_u64 v[144:145], v[138:139], 0, v[144:145]
	global_load_dwordx4 v[186:189], v[144:145], off
	v_add_u32_e32 v152, 0x80, v166
	v_ashrrev_i32_e32 v153, 31, v152
	v_lshlrev_b64 v[144:145], 6, v[152:153]
	v_add_u32_e32 v148, 0x90, v166
	v_lshl_add_u64 v[144:145], v[138:139], 0, v[144:145]
	v_ashrrev_i32_e32 v149, 31, v148
	global_load_dwordx4 v[190:193], v[144:145], off
	v_lshlrev_b64 v[144:145], 6, v[148:149]
	v_lshl_add_u64 v[144:145], v[138:139], 0, v[144:145]
	global_load_dwordx4 v[194:197], v[144:145], off
	v_add_u32_e32 v144, 0xb0, v166
	v_ashrrev_i32_e32 v145, 31, v144
	v_lshlrev_b64 v[146:147], 6, v[144:145]
	v_lshl_add_u64 v[146:147], v[138:139], 0, v[146:147]
	global_load_dwordx4 v[198:201], v[146:147], off
	v_and_b32_e32 v147, 64, v169
	v_add_u32_e32 v146, 0xa0, v166
	v_add_u32_e32 v150, 64, v147
	v_ashrrev_i32_e32 v147, 31, v146
	v_lshlrev_b64 v[202:203], 6, v[146:147]
	v_lshl_add_u64 v[202:203], v[138:139], 0, v[202:203]
	global_load_dwordx4 v[202:205], v[202:203], off
	s_and_b64 vcc, exec, s[10:11]
	s_cbranch_vccz .LBB0_1387
	s_barrier

; #define PG8_STAGE(bufoff, gbase, voff) do { _Pragma("unroll") for (int _i = 0; _i < 2; ++_i) \
;     __builtin_amdgcn_global_load_lds((const unsigned*)((const char*)(gbase) + (voff)[_i]), (PG8_LAS unsigned*)(lds + (bufoff) + ldsw + _i * 8192), 16, 0, 0); } while (0)
; #define PG8_LDA(dst, b, h) do { _Pragma("unroll") for (int m = 0; m < 4; ++m) _Pragma("unroll") for (int k = 0; k < 2; ++k) dst[m][k] = *(const PG8_LAS bf16x8*)(lds + PG8_SA(b, h) + aoff + m * 2048 + k * 1024); } while (0)
; #define PG8_LDB(dst, b, h) do { _Pragma("unroll") for (int n = 0; n < 2; ++n) _Pragma("unroll") for (int k = 0; k < 2; ++k) dst[n][k] = *(const PG8_LAS bf16x8*)(lds + PG8_SB(b, h) + boff + n * 2048 + k * 1024); } while (0)
; #define PG8_MMA(ai, bj, At, Bt) do { __builtin_amdgcn_s_setprio(1); _Pragma("unroll") for (int m = 0; m < 4; ++m) _Pragma("unroll") for (int n = 0; n < 2; ++n) _Pragma("unroll") for (int k = 0; k < 2; ++k) \
;     acc[ai][bj][m][n] = __builtin_amdgcn_mfma_f32_16x16x32_bf16(Bt[n][k], At[m][k], acc[ai][bj][m][n], 0, 0, 0); __builtin_amdgcn_s_setprio(0); } while (0)
; #define PG8_WAIT_V(n) asm volatile("s_waitcnt vmcnt(" #n ")" ::: "memory")
; #define PG8_WAIT_L(n) asm volatile("s_waitcnt lgkmcnt(" #n ")" ::: "memory")
; #define PG8_BAR __builtin_amdgcn_s_barrier()
; #define PG8_SCHED __builtin_amdgcn_sched_barrier(0)
; template <class Epi, class Sched>
; DI void gemm_phase(PG8_LAS unsigned char* lds, const Gemm g, const Sched& S, const Epi& E) {
;     ...
;       PG8_LDB(B0, 0, 0); PG8_LDB(B1, 0, 1); PG8_SCHED; PG8_LDA(At, 0, 0); PG8_STAGE(PG8_SA(1, 1), a1 + hstepA, voffA);
;       PG8_WAIT_V(8); PG8_WAIT_L(0); PG8_BAR; PG8_MMA(0, 0, At, B0); PG8_MMA(0, 1, At, B1); PG8_BAR; PG8_SCHED;
;       PG8_LDA(At, 0, 1); PG8_STAGE(PG8_SB(0, 0), b2, voffB); PG8_STAGE(PG8_SB(0, 1), b2 + hstepB, voffB); PG8_STAGE(PG8_SA(0, 0), a2, voffA);
;       PG8_WAIT_V(8); PG8_WAIT_L(0); PG8_BAR; PG8_MMA(1, 0, At, B0); PG8_MMA(1, 1, At, B1); PG8_BAR; PG8_SCHED;
.LBB0_1456:
	ds_read_b128 v[150:153], v145
	ds_read_b128 v[154:157], v145 offset:1024
	ds_read_b128 v[158:161], v145 offset:2048
	ds_read_b128 v[162:165], v145 offset:3072
	ds_read_b128 v[166:169], v146
	ds_read_b128 v[170:173], v146 offset:1024
	ds_read_b128 v[174:177], v146 offset:2048
	ds_read_b128 v[178:181], v146 offset:3072
	s_add_u32 s14, s12, 0x100
	s_addc_u32 s15, s13, 0
	s_cmp_eq_u32 s60, 40
	s_cselect_b32 s19, s9, s15
	s_cselect_b32 s18, s8, s14
	s_cselect_b32 s17, s11, s59
	s_cselect_b32 s16, s10, s58
	s_mov_b32 m0, s49
	ds_read_b128 v[182:185], v147
	ds_read_b128 v[186:189], v147 offset:1024
	ds_read_b128 v[190:193], v147 offset:2048
	ds_read_b128 v[194:197], v147 offset:3072
	ds_read_b128 v[198:201], v147 offset:4096
	ds_read_b128 v[202:205], v147 offset:5120
	ds_read_b128 v[206:209], v147 offset:6144
	ds_read_b128 v[210:213], v147 offset:7168
	global_load_lds_dwordx4 v138, s[12:13]
	s_mov_b32 m0, s52
	s_nop 0
	global_load_lds_dwordx4 v140, s[12:13]
	s_waitcnt vmcnt(8)
	s_waitcnt lgkmcnt(0)
	s_barrier
	s_setprio 1
	s_waitcnt lgkmcnt(0)
	v_mfma_f32_16x16x32_bf16 v[124:127], v[150:153], v[182:185], v[124:127]
	v_mfma_f32_16x16x32_bf16 v[120:123], v[158:161], v[182:185], v[120:123]
	v_mfma_f32_16x16x32_bf16 v[108:111], v[150:153], v[190:193], v[108:111]
	v_mfma_f32_16x16x32_bf16 v[104:107], v[158:161], v[190:193], v[104:107]
	v_mfma_f32_16x16x32_bf16 v[92:95], v[150:153], v[198:201], v[92:95]
	v_mfma_f32_16x16x32_bf16 v[88:91], v[158:161], v[198:201], v[88:91]
	v_mfma_f32_16x16x32_bf16 v[76:79], v[150:153], v[206:209], v[76:79]
	v_mfma_f32_16x16x32_bf16 v[72:75], v[158:161], v[206:209], v[72:75]
	v_mfma_f32_16x16x32_bf16 v[124:127], v[154:157], v[186:189], v[124:127]
	v_mfma_f32_16x16x32_bf16 v[120:123], v[162:165], v[186:189], v[120:123]
	v_mfma_f32_16x16x32_bf16 v[108:111], v[154:157], v[194:197], v[108:111]
	v_mfma_f32_16x16x32_bf16 v[104:107], v[162:165], v[194:197], v[104:107]
	v_mfma_f32_16x16x32_bf16 v[92:95], v[154:157], v[202:205], v[92:95]
	v_mfma_f32_16x16x32_bf16 v[88:91], v[162:165], v[202:205], v[88:91]
	v_mfma_f32_16x16x32_bf16 v[76:79], v[154:157], v[210:213], v[76:79]
	v_mfma_f32_16x16x32_bf16 v[72:75], v[162:165], v[210:213], v[72:75]
	s_setprio 0
	s_setprio 1
	v_mfma_f32_16x16x32_bf16 v[116:119], v[166:169], v[182:185], v[116:119]
	v_mfma_f32_16x16x32_bf16 v[112:115], v[174:177], v[182:185], v[112:115]
	v_mfma_f32_16x16x32_bf16 v[100:103], v[166:169], v[190:193], v[100:103]
	v_mfma_f32_16x16x32_bf16 v[96:99], v[174:177], v[190:193], v[96:99]
	v_mfma_f32_16x16x32_bf16 v[84:87], v[166:169], v[198:201], v[84:87]
	v_mfma_f32_16x16x32_bf16 v[80:83], v[174:177], v[198:201], v[80:83]
	v_mfma_f32_16x16x32_bf16 v[68:71], v[166:169], v[206:209], v[68:71]
	v_mfma_f32_16x16x32_bf16 v[64:67], v[174:177], v[206:209], v[64:67]
	v_mfma_f32_16x16x32_bf16 v[116:119], v[170:173], v[186:189], v[116:119]
	v_mfma_f32_16x16x32_bf16 v[112:115], v[178:181], v[186:189], v[112:115]
	v_mfma_f32_16x16x32_bf16 v[100:103], v[170:173], v[194:197], v[100:103]
	v_mfma_f32_16x16x32_bf16 v[96:99], v[178:181], v[194:197], v[96:99]
	v_mfma_f32_16x16x32_bf16 v[84:87], v[170:173], v[202:205], v[84:87]
	v_mfma_f32_16x16x32_bf16 v[80:83], v[178:181], v[202:205], v[80:83]
	v_mfma_f32_16x16x32_bf16 v[68:71], v[170:173], v[210:213], v[68:71]
	v_mfma_f32_16x16x32_bf16 v[64:67], v[178:181], v[210:213], v[64:67]
	s_setprio 0
	s_barrier
	s_add_i32 s12, s33, s20
	s_mov_b32 m0, s12
	ds_read_b128 v[182:185], v147 offset:16384
	ds_read_b128 v[186:189], v147 offset:17408
	ds_read_b128 v[190:193], v147 offset:18432
	ds_read_b128 v[194:197], v147 offset:19456
	ds_read_b128 v[198:201], v147 offset:20480
	ds_read_b128 v[202:205], v147 offset:21504
	ds_read_b128 v[206:209], v147 offset:22528
	ds_read_b128 v[210:213], v147 offset:23552
	global_load_lds_dwordx4 v132, s[16:17]
	s_add_i32 m0, s12, 0x2000
	s_add_u32 s12, s16, 0xb0000
	s_addc_u32 s13, s17, 0
	s_add_i32 s61, s34, s20
	global_load_lds_dwordx4 v128, s[16:17]
	s_mov_b32 m0, s61
	s_nop 0
	global_load_lds_dwordx4 v132, s[12:13]
	s_add_i32 m0, s61, 0x2000
	s_nop 0
	global_load_lds_dwordx4 v128, s[12:13]
	s_mov_b32 m0, s22
	s_nop 0
	global_load_lds_dwordx4 v134, s[18:19]
	s_mov_b32 m0, s23
	s_nop 0
	global_load_lds_dwordx4 v130, s[18:19]
	s_waitcnt vmcnt(8)
	s_waitcnt lgkmcnt(0)
	s_barrier
	s_setprio 1
	s_waitcnt lgkmcnt(0)
	v_mfma_f32_16x16x32_bf16 v[60:63], v[150:153], v[182:185], v[60:63]
	v_mfma_f32_16x16x32_bf16 v[56:59], v[158:161], v[182:185], v[56:59]
	v_mfma_f32_16x16x32_bf16 v[44:47], v[150:153], v[190:193], v[44:47]
	v_mfma_f32_16x16x32_bf16 v[40:43], v[158:161], v[190:193], v[40:43]
	v_mfma_f32_16x16x32_bf16 v[28:31], v[150:153], v[198:201], v[28:31]
	v_mfma_f32_16x16x32_bf16 v[24:27], v[158:161], v[198:201], v[24:27]
	v_mfma_f32_16x16x32_bf16 v[16:19], v[150:153], v[206:209], v[16:19]
	v_mfma_f32_16x16x32_bf16 v[8:11], v[158:161], v[206:209], v[8:11]
	v_mfma_f32_16x16x32_bf16 v[60:63], v[154:157], v[186:189], v[60:63]
	v_mfma_f32_16x16x32_bf16 v[56:59], v[162:165], v[186:189], v[56:59]
	v_mfma_f32_16x16x32_bf16 v[44:47], v[154:157], v[194:197], v[44:47]
	v_mfma_f32_16x16x32_bf16 v[40:43], v[162:165], v[194:197], v[40:43]
	v_mfma_f32_16x16x32_bf16 v[28:31], v[154:157], v[202:205], v[28:31]
	v_mfma_f32_16x16x32_bf16 v[24:27], v[162:165], v[202:205], v[24:27]
	v_mfma_f32_16x16x32_bf16 v[16:19], v[154:157], v[210:213], v[16:19]
	v_mfma_f32_16x16x32_bf16 v[8:11], v[162:165], v[210:213], v[8:11]
	s_setprio 0
	s_setprio 1
	v_mfma_f32_16x16x32_bf16 v[52:55], v[166:169], v[182:185], v[52:55]
	v_mfma_f32_16x16x32_bf16 v[48:51], v[174:177], v[182:185], v[48:51]
	v_mfma_f32_16x16x32_bf16 v[36:39], v[166:169], v[190:193], v[36:39]
	v_mfma_f32_16x16x32_bf16 v[32:35], v[174:177], v[190:193], v[32:35]
	v_mfma_f32_16x16x32_bf16 v[20:23], v[166:169], v[198:201], v[20:23]
	v_mfma_f32_16x16x32_bf16 v[12:15], v[174:177], v[198:201], v[12:15]
	v_mfma_f32_16x16x32_bf16 v[4:7], v[166:169], v[206:209], v[4:7]
	v_mfma_f32_16x16x32_bf16 v[0:3], v[174:177], v[206:209], v[0:3]
	v_mfma_f32_16x16x32_bf16 v[52:55], v[170:173], v[186:189], v[52:55]
	v_mfma_f32_16x16x32_bf16 v[48:51], v[178:181], v[186:189], v[48:51]
	v_mfma_f32_16x16x32_bf16 v[36:39], v[170:173], v[194:197], v[36:39]
	v_mfma_f32_16x16x32_bf16 v[32:35], v[178:181], v[194:197], v[32:35]
	v_mfma_f32_16x16x32_bf16 v[20:23], v[170:173], v[202:205], v[20:23]
	v_mfma_f32_16x16x32_bf16 v[12:15], v[178:181], v[202:205], v[12:15]
	v_mfma_f32_16x16x32_bf16 v[4:7], v[170:173], v[210:213], v[4:7]
	v_mfma_f32_16x16x32_bf16 v[0:3], v[178:181], v[210:213], v[0:3]
	s_setprio 0
	s_barrier
; #define PG8_STAGE(bufoff, gbase, voff) do { _Pragma("unroll") for (int _i = 0; _i < 2; ++_i) \
;     __builtin_amdgcn_global_load_lds((const unsigned*)((const char*)(gbase) + (voff)[_i]), (PG8_LAS unsigned*)(lds + (bufoff) + ldsw + _i * 8192), 16, 0, 0); } while (0)
; #define PG8_LDA(dst, b, h) do { _Pragma("unroll") for (int m = 0; m < 4; ++m) _Pragma("unroll") for (int k = 0; k < 2; ++k) dst[m][k] = *(const PG8_LAS bf16x8*)(lds + PG8_SA(b, h) + aoff + m * 2048 + k * 1024); } while (0)
; #define PG8_LDB(dst, b, h) do { _Pragma("unroll") for (int n = 0; n < 2; ++n) _Pragma("unroll") for (int k = 0; k < 2; ++k) dst[n][k] = *(const PG8_LAS bf16x8*)(lds + PG8_SB(b, h) + boff + n * 2048 + k * 1024); } while (0)
; #define PG8_MMA(ai, bj, At, Bt) do { __builtin_amdgcn_s_setprio(1); _Pragma("unroll") for (int m = 0; m < 4; ++m) _Pragma("unroll") for (int n = 0; n < 2; ++n) _Pragma("unroll") for (int k = 0; k < 2; ++k) \
;     acc[ai][bj][m][n] = __builtin_amdgcn_mfma_f32_16x16x32_bf16(Bt[n][k], At[m][k], acc[ai][bj][m][n], 0, 0, 0); __builtin_amdgcn_s_setprio(0); } while (0)
; #define PG8_WAIT_V(n) asm volatile("s_waitcnt vmcnt(" #n ")" ::: "memory")
; #define PG8_WAIT_L(n) asm volatile("s_waitcnt lgkmcnt(" #n ")" ::: "memory")
; #define PG8_BAR __builtin_amdgcn_s_barrier()
; #define PG8_SCHED __builtin_amdgcn_sched_barrier(0)
; template <class Epi, class Sched>
; DI void gemm_phase(PG8_LAS unsigned char* lds, const Gemm g, const Sched& S, const Epi& E) {
;     ...
;       PG8_LDB(B0, 1, 0); PG8_LDB(B1, 1, 1); PG8_SCHED; PG8_LDA(At, 1, 0); PG8_STAGE(PG8_SA(0, 1), a2 + hstepA, voffA);
;       PG8_WAIT_V(8); PG8_WAIT_L(0); PG8_BAR; PG8_MMA(0, 0, At, B0); PG8_MMA(0, 1, At, B1); PG8_BAR; PG8_SCHED;
	s_add_i32 s61, s30, 0x110
	v_add_u32_e32 v149, s61, v144
	ds_read_b128 v[150:153], v149
	ds_read_b128 v[154:157], v149 offset:1024
	ds_read_b128 v[158:161], v149 offset:2048
	ds_read_b128 v[162:165], v149 offset:3072
	ds_read_b128 v[166:169], v148
	ds_read_b128 v[170:173], v148 offset:1024
	ds_read_b128 v[174:177], v148 offset:2048
	ds_read_b128 v[178:181], v148 offset:3072
	s_add_u32 s12, s18, 0xb0000
	s_addc_u32 s13, s19, 0
	s_mov_b32 m0, s24
	ds_read_b128 v[182:185], v147 offset:32768
	ds_read_b128 v[186:189], v147 offset:33792
	ds_read_b128 v[190:193], v147 offset:34816
	ds_read_b128 v[194:197], v147 offset:35840
	ds_read_b128 v[198:201], v147 offset:36864
	ds_read_b128 v[202:205], v147 offset:37888
	ds_read_b128 v[206:209], v147 offset:38912
	ds_read_b128 v[210:213], v147 offset:39936
	global_load_lds_dwordx4 v134, s[12:13]
	s_mov_b32 m0, s25
	s_nop 0
	global_load_lds_dwordx4 v130, s[12:13]
	s_waitcnt vmcnt(8)
	s_waitcnt lgkmcnt(0)
	s_barrier
	s_setprio 1
	s_waitcnt lgkmcnt(0)
	v_mfma_f32_16x16x32_bf16 v[124:127], v[150:153], v[182:185], v[124:127]
	v_mfma_f32_16x16x32_bf16 v[120:123], v[158:161], v[182:185], v[120:123]
	v_mfma_f32_16x16x32_bf16 v[108:111], v[150:153], v[190:193], v[108:111]
	v_mfma_f32_16x16x32_bf16 v[104:107], v[158:161], v[190:193], v[104:107]
	v_mfma_f32_16x16x32_bf16 v[92:95], v[150:153], v[198:201], v[92:95]
	v_mfma_f32_16x16x32_bf16 v[88:91], v[158:161], v[198:201], v[88:91]
	v_mfma_f32_16x16x32_bf16 v[76:79], v[150:153], v[206:209], v[76:79]
	v_mfma_f32_16x16x32_bf16 v[72:75], v[158:161], v[206:209], v[72:75]
	v_mfma_f32_16x16x32_bf16 v[124:127], v[154:157], v[186:189], v[124:127]
	v_mfma_f32_16x16x32_bf16 v[120:123], v[162:165], v[186:189], v[120:123]
	v_mfma_f32_16x16x32_bf16 v[108:111], v[154:157], v[194:197], v[108:111]
	v_mfma_f32_16x16x32_bf16 v[104:107], v[162:165], v[194:197], v[104:107]
	v_mfma_f32_16x16x32_bf16 v[92:95], v[154:157], v[202:205], v[92:95]
	v_mfma_f32_16x16x32_bf16 v[88:91], v[162:165], v[202:205], v[88:91]
	v_mfma_f32_16x16x32_bf16 v[76:79], v[154:157], v[210:213], v[76:79]
	v_mfma_f32_16x16x32_bf16 v[72:75], v[162:165], v[210:213], v[72:75]
	s_setprio 0
	s_setprio 1
	v_mfma_f32_16x16x32_bf16 v[116:119], v[166:169], v[182:185], v[116:119]
	v_mfma_f32_16x16x32_bf16 v[112:115], v[174:177], v[182:185], v[112:115]
	v_mfma_f32_16x16x32_bf16 v[100:103], v[166:169], v[190:193], v[100:103]
	v_mfma_f32_16x16x32_bf16 v[96:99], v[174:177], v[190:193], v[96:99]
	v_mfma_f32_16x16x32_bf16 v[84:87], v[166:169], v[198:201], v[84:87]
	v_mfma_f32_16x16x32_bf16 v[80:83], v[174:177], v[198:201], v[80:83]
	v_mfma_f32_16x16x32_bf16 v[68:71], v[166:169], v[206:209], v[68:71]
	v_mfma_f32_16x16x32_bf16 v[64:67], v[174:177], v[206:209], v[64:67]
	v_mfma_f32_16x16x32_bf16 v[116:119], v[170:173], v[186:189], v[116:119]
	v_mfma_f32_16x16x32_bf16 v[112:115], v[178:181], v[186:189], v[112:115]
	v_mfma_f32_16x16x32_bf16 v[100:103], v[170:173], v[194:197], v[100:103]
	v_mfma_f32_16x16x32_bf16 v[96:99], v[178:181], v[194:197], v[96:99]
	v_mfma_f32_16x16x32_bf16 v[84:87], v[170:173], v[202:205], v[84:87]
	v_mfma_f32_16x16x32_bf16 v[80:83], v[178:181], v[202:205], v[80:83]
	v_mfma_f32_16x16x32_bf16 v[68:71], v[170:173], v[210:213], v[68:71]
	v_mfma_f32_16x16x32_bf16 v[64:67], v[178:181], v[210:213], v[64:67]
	s_setprio 0
	s_barrier
; #define PG8_STAGE(bufoff, gbase, voff) do { _Pragma("unroll") for (int _i = 0; _i < 2; ++_i) \
;     __builtin_amdgcn_global_load_lds((const unsigned*)((const char*)(gbase) + (voff)[_i]), (PG8_LAS unsigned*)(lds + (bufoff) + ldsw + _i * 8192), 16, 0, 0); } while (0)
; #define PG8_LDA(dst, b, h) do { _Pragma("unroll") for (int m = 0; m < 4; ++m) _Pragma("unroll") for (int k = 0; k < 2; ++k) dst[m][k] = *(const PG8_LAS bf16x8*)(lds + PG8_SA(b, h) + aoff + m * 2048 + k * 1024); } while (0)
; #define PG8_MMA(ai, bj, At, Bt) do { __builtin_amdgcn_s_setprio(1); _Pragma("unroll") for (int m = 0; m < 4; ++m) _Pragma("unroll") for (int n = 0; n < 2; ++n) _Pragma("unroll") for (int k = 0; k < 2; ++k) \
;     acc[ai][bj][m][n] = __builtin_amdgcn_mfma_f32_16x16x32_bf16(Bt[n][k], At[m][k], acc[ai][bj][m][n], 0, 0, 0); __builtin_amdgcn_s_setprio(0); } while (0)
; #define PG8_WAIT_V(n) asm volatile("s_waitcnt vmcnt(" #n ")" ::: "memory")
; #define PG8_WAIT_L(n) asm volatile("s_waitcnt lgkmcnt(" #n ")" ::: "memory")
; #define PG8_BAR __builtin_amdgcn_s_barrier()
; #define PG8_SCHED __builtin_amdgcn_sched_barrier(0)
;   DI void operator()(const f32x4 (&acc)[2][2][4][2], const Unit& u, int wr, int wc, int fr, int fq) const {
;     ...
;     RES_LD(0)
; template <class Epi, class Sched>
; DI void gemm_phase(PG8_LAS unsigned char* lds, const Gemm g, const Sched& S, const Epi& E) {
;     ...
;       PG8_LDA(At, 1, 1); PG8_STAGE(PG8_SB(1, 0), b3, voffB); PG8_STAGE(PG8_SB(1, 1), b3 + hstepB, voffB); PG8_STAGE(PG8_SA(1, 0), a3, voffA);
;       PG8_WAIT_V(8); PG8_WAIT_L(0); PG8_BAR; PG8_MMA(1, 0, At, B0); PG8_MMA(1, 1, At, B1); PG8_BAR; PG8_SCHED;
;     }
;     if (wr == 0) PG8_BAR;
;     E(acc, cur, wr, wc, fr, fq);
	s_add_i32 s12, s61, s20
	s_mov_b32 m0, s12
	ds_read_b128 v[182:185], v147 offset:49152
	ds_read_b128 v[186:189], v147 offset:50176
	ds_read_b128 v[190:193], v147 offset:51200
	ds_read_b128 v[194:197], v147 offset:52224
	ds_read_b128 v[198:201], v147 offset:53248
	ds_read_b128 v[202:205], v147 offset:54272
	ds_read_b128 v[206:209], v147 offset:55296
	ds_read_b128 v[210:213], v147 offset:56320
	s_add_u32 s100, s16, 0x80
	s_addc_u32 s101, s17, 0
	global_load_lds_dwordx4 v132, s[100:101]
	s_add_i32 m0, s12, 0x2000
	s_add_u32 s12, s16, 0xb0080
	s_addc_u32 s13, s17, 0
	s_add_i32 s16, s53, s20
	global_load_lds_dwordx4 v128, s[100:101]
	s_mov_b32 m0, s16
	s_nop 0
	global_load_lds_dwordx4 v132, s[12:13]
	s_add_i32 m0, s16, 0x2000
	s_nop 0
	global_load_lds_dwordx4 v128, s[12:13]
	s_mov_b32 m0, s28
	s_nop 0
	s_add_u32 s100, s18, 0x80
	s_addc_u32 s101, s19, 0
	global_load_lds_dwordx4 v134, s[100:101]
	s_mov_b32 m0, s29
	s_nop 0
	global_load_lds_dwordx4 v130, s[100:101]
	s_waitcnt vmcnt(8)
	s_waitcnt lgkmcnt(0)
	s_barrier
	s_setprio 1
	s_waitcnt lgkmcnt(0)
	v_mfma_f32_16x16x32_bf16 v[60:63], v[150:153], v[182:185], v[60:63]
	v_mfma_f32_16x16x32_bf16 v[56:59], v[158:161], v[182:185], v[56:59]
	v_mfma_f32_16x16x32_bf16 v[44:47], v[150:153], v[190:193], v[44:47]
	v_mfma_f32_16x16x32_bf16 v[40:43], v[158:161], v[190:193], v[40:43]
	v_mfma_f32_16x16x32_bf16 v[28:31], v[150:153], v[198:201], v[28:31]
	v_mfma_f32_16x16x32_bf16 v[24:27], v[158:161], v[198:201], v[24:27]
	v_mfma_f32_16x16x32_bf16 v[16:19], v[150:153], v[206:209], v[16:19]
	v_mfma_f32_16x16x32_bf16 v[8:11], v[158:161], v[206:209], v[8:11]
	v_mfma_f32_16x16x32_bf16 v[60:63], v[154:157], v[186:189], v[60:63]
	v_mfma_f32_16x16x32_bf16 v[56:59], v[162:165], v[186:189], v[56:59]
	v_mfma_f32_16x16x32_bf16 v[44:47], v[154:157], v[194:197], v[44:47]
	v_mfma_f32_16x16x32_bf16 v[40:43], v[162:165], v[194:197], v[40:43]
	v_mfma_f32_16x16x32_bf16 v[28:31], v[154:157], v[202:205], v[28:31]
	v_mfma_f32_16x16x32_bf16 v[24:27], v[162:165], v[202:205], v[24:27]
	v_mfma_f32_16x16x32_bf16 v[16:19], v[154:157], v[210:213], v[16:19]
	v_mfma_f32_16x16x32_bf16 v[8:11], v[162:165], v[210:213], v[8:11]
	s_setprio 0
	s_setprio 1
	v_mfma_f32_16x16x32_bf16 v[52:55], v[166:169], v[182:185], v[52:55]
	v_mfma_f32_16x16x32_bf16 v[48:51], v[174:177], v[182:185], v[48:51]
	v_mfma_f32_16x16x32_bf16 v[36:39], v[166:169], v[190:193], v[36:39]
	v_mfma_f32_16x16x32_bf16 v[32:35], v[174:177], v[190:193], v[32:35]
	v_mfma_f32_16x16x32_bf16 v[20:23], v[166:169], v[198:201], v[20:23]
	v_mfma_f32_16x16x32_bf16 v[12:15], v[174:177], v[198:201], v[12:15]
	v_mfma_f32_16x16x32_bf16 v[4:7], v[166:169], v[206:209], v[4:7]
	v_mfma_f32_16x16x32_bf16 v[0:3], v[174:177], v[206:209], v[0:3]
	v_mfma_f32_16x16x32_bf16 v[52:55], v[170:173], v[186:189], v[52:55]
	v_mfma_f32_16x16x32_bf16 v[48:51], v[178:181], v[186:189], v[48:51]
	v_mfma_f32_16x16x32_bf16 v[36:39], v[170:173], v[194:197], v[36:39]
	v_mfma_f32_16x16x32_bf16 v[32:35], v[178:181], v[194:197], v[32:35]
	v_mfma_f32_16x16x32_bf16 v[20:23], v[170:173], v[202:205], v[20:23]
	v_mfma_f32_16x16x32_bf16 v[12:15], v[178:181], v[202:205], v[12:15]
	v_mfma_f32_16x16x32_bf16 v[4:7], v[170:173], v[210:213], v[4:7]
	v_mfma_f32_16x16x32_bf16 v[0:3], v[178:181], v[210:213], v[0:3]
	s_setprio 0
	s_barrier
	s_add_i32 s60, s60, 2
	s_add_u32 s58, s58, 0x100
	s_addc_u32 s59, s59, 0
	s_cmp_gt_u32 s60, 41
	s_mov_b64 s[12:13], s[14:15]
	s_cbranch_scc0 .LBB0_1456
	v_lshl_add_u32 v142, s57, 8, v137
	v_ashrrev_i32_e32 v143, 31, v142
	s_lshl_b32 s12, s56, 8
	v_lshlrev_b64 v[142:143], 10, v[142:143]
	s_ashr_i32 s13, s12, 31
	v_lshl_add_u64 v[166:167], v[142:143], 0, s[12:13]
	v_or_b32_e32 v166, v166, v136
	v_lshl_add_u64 v[142:143], v[166:167], 1, s[50:51]
	v_add_co_u32_e32 v162, vcc, s31, v142
	global_load_dwordx4 v[150:153], v[142:143], off
	global_load_dwordx4 v[154:157], v[142:143], off offset:256
	v_addc_co_u32_e32 v163, vcc, 0, v143, vcc
	global_load_dwordx4 v[158:161], v[162:163], off
	s_nop 0
	global_load_dwordx4 v[162:165], v[162:163], off offset:256
	s_and_b64 vcc, exec, s[6:7]
	s_cbranch_vccz .LBB0_1459
	s_barrier
